# gla_inter oi loads de-serialized + flat->global, gla_intra q/k loads software-pipelined, rwkv prep loads batched (both copies), scan step hand-scheduled
# speedup vs baseline: 1.0271x; 1.0271x over previous
.LBB0_305:
	v_lshl_or_b32 v32, s37, 14, v89
	v_lshl_add_u64 v[2:3], v[32:33], 2, s[88:89]
	v_add_co_u32_e32 v0, vcc, 0x1000, v2
	global_load_dword v23, v[2:3], off
	s_nop 0
	v_addc_co_u32_e32 v1, vcc, 0, v3, vcc
	global_load_dword v24, v[0:1], off
	v_add_co_u32_e32 v0, vcc, 0x2000, v2
	s_movk_i32 s0, 0x3000
	s_nop 0
	v_addc_co_u32_e32 v1, vcc, 0, v3, vcc
	global_load_dword v25, v[0:1], off
	v_add_co_u32_e32 v0, vcc, s0, v2
	s_movk_i32 s0, 0x6000
	s_nop 0
	v_addc_co_u32_e32 v1, vcc, 0, v3, vcc
	global_load_dword v87, v[0:1], off
	v_add_co_u32_e32 v0, vcc, 0x4000, v2
	s_lshl_b32 s66, s37, 10
	s_nop 0
	v_addc_co_u32_e32 v1, vcc, 0, v3, vcc
	v_add_co_u32_e32 v4, vcc, 0x5000, v2
	global_load_dword v0, v[0:1], off
	s_nop 0
	v_addc_co_u32_e32 v5, vcc, 0, v3, vcc
	global_load_dword v19, v[4:5], off
	v_add_co_u32_e32 v4, vcc, s0, v2
	s_mov_b32 s0, 0x8000
	s_nop 0
	v_addc_co_u32_e32 v5, vcc, 0, v3, vcc
	global_load_dword v22, v[4:5], off
	v_add_co_u32_e32 v4, vcc, 0x7000, v2
	v_or_b32_e32 v32, s66, v89
	s_nop 0
	v_addc_co_u32_e32 v5, vcc, 0, v3, vcc
	global_load_dword v245, v[4:5], off
	v_add_co_u32_e32 v4, vcc, s0, v2
	s_mov_b32 s0, 0xb000
	s_nop 0
	v_addc_co_u32_e32 v5, vcc, 0, v3, vcc
	global_load_dword v85, v[4:5], off
	v_add_co_u32_e32 v4, vcc, 0x9000, v2
	v_cndmask_b32_e64 v30, v120, v119, s[38:39]
	s_nop 0
	v_addc_co_u32_e32 v5, vcc, 0, v3, vcc
	global_load_dword v246, v[4:5], off
	v_add_co_u32_e32 v4, vcc, s0, v2
	s_mov_b32 s0, 0xd000
	s_nop 0
	v_addc_co_u32_e32 v5, vcc, 0, v3, vcc
	global_load_dword v247, v[4:5], off offset:-4096
	global_load_dword v248, v[4:5], off
	v_add_co_u32_e32 v4, vcc, s0, v2
	s_mov_b32 s0, 0xf000
	s_nop 0
	v_addc_co_u32_e32 v5, vcc, 0, v3, vcc
	v_add_co_u32_e32 v2, vcc, s0, v2
	global_load_dword v1, v[4:5], off offset:-4096
	s_nop 0
	global_load_dword v5, v[4:5], off
	v_addc_co_u32_e32 v3, vcc, 0, v3, vcc
	global_load_dword v17, v[2:3], off offset:-4096
	global_load_dword v4, v[2:3], off
	v_lshl_add_u64 v[2:3], v[32:33], 2, s[90:91]
	global_load_dword v249, v[2:3], off
	s_lshl_b32 s0, s37, 6
	s_add_i32 s37, s0, 16
	v_sub_u32_e32 v2, 63, v90
	s_add_i32 s37, s37, 0x12c00
	v_cndmask_b32_e64 v86, v2, v90, s[38:39]
	v_lshl_add_u32 v2, v86, 7, s37
	ds_read_b128 v[26:29], v2
	ds_read_b128 v[34:37], v2 offset:16
	ds_read_b128 v[38:41], v2 offset:32
	ds_read_b128 v[42:45], v2 offset:48
	s_waitcnt vmcnt(0) lgkmcnt(0)
	v_mul_f32_e32 v2, v24, v27
	v_fmac_f32_e32 v2, v23, v26
	v_fmac_f32_e32 v2, v25, v28
	v_fmac_f32_e32 v2, v87, v29
	v_mul_f32_e32 v3, v19, v35
	v_fmac_f32_e32 v3, v0, v34
	v_fmac_f32_e32 v3, v22, v36
	v_fmac_f32_e32 v3, v245, v37
	v_add_f32_e32 v2, v249, v2
	v_add_f32_e32 v2, v2, v3
	v_mul_f32_e32 v3, v246, v39
	v_fmac_f32_e32 v3, v85, v38
	v_fmac_f32_e32 v3, v247, v40
	v_fmac_f32_e32 v3, v248, v41
	v_add_f32_e32 v2, v2, v3
	v_mul_f32_e32 v3, v5, v43
	v_fmac_f32_e32 v3, v1, v42
	v_fmac_f32_e32 v3, v17, v44
	v_fmac_f32_e32 v3, v4, v45
	v_add_f32_e32 v2, v2, v3
	v_min_f32_e32 v3, 0, v2
	v_mul_f32_e64 v2, |v2|, s97
	v_exp_f32_e32 v2, v2
	s_nop 0
	v_add_f32_e32 v2, 1.0, v2
	v_cmp_gt_f32_e32 vcc, s33, v2
	s_nop 1
	v_cndmask_b32_e64 v20, 0, 32, vcc
	v_ldexp_f32 v2, v2, v20
	v_log_f32_e32 v2, v2
	s_nop 0
	v_mul_f32_e32 v20, 0x3f317217, v2
	v_fma_f32 v20, v2, s72, -v20
	v_fmac_f32_e32 v20, 0x3377d1cf, v2
	v_fmac_f32_e32 v20, 0x3f317217, v2
	v_cmp_lt_f32_e64 s[0:1], |v2|, s73
	s_nop 1
	v_cndmask_b32_e64 v2, v2, v20, s[0:1]
	v_cndmask_b32_e32 v20, 0, v227, vcc
	v_sub_f32_e32 v2, v2, v20
	v_sub_f32_e32 v2, v3, v2
	s_mov_b32 s0, 0x3d800000
	v_fma_f32 v83, v2, s0, 0
	v_sub_u32_e32 v2, 63, v9
	v_cndmask_b32_e64 v84, v2, v9, s[38:39]
	v_lshl_add_u32 v2, v84, 7, s37
	ds_read_b128 v[26:29], v2
	ds_read_b128 v[34:37], v2 offset:16
	ds_read_b128 v[38:41], v2 offset:32
	ds_read_b128 v[42:45], v2 offset:48
	s_waitcnt lgkmcnt(3)
	v_mul_f32_e32 v2, v24, v27
	v_fmac_f32_e32 v2, v23, v26
	s_waitcnt lgkmcnt(2)
	v_mul_f32_e32 v3, v19, v35
	v_fmac_f32_e32 v2, v25, v28
	v_fmac_f32_e32 v3, v0, v34
	v_fmac_f32_e32 v2, v87, v29
	v_fmac_f32_e32 v3, v22, v36
	v_add_f32_e32 v2, v249, v2
	v_fmac_f32_e32 v3, v245, v37
	v_add_f32_e32 v2, v2, v3
	s_waitcnt lgkmcnt(1)
	v_mul_f32_e32 v3, v246, v39
	v_fmac_f32_e32 v3, v85, v38
	v_fmac_f32_e32 v3, v247, v40
	v_fmac_f32_e32 v3, v248, v41
	v_add_f32_e32 v2, v2, v3
	s_waitcnt lgkmcnt(0)
	v_mul_f32_e32 v3, v5, v43
	v_fmac_f32_e32 v3, v1, v42
	v_fmac_f32_e32 v3, v17, v44
	v_fmac_f32_e32 v3, v4, v45
	v_add_f32_e32 v2, v2, v3
	v_min_f32_e32 v3, 0, v2
	v_mul_f32_e64 v2, |v2|, s97
	v_exp_f32_e32 v2, v2
	s_nop 0
	v_add_f32_e32 v2, 1.0, v2
	v_cmp_gt_f32_e32 vcc, s33, v2
	s_nop 1
	v_cndmask_b32_e64 v20, 0, 32, vcc
	v_ldexp_f32 v2, v2, v20
	v_log_f32_e32 v2, v2
	s_nop 0
	v_mul_f32_e32 v20, 0x3f317217, v2
	v_fma_f32 v20, v2, s72, -v20
	v_fmac_f32_e32 v20, 0x3377d1cf, v2
	v_fmac_f32_e32 v20, 0x3f317217, v2
	v_cmp_lt_f32_e64 s[0:1], |v2|, s73
	s_nop 1
	v_cndmask_b32_e64 v2, v2, v20, s[0:1]
	v_cndmask_b32_e32 v20, 0, v227, vcc
	v_sub_f32_e32 v2, v2, v20
	v_sub_f32_e32 v2, v3, v2
	v_fmamk_f32 v81, v2, 0x3d800000, v83
	v_sub_u32_e32 v2, 63, v94
	v_cndmask_b32_e64 v82, v2, v94, s[38:39]
	v_lshl_add_u32 v2, v82, 7, s37
	ds_read_b128 v[26:29], v2
	ds_read_b128 v[34:37], v2 offset:16
	ds_read_b128 v[38:41], v2 offset:32
	ds_read_b128 v[42:45], v2 offset:48
	s_waitcnt lgkmcnt(3)
	v_mul_f32_e32 v2, v24, v27
	v_fmac_f32_e32 v2, v23, v26
	s_waitcnt lgkmcnt(2)
	v_mul_f32_e32 v3, v19, v35
	v_fmac_f32_e32 v2, v25, v28
	v_fmac_f32_e32 v3, v0, v34
	v_fmac_f32_e32 v2, v87, v29
	v_fmac_f32_e32 v3, v22, v36
	v_add_f32_e32 v2, v249, v2
	v_fmac_f32_e32 v3, v245, v37
	v_add_f32_e32 v2, v2, v3
	s_waitcnt lgkmcnt(1)
	v_mul_f32_e32 v3, v246, v39
	v_fmac_f32_e32 v3, v85, v38
	v_fmac_f32_e32 v3, v247, v40
	v_fmac_f32_e32 v3, v248, v41
	v_add_f32_e32 v2, v2, v3
	s_waitcnt lgkmcnt(0)
	v_mul_f32_e32 v3, v5, v43
	v_fmac_f32_e32 v3, v1, v42
	v_fmac_f32_e32 v3, v17, v44
	v_fmac_f32_e32 v3, v4, v45
	v_add_f32_e32 v2, v2, v3
	v_min_f32_e32 v3, 0, v2
	v_mul_f32_e64 v2, |v2|, s97
	v_exp_f32_e32 v2, v2
	s_nop 0
	v_add_f32_e32 v2, 1.0, v2
	v_cmp_gt_f32_e32 vcc, s33, v2
	s_nop 1
	v_cndmask_b32_e64 v20, 0, 32, vcc
	v_ldexp_f32 v2, v2, v20
	v_log_f32_e32 v2, v2
	s_nop 0
	v_mul_f32_e32 v20, 0x3f317217, v2
	v_fma_f32 v20, v2, s72, -v20
	v_fmac_f32_e32 v20, 0x3377d1cf, v2
	v_fmac_f32_e32 v20, 0x3f317217, v2
	v_cmp_lt_f32_e64 s[0:1], |v2|, s73
	s_nop 1
	v_cndmask_b32_e64 v2, v2, v20, s[0:1]
	v_cndmask_b32_e32 v20, 0, v227, vcc
	v_sub_f32_e32 v2, v2, v20
	v_sub_f32_e32 v2, v3, v2
	v_fmamk_f32 v79, v2, 0x3d800000, v81
	v_sub_u32_e32 v2, 63, v95
	v_cndmask_b32_e64 v80, v2, v95, s[38:39]
	v_lshl_add_u32 v2, v80, 7, s37
	ds_read_b128 v[26:29], v2
	ds_read_b128 v[34:37], v2 offset:16
	ds_read_b128 v[38:41], v2 offset:32
	ds_read_b128 v[42:45], v2 offset:48
	s_waitcnt lgkmcnt(3)
	v_mul_f32_e32 v2, v24, v27
	v_fmac_f32_e32 v2, v23, v26
	s_waitcnt lgkmcnt(2)
	v_mul_f32_e32 v3, v19, v35
	v_fmac_f32_e32 v2, v25, v28
	v_fmac_f32_e32 v3, v0, v34
	v_fmac_f32_e32 v2, v87, v29
	v_fmac_f32_e32 v3, v22, v36
	v_add_f32_e32 v2, v249, v2
	v_fmac_f32_e32 v3, v245, v37
	v_add_f32_e32 v2, v2, v3
	s_waitcnt lgkmcnt(1)
	v_mul_f32_e32 v3, v246, v39
	v_fmac_f32_e32 v3, v85, v38
	v_fmac_f32_e32 v3, v247, v40
	v_fmac_f32_e32 v3, v248, v41
	v_add_f32_e32 v2, v2, v3
	s_waitcnt lgkmcnt(0)
	v_mul_f32_e32 v3, v5, v43
	v_fmac_f32_e32 v3, v1, v42
	v_fmac_f32_e32 v3, v17, v44
	v_fmac_f32_e32 v3, v4, v45
	v_add_f32_e32 v2, v2, v3
	v_min_f32_e32 v3, 0, v2
	v_mul_f32_e64 v2, |v2|, s97
	v_exp_f32_e32 v2, v2
	s_nop 0
	v_add_f32_e32 v2, 1.0, v2
	v_cmp_gt_f32_e32 vcc, s33, v2
	s_nop 1
	v_cndmask_b32_e64 v20, 0, 32, vcc
	v_ldexp_f32 v2, v2, v20
	v_log_f32_e32 v2, v2
	s_nop 0
	v_mul_f32_e32 v20, 0x3f317217, v2
	v_fma_f32 v20, v2, s72, -v20
	v_fmac_f32_e32 v20, 0x3377d1cf, v2
	v_fmac_f32_e32 v20, 0x3f317217, v2
	v_cmp_lt_f32_e64 s[0:1], |v2|, s73
	s_nop 1
	v_cndmask_b32_e64 v2, v2, v20, s[0:1]
	v_cndmask_b32_e32 v20, 0, v227, vcc
	v_sub_f32_e32 v2, v2, v20
	v_sub_f32_e32 v2, v3, v2
	v_fmamk_f32 v77, v2, 0x3d800000, v79
	v_sub_u32_e32 v2, 63, v96
	v_cndmask_b32_e64 v78, v2, v96, s[38:39]
	v_lshl_add_u32 v2, v78, 7, s37
	ds_read_b128 v[26:29], v2
	ds_read_b128 v[34:37], v2 offset:16
	ds_read_b128 v[38:41], v2 offset:32
	ds_read_b128 v[42:45], v2 offset:48
	s_waitcnt lgkmcnt(3)
	v_mul_f32_e32 v2, v24, v27
	v_fmac_f32_e32 v2, v23, v26
	s_waitcnt lgkmcnt(2)
	v_mul_f32_e32 v3, v19, v35
	v_fmac_f32_e32 v2, v25, v28
	v_fmac_f32_e32 v3, v0, v34
	v_fmac_f32_e32 v2, v87, v29
	v_fmac_f32_e32 v3, v22, v36
	v_add_f32_e32 v2, v249, v2
	v_fmac_f32_e32 v3, v245, v37
	v_add_f32_e32 v2, v2, v3
	s_waitcnt lgkmcnt(1)
	v_mul_f32_e32 v3, v246, v39
	v_fmac_f32_e32 v3, v85, v38
	v_fmac_f32_e32 v3, v247, v40
	v_fmac_f32_e32 v3, v248, v41
	v_add_f32_e32 v2, v2, v3
	s_waitcnt lgkmcnt(0)
	v_mul_f32_e32 v3, v5, v43
	v_fmac_f32_e32 v3, v1, v42
	v_fmac_f32_e32 v3, v17, v44
	v_fmac_f32_e32 v3, v4, v45
	v_add_f32_e32 v2, v2, v3
	v_min_f32_e32 v3, 0, v2
	v_mul_f32_e64 v2, |v2|, s97
	v_exp_f32_e32 v2, v2
	s_nop 0
	v_add_f32_e32 v2, 1.0, v2
	v_cmp_gt_f32_e32 vcc, s33, v2
	s_nop 1
	v_cndmask_b32_e64 v20, 0, 32, vcc
	v_ldexp_f32 v2, v2, v20
	v_log_f32_e32 v2, v2
	s_nop 0
	v_mul_f32_e32 v20, 0x3f317217, v2
	v_fma_f32 v20, v2, s72, -v20
	v_fmac_f32_e32 v20, 0x3377d1cf, v2
	v_fmac_f32_e32 v20, 0x3f317217, v2
	v_cmp_lt_f32_e64 s[0:1], |v2|, s73
	s_nop 1
	v_cndmask_b32_e64 v2, v2, v20, s[0:1]
	v_cndmask_b32_e32 v20, 0, v227, vcc
	v_sub_f32_e32 v2, v2, v20
	v_sub_f32_e32 v2, v3, v2
	v_fmamk_f32 v75, v2, 0x3d800000, v77
	v_sub_u32_e32 v2, 63, v97
	v_cndmask_b32_e64 v76, v2, v97, s[38:39]
	v_lshl_add_u32 v2, v76, 7, s37
	ds_read_b128 v[26:29], v2
	ds_read_b128 v[34:37], v2 offset:16
	ds_read_b128 v[38:41], v2 offset:32
	ds_read_b128 v[42:45], v2 offset:48
	s_waitcnt lgkmcnt(3)
	v_mul_f32_e32 v2, v24, v27
	v_fmac_f32_e32 v2, v23, v26
	s_waitcnt lgkmcnt(2)
	v_mul_f32_e32 v3, v19, v35
	v_fmac_f32_e32 v2, v25, v28
	v_fmac_f32_e32 v3, v0, v34
	v_fmac_f32_e32 v2, v87, v29
	v_fmac_f32_e32 v3, v22, v36
	v_add_f32_e32 v2, v249, v2
	v_fmac_f32_e32 v3, v245, v37
	v_add_f32_e32 v2, v2, v3
	s_waitcnt lgkmcnt(1)
	v_mul_f32_e32 v3, v246, v39
	v_fmac_f32_e32 v3, v85, v38
	v_fmac_f32_e32 v3, v247, v40
	v_fmac_f32_e32 v3, v248, v41
	v_add_f32_e32 v2, v2, v3
	s_waitcnt lgkmcnt(0)
	v_mul_f32_e32 v3, v5, v43
	v_fmac_f32_e32 v3, v1, v42
	v_fmac_f32_e32 v3, v17, v44
	v_fmac_f32_e32 v3, v4, v45
	v_add_f32_e32 v2, v2, v3
	v_min_f32_e32 v3, 0, v2
	v_mul_f32_e64 v2, |v2|, s97
	v_exp_f32_e32 v2, v2
	s_nop 0
	v_add_f32_e32 v2, 1.0, v2
	v_cmp_gt_f32_e32 vcc, s33, v2
	s_nop 1
	v_cndmask_b32_e64 v20, 0, 32, vcc
	v_ldexp_f32 v2, v2, v20
	v_log_f32_e32 v2, v2
	s_nop 0
	v_mul_f32_e32 v20, 0x3f317217, v2
	v_fma_f32 v20, v2, s72, -v20
	v_fmac_f32_e32 v20, 0x3377d1cf, v2
	v_fmac_f32_e32 v20, 0x3f317217, v2
	v_cmp_lt_f32_e64 s[0:1], |v2|, s73
	s_nop 1
	v_cndmask_b32_e64 v2, v2, v20, s[0:1]
	v_cndmask_b32_e32 v20, 0, v227, vcc
	v_sub_f32_e32 v2, v2, v20
	v_sub_f32_e32 v2, v3, v2
	v_fmamk_f32 v73, v2, 0x3d800000, v75
	v_sub_u32_e32 v2, 63, v98
	v_cndmask_b32_e64 v74, v2, v98, s[38:39]
	v_lshl_add_u32 v2, v74, 7, s37
	ds_read_b128 v[26:29], v2
	ds_read_b128 v[34:37], v2 offset:16
	ds_read_b128 v[38:41], v2 offset:32
	ds_read_b128 v[42:45], v2 offset:48
	s_waitcnt lgkmcnt(3)
	v_mul_f32_e32 v2, v24, v27
	v_fmac_f32_e32 v2, v23, v26
	s_waitcnt lgkmcnt(2)
	v_mul_f32_e32 v3, v19, v35
	v_fmac_f32_e32 v2, v25, v28
	v_fmac_f32_e32 v3, v0, v34
	v_fmac_f32_e32 v2, v87, v29
	v_fmac_f32_e32 v3, v22, v36
	v_add_f32_e32 v2, v249, v2
	v_fmac_f32_e32 v3, v245, v37
	v_add_f32_e32 v2, v2, v3
	s_waitcnt lgkmcnt(1)
	v_mul_f32_e32 v3, v246, v39
	v_fmac_f32_e32 v3, v85, v38
	v_fmac_f32_e32 v3, v247, v40
	v_fmac_f32_e32 v3, v248, v41
	v_add_f32_e32 v2, v2, v3
	s_waitcnt lgkmcnt(0)
	v_mul_f32_e32 v3, v5, v43
	v_fmac_f32_e32 v3, v1, v42
	v_fmac_f32_e32 v3, v17, v44
	v_fmac_f32_e32 v3, v4, v45
	v_add_f32_e32 v2, v2, v3
	v_min_f32_e32 v3, 0, v2
	v_mul_f32_e64 v2, |v2|, s97
	v_exp_f32_e32 v2, v2
	s_nop 0
	v_add_f32_e32 v2, 1.0, v2
	v_cmp_gt_f32_e32 vcc, s33, v2
	s_nop 1
	v_cndmask_b32_e64 v20, 0, 32, vcc
	v_ldexp_f32 v2, v2, v20
	v_log_f32_e32 v2, v2
	s_nop 0
	v_mul_f32_e32 v20, 0x3f317217, v2
	v_fma_f32 v20, v2, s72, -v20
	v_fmac_f32_e32 v20, 0x3377d1cf, v2
	v_fmac_f32_e32 v20, 0x3f317217, v2
	v_cmp_lt_f32_e64 s[0:1], |v2|, s73
	s_nop 1
	v_cndmask_b32_e64 v2, v2, v20, s[0:1]
	v_cndmask_b32_e32 v20, 0, v227, vcc
	v_sub_f32_e32 v2, v2, v20
	v_sub_f32_e32 v2, v3, v2
	v_fmamk_f32 v71, v2, 0x3d800000, v73
	v_sub_u32_e32 v2, 63, v99
	v_cndmask_b32_e64 v72, v2, v99, s[38:39]
	v_lshl_add_u32 v2, v72, 7, s37
	ds_read_b128 v[26:29], v2
	ds_read_b128 v[34:37], v2 offset:16
	ds_read_b128 v[38:41], v2 offset:32
	ds_read_b128 v[42:45], v2 offset:48
	s_waitcnt lgkmcnt(3)
	v_mul_f32_e32 v2, v24, v27
	v_fmac_f32_e32 v2, v23, v26
	s_waitcnt lgkmcnt(2)
	v_mul_f32_e32 v3, v19, v35
	v_fmac_f32_e32 v2, v25, v28
	v_fmac_f32_e32 v3, v0, v34
	v_fmac_f32_e32 v2, v87, v29
	v_fmac_f32_e32 v3, v22, v36
	v_add_f32_e32 v2, v249, v2
	v_fmac_f32_e32 v3, v245, v37
	v_add_f32_e32 v2, v2, v3
	s_waitcnt lgkmcnt(1)
	v_mul_f32_e32 v3, v246, v39
	v_fmac_f32_e32 v3, v85, v38
	v_fmac_f32_e32 v3, v247, v40
	v_fmac_f32_e32 v3, v248, v41
	v_add_f32_e32 v2, v2, v3
	s_waitcnt lgkmcnt(0)
	v_mul_f32_e32 v3, v5, v43
	v_fmac_f32_e32 v3, v1, v42
	v_fmac_f32_e32 v3, v17, v44
	v_fmac_f32_e32 v3, v4, v45
	v_add_f32_e32 v2, v2, v3
	v_min_f32_e32 v3, 0, v2
	v_mul_f32_e64 v2, |v2|, s97
	v_exp_f32_e32 v2, v2
	s_nop 0
	v_add_f32_e32 v2, 1.0, v2
	v_cmp_gt_f32_e32 vcc, s33, v2
	s_nop 1
	v_cndmask_b32_e64 v20, 0, 32, vcc
	v_ldexp_f32 v2, v2, v20
	v_log_f32_e32 v2, v2
	s_nop 0
	v_mul_f32_e32 v20, 0x3f317217, v2
	v_fma_f32 v20, v2, s72, -v20
	v_fmac_f32_e32 v20, 0x3377d1cf, v2
	v_fmac_f32_e32 v20, 0x3f317217, v2
	v_cmp_lt_f32_e64 s[0:1], |v2|, s73
	s_nop 1
	v_cndmask_b32_e64 v2, v2, v20, s[0:1]
	v_cndmask_b32_e32 v20, 0, v227, vcc
	v_sub_f32_e32 v2, v2, v20
	v_sub_f32_e32 v2, v3, v2
	v_fmamk_f32 v69, v2, 0x3d800000, v71
	v_sub_u32_e32 v2, 63, v100
	v_cndmask_b32_e64 v70, v2, v100, s[38:39]
	v_lshl_add_u32 v2, v70, 7, s37
	ds_read_b128 v[26:29], v2
	ds_read_b128 v[34:37], v2 offset:16
	ds_read_b128 v[38:41], v2 offset:32
	ds_read_b128 v[42:45], v2 offset:48
	s_waitcnt lgkmcnt(3)
	v_mul_f32_e32 v2, v24, v27
	v_fmac_f32_e32 v2, v23, v26
	s_waitcnt lgkmcnt(2)
	v_mul_f32_e32 v3, v19, v35
	v_fmac_f32_e32 v2, v25, v28
	v_fmac_f32_e32 v3, v0, v34
	v_fmac_f32_e32 v2, v87, v29
	v_fmac_f32_e32 v3, v22, v36
	v_add_f32_e32 v2, v249, v2
	v_fmac_f32_e32 v3, v245, v37
	v_add_f32_e32 v2, v2, v3
	s_waitcnt lgkmcnt(1)
	v_mul_f32_e32 v3, v246, v39
	v_fmac_f32_e32 v3, v85, v38
	v_fmac_f32_e32 v3, v247, v40
	v_fmac_f32_e32 v3, v248, v41
	v_add_f32_e32 v2, v2, v3
	s_waitcnt lgkmcnt(0)
	v_mul_f32_e32 v3, v5, v43
	v_fmac_f32_e32 v3, v1, v42
	v_fmac_f32_e32 v3, v17, v44
	v_fmac_f32_e32 v3, v4, v45
	v_add_f32_e32 v2, v2, v3
	v_min_f32_e32 v3, 0, v2
	v_mul_f32_e64 v2, |v2|, s97
	v_exp_f32_e32 v2, v2
	s_nop 0
	v_add_f32_e32 v2, 1.0, v2
	v_cmp_gt_f32_e32 vcc, s33, v2
	s_nop 1
	v_cndmask_b32_e64 v20, 0, 32, vcc
	v_ldexp_f32 v2, v2, v20
	v_log_f32_e32 v2, v2
	s_nop 0
	v_mul_f32_e32 v20, 0x3f317217, v2
	v_fma_f32 v20, v2, s72, -v20
	v_fmac_f32_e32 v20, 0x3377d1cf, v2
	v_fmac_f32_e32 v20, 0x3f317217, v2
	v_cmp_lt_f32_e64 s[0:1], |v2|, s73
	s_nop 1
	v_cndmask_b32_e64 v2, v2, v20, s[0:1]
	v_cndmask_b32_e32 v20, 0, v227, vcc
	v_sub_f32_e32 v2, v2, v20
	v_sub_f32_e32 v2, v3, v2
	v_fmamk_f32 v67, v2, 0x3d800000, v69
	v_sub_u32_e32 v2, 63, v101
	v_cndmask_b32_e64 v68, v2, v101, s[38:39]
	v_lshl_add_u32 v2, v68, 7, s37
	ds_read_b128 v[26:29], v2
	ds_read_b128 v[34:37], v2 offset:16
	ds_read_b128 v[38:41], v2 offset:32
	ds_read_b128 v[42:45], v2 offset:48
	s_waitcnt lgkmcnt(3)
	v_mul_f32_e32 v2, v24, v27
	v_fmac_f32_e32 v2, v23, v26
	s_waitcnt lgkmcnt(2)
	v_mul_f32_e32 v3, v19, v35
	v_fmac_f32_e32 v2, v25, v28
	v_fmac_f32_e32 v3, v0, v34
	v_fmac_f32_e32 v2, v87, v29
	v_fmac_f32_e32 v3, v22, v36
	v_add_f32_e32 v2, v249, v2
	v_fmac_f32_e32 v3, v245, v37
	v_add_f32_e32 v2, v2, v3
	s_waitcnt lgkmcnt(1)
	v_mul_f32_e32 v3, v246, v39
	v_fmac_f32_e32 v3, v85, v38
	v_fmac_f32_e32 v3, v247, v40
	v_fmac_f32_e32 v3, v248, v41
	v_add_f32_e32 v2, v2, v3
	s_waitcnt lgkmcnt(0)
	v_mul_f32_e32 v3, v5, v43
	v_fmac_f32_e32 v3, v1, v42
	v_fmac_f32_e32 v3, v17, v44
	v_fmac_f32_e32 v3, v4, v45
	v_add_f32_e32 v2, v2, v3
	v_min_f32_e32 v3, 0, v2
	v_mul_f32_e64 v2, |v2|, s97
	v_exp_f32_e32 v2, v2
	s_nop 0
	v_add_f32_e32 v2, 1.0, v2
	v_cmp_gt_f32_e32 vcc, s33, v2
	s_nop 1
	v_cndmask_b32_e64 v20, 0, 32, vcc
	v_ldexp_f32 v2, v2, v20
	v_log_f32_e32 v2, v2
	s_nop 0
	v_mul_f32_e32 v20, 0x3f317217, v2
	v_fma_f32 v20, v2, s72, -v20
	v_fmac_f32_e32 v20, 0x3377d1cf, v2
	v_fmac_f32_e32 v20, 0x3f317217, v2
	v_cmp_lt_f32_e64 s[0:1], |v2|, s73
	s_nop 1
	v_cndmask_b32_e64 v2, v2, v20, s[0:1]
	v_cndmask_b32_e32 v20, 0, v227, vcc
	v_sub_f32_e32 v2, v2, v20
	v_sub_f32_e32 v2, v3, v2
	v_fmamk_f32 v65, v2, 0x3d800000, v67
	v_sub_u32_e32 v2, 63, v102
	v_cndmask_b32_e64 v66, v2, v102, s[38:39]
	v_lshl_add_u32 v2, v66, 7, s37
	ds_read_b128 v[26:29], v2
	ds_read_b128 v[34:37], v2 offset:16
	ds_read_b128 v[38:41], v2 offset:32
	ds_read_b128 v[42:45], v2 offset:48
	s_waitcnt lgkmcnt(3)
	v_mul_f32_e32 v2, v24, v27
	v_fmac_f32_e32 v2, v23, v26
	s_waitcnt lgkmcnt(2)
	v_mul_f32_e32 v3, v19, v35
	v_fmac_f32_e32 v2, v25, v28
	v_fmac_f32_e32 v3, v0, v34
	v_fmac_f32_e32 v2, v87, v29
	v_fmac_f32_e32 v3, v22, v36
	v_add_f32_e32 v2, v249, v2
	v_fmac_f32_e32 v3, v245, v37
	v_add_f32_e32 v2, v2, v3
	s_waitcnt lgkmcnt(1)
	v_mul_f32_e32 v3, v246, v39
	v_fmac_f32_e32 v3, v85, v38
	v_fmac_f32_e32 v3, v247, v40
	v_fmac_f32_e32 v3, v248, v41
	v_add_f32_e32 v2, v2, v3
	s_waitcnt lgkmcnt(0)
	v_mul_f32_e32 v3, v5, v43
	v_fmac_f32_e32 v3, v1, v42
	v_fmac_f32_e32 v3, v17, v44
	v_fmac_f32_e32 v3, v4, v45
	v_add_f32_e32 v2, v2, v3
	v_min_f32_e32 v3, 0, v2
	v_mul_f32_e64 v2, |v2|, s97
	v_exp_f32_e32 v2, v2
	s_nop 0
	v_add_f32_e32 v2, 1.0, v2
	v_cmp_gt_f32_e32 vcc, s33, v2
	s_nop 1
	v_cndmask_b32_e64 v20, 0, 32, vcc
	v_ldexp_f32 v2, v2, v20
	v_log_f32_e32 v2, v2
	s_nop 0
	v_mul_f32_e32 v20, 0x3f317217, v2
	v_fma_f32 v20, v2, s72, -v20
	v_fmac_f32_e32 v20, 0x3377d1cf, v2
	v_fmac_f32_e32 v20, 0x3f317217, v2
	v_cmp_lt_f32_e64 s[0:1], |v2|, s73
	s_nop 1
	v_cndmask_b32_e64 v2, v2, v20, s[0:1]
	v_cndmask_b32_e32 v20, 0, v227, vcc
	v_sub_f32_e32 v2, v2, v20
	v_sub_f32_e32 v2, v3, v2
	v_fmamk_f32 v63, v2, 0x3d800000, v65
	v_sub_u32_e32 v2, 63, v103
	v_cndmask_b32_e64 v64, v2, v103, s[38:39]
	v_lshl_add_u32 v2, v64, 7, s37
	ds_read_b128 v[26:29], v2
	ds_read_b128 v[34:37], v2 offset:16
	ds_read_b128 v[38:41], v2 offset:32
	ds_read_b128 v[42:45], v2 offset:48
	s_waitcnt lgkmcnt(3)
	v_mul_f32_e32 v2, v24, v27
	v_fmac_f32_e32 v2, v23, v26
	s_waitcnt lgkmcnt(2)
	v_mul_f32_e32 v3, v19, v35
	v_fmac_f32_e32 v2, v25, v28
	v_fmac_f32_e32 v3, v0, v34
	v_fmac_f32_e32 v2, v87, v29
	v_fmac_f32_e32 v3, v22, v36
	v_add_f32_e32 v2, v249, v2
	v_fmac_f32_e32 v3, v245, v37
	v_add_f32_e32 v2, v2, v3
	s_waitcnt lgkmcnt(1)
	v_mul_f32_e32 v3, v246, v39
	v_fmac_f32_e32 v3, v85, v38
	v_fmac_f32_e32 v3, v247, v40
	v_fmac_f32_e32 v3, v248, v41
	v_add_f32_e32 v2, v2, v3
	s_waitcnt lgkmcnt(0)
	v_mul_f32_e32 v3, v5, v43
	v_fmac_f32_e32 v3, v1, v42
	v_fmac_f32_e32 v3, v17, v44
	v_fmac_f32_e32 v3, v4, v45
	v_add_f32_e32 v2, v2, v3
	v_min_f32_e32 v3, 0, v2
	v_mul_f32_e64 v2, |v2|, s97
	v_exp_f32_e32 v2, v2
	s_nop 0
	v_add_f32_e32 v2, 1.0, v2
	v_cmp_gt_f32_e32 vcc, s33, v2
	s_nop 1
	v_cndmask_b32_e64 v20, 0, 32, vcc
	v_ldexp_f32 v2, v2, v20
	v_log_f32_e32 v2, v2
	s_nop 0
	v_mul_f32_e32 v20, 0x3f317217, v2
	v_fma_f32 v20, v2, s72, -v20
	v_fmac_f32_e32 v20, 0x3377d1cf, v2
	v_fmac_f32_e32 v20, 0x3f317217, v2
	v_cmp_lt_f32_e64 s[0:1], |v2|, s73
	s_nop 1
	v_cndmask_b32_e64 v2, v2, v20, s[0:1]
	v_cndmask_b32_e32 v20, 0, v227, vcc
	v_sub_f32_e32 v2, v2, v20
	v_sub_f32_e32 v2, v3, v2
	v_fmamk_f32 v61, v2, 0x3d800000, v63
	v_sub_u32_e32 v2, 63, v104
	v_cndmask_b32_e64 v62, v2, v104, s[38:39]
	v_lshl_add_u32 v2, v62, 7, s37
	ds_read_b128 v[26:29], v2
	ds_read_b128 v[34:37], v2 offset:16
	ds_read_b128 v[38:41], v2 offset:32
	ds_read_b128 v[42:45], v2 offset:48
	s_waitcnt lgkmcnt(3)
	v_mul_f32_e32 v2, v24, v27
	v_fmac_f32_e32 v2, v23, v26
	s_waitcnt lgkmcnt(2)
	v_mul_f32_e32 v3, v19, v35
	v_fmac_f32_e32 v2, v25, v28
	v_fmac_f32_e32 v3, v0, v34
	v_fmac_f32_e32 v2, v87, v29
	v_fmac_f32_e32 v3, v22, v36
	v_add_f32_e32 v2, v249, v2
	v_fmac_f32_e32 v3, v245, v37
	v_add_f32_e32 v2, v2, v3
	s_waitcnt lgkmcnt(1)
	v_mul_f32_e32 v3, v246, v39
	v_fmac_f32_e32 v3, v85, v38
	v_fmac_f32_e32 v3, v247, v40
	v_fmac_f32_e32 v3, v248, v41
	v_add_f32_e32 v2, v2, v3
	s_waitcnt lgkmcnt(0)
	v_mul_f32_e32 v3, v5, v43
	v_fmac_f32_e32 v3, v1, v42
	v_fmac_f32_e32 v3, v17, v44
	v_fmac_f32_e32 v3, v4, v45
	v_add_f32_e32 v2, v2, v3
	v_min_f32_e32 v3, 0, v2
	v_mul_f32_e64 v2, |v2|, s97
	v_exp_f32_e32 v2, v2
	s_nop 0
	v_add_f32_e32 v2, 1.0, v2
	v_cmp_gt_f32_e32 vcc, s33, v2
	s_nop 1
	v_cndmask_b32_e64 v20, 0, 32, vcc
	v_ldexp_f32 v2, v2, v20
	v_log_f32_e32 v2, v2
	s_nop 0
	v_mul_f32_e32 v20, 0x3f317217, v2
	v_fma_f32 v20, v2, s72, -v20
	v_fmac_f32_e32 v20, 0x3377d1cf, v2
	v_fmac_f32_e32 v20, 0x3f317217, v2
	v_cmp_lt_f32_e64 s[0:1], |v2|, s73
	s_nop 1
	v_cndmask_b32_e64 v2, v2, v20, s[0:1]
	v_cndmask_b32_e32 v20, 0, v227, vcc
	v_sub_f32_e32 v2, v2, v20
	v_sub_f32_e32 v2, v3, v2
	v_fmamk_f32 v59, v2, 0x3d800000, v61
	v_sub_u32_e32 v2, 63, v105
	v_cndmask_b32_e64 v60, v2, v105, s[38:39]
	v_lshl_add_u32 v2, v60, 7, s37
	ds_read_b128 v[26:29], v2
	ds_read_b128 v[34:37], v2 offset:16
	ds_read_b128 v[38:41], v2 offset:32
	ds_read_b128 v[42:45], v2 offset:48
	s_waitcnt lgkmcnt(3)
	v_mul_f32_e32 v2, v24, v27
	v_fmac_f32_e32 v2, v23, v26
	s_waitcnt lgkmcnt(2)
	v_mul_f32_e32 v3, v19, v35
	v_fmac_f32_e32 v2, v25, v28
	v_fmac_f32_e32 v3, v0, v34
	v_fmac_f32_e32 v2, v87, v29
	v_fmac_f32_e32 v3, v22, v36
	v_add_f32_e32 v2, v249, v2
	v_fmac_f32_e32 v3, v245, v37
	v_add_f32_e32 v2, v2, v3
	s_waitcnt lgkmcnt(1)
	v_mul_f32_e32 v3, v246, v39
	v_fmac_f32_e32 v3, v85, v38
	v_fmac_f32_e32 v3, v247, v40
	v_fmac_f32_e32 v3, v248, v41
	v_add_f32_e32 v2, v2, v3
	s_waitcnt lgkmcnt(0)
	v_mul_f32_e32 v3, v5, v43
	v_fmac_f32_e32 v3, v1, v42
	v_fmac_f32_e32 v3, v17, v44
	v_fmac_f32_e32 v3, v4, v45
	v_add_f32_e32 v2, v2, v3
	v_min_f32_e32 v3, 0, v2
	v_mul_f32_e64 v2, |v2|, s97
	v_exp_f32_e32 v2, v2
	s_nop 0
	v_add_f32_e32 v2, 1.0, v2
	v_cmp_gt_f32_e32 vcc, s33, v2
	s_nop 1
	v_cndmask_b32_e64 v20, 0, 32, vcc
	v_ldexp_f32 v2, v2, v20
	v_log_f32_e32 v2, v2
	s_nop 0
	v_mul_f32_e32 v20, 0x3f317217, v2
	v_fma_f32 v20, v2, s72, -v20
	v_fmac_f32_e32 v20, 0x3377d1cf, v2
	v_fmac_f32_e32 v20, 0x3f317217, v2
	v_cmp_lt_f32_e64 s[0:1], |v2|, s73
	s_nop 1
	v_cndmask_b32_e64 v2, v2, v20, s[0:1]
	v_cndmask_b32_e32 v20, 0, v227, vcc
	v_sub_f32_e32 v2, v2, v20
	v_sub_f32_e32 v2, v3, v2
	v_fmamk_f32 v57, v2, 0x3d800000, v59
	v_sub_u32_e32 v2, 63, v106
	v_cndmask_b32_e64 v58, v2, v106, s[38:39]
	v_lshl_add_u32 v2, v58, 7, s37
	ds_read_b128 v[26:29], v2
	ds_read_b128 v[34:37], v2 offset:16
	ds_read_b128 v[38:41], v2 offset:32
	ds_read_b128 v[42:45], v2 offset:48
	s_waitcnt lgkmcnt(3)
	v_mul_f32_e32 v2, v24, v27
	v_fmac_f32_e32 v2, v23, v26
	s_waitcnt lgkmcnt(2)
	v_mul_f32_e32 v3, v19, v35
	v_fmac_f32_e32 v2, v25, v28
	v_fmac_f32_e32 v3, v0, v34
	v_fmac_f32_e32 v2, v87, v29
	v_fmac_f32_e32 v3, v22, v36
	v_add_f32_e32 v2, v249, v2
	v_fmac_f32_e32 v3, v245, v37
	v_add_f32_e32 v2, v2, v3
	s_waitcnt lgkmcnt(1)
	v_mul_f32_e32 v3, v246, v39
	v_fmac_f32_e32 v3, v85, v38
	v_fmac_f32_e32 v3, v247, v40
	v_fmac_f32_e32 v3, v248, v41
	v_add_f32_e32 v2, v2, v3
	s_waitcnt lgkmcnt(0)
	v_mul_f32_e32 v3, v5, v43
	v_fmac_f32_e32 v3, v1, v42
	v_fmac_f32_e32 v3, v17, v44
	v_fmac_f32_e32 v3, v4, v45
	v_add_f32_e32 v2, v2, v3
	v_min_f32_e32 v3, 0, v2
	v_mul_f32_e64 v2, |v2|, s97
	v_exp_f32_e32 v2, v2
	s_nop 0
	v_add_f32_e32 v2, 1.0, v2
	v_cmp_gt_f32_e32 vcc, s33, v2
	s_nop 1
	v_cndmask_b32_e64 v20, 0, 32, vcc
	v_ldexp_f32 v2, v2, v20
	v_log_f32_e32 v2, v2
	s_nop 0
	v_mul_f32_e32 v20, 0x3f317217, v2
	v_fma_f32 v20, v2, s72, -v20
	v_fmac_f32_e32 v20, 0x3377d1cf, v2
	v_fmac_f32_e32 v20, 0x3f317217, v2
	v_cmp_lt_f32_e64 s[0:1], |v2|, s73
	s_nop 1
	v_cndmask_b32_e64 v2, v2, v20, s[0:1]
	v_cndmask_b32_e32 v20, 0, v227, vcc
	v_sub_f32_e32 v2, v2, v20
	v_sub_f32_e32 v2, v3, v2
	v_fmamk_f32 v55, v2, 0x3d800000, v57
	v_sub_u32_e32 v2, 63, v107
	v_cndmask_b32_e64 v56, v2, v107, s[38:39]
	v_lshl_add_u32 v2, v56, 7, s37
	ds_read_b128 v[26:29], v2
	ds_read_b128 v[34:37], v2 offset:16
	ds_read_b128 v[38:41], v2 offset:32
	ds_read_b128 v[42:45], v2 offset:48
	s_waitcnt lgkmcnt(3)
	v_mul_f32_e32 v2, v24, v27
	v_fmac_f32_e32 v2, v23, v26
	s_waitcnt lgkmcnt(2)
	v_mul_f32_e32 v3, v19, v35
	v_fmac_f32_e32 v2, v25, v28
	v_fmac_f32_e32 v3, v0, v34
	v_fmac_f32_e32 v2, v87, v29
	v_fmac_f32_e32 v3, v22, v36
	v_add_f32_e32 v2, v249, v2
	v_fmac_f32_e32 v3, v245, v37
	v_add_f32_e32 v2, v2, v3
	s_waitcnt lgkmcnt(1)
	v_mul_f32_e32 v3, v246, v39
	v_fmac_f32_e32 v3, v85, v38
	v_fmac_f32_e32 v3, v247, v40
	v_fmac_f32_e32 v3, v248, v41
	v_add_f32_e32 v2, v2, v3
	s_waitcnt lgkmcnt(0)
	v_mul_f32_e32 v3, v5, v43
	v_fmac_f32_e32 v3, v1, v42
	v_fmac_f32_e32 v3, v17, v44
	v_fmac_f32_e32 v3, v4, v45
	v_add_f32_e32 v2, v2, v3
	v_min_f32_e32 v3, 0, v2
	v_mul_f32_e64 v2, |v2|, s97
	v_exp_f32_e32 v2, v2
	s_nop 0
	v_add_f32_e32 v2, 1.0, v2
	v_cmp_gt_f32_e32 vcc, s33, v2
	s_nop 1
	v_cndmask_b32_e64 v20, 0, 32, vcc
	v_ldexp_f32 v2, v2, v20
	v_log_f32_e32 v2, v2
	s_nop 0
	v_mul_f32_e32 v20, 0x3f317217, v2
	v_fma_f32 v20, v2, s72, -v20
	v_fmac_f32_e32 v20, 0x3377d1cf, v2
	v_fmac_f32_e32 v20, 0x3f317217, v2
	v_cmp_lt_f32_e64 s[0:1], |v2|, s73
	s_nop 1
	v_cndmask_b32_e64 v2, v2, v20, s[0:1]
	v_cndmask_b32_e32 v20, 0, v227, vcc
	v_sub_f32_e32 v2, v2, v20
	v_sub_f32_e32 v2, v3, v2
	v_fmamk_f32 v53, v2, 0x3d800000, v55
	v_sub_u32_e32 v2, 63, v108
	v_cndmask_b32_e64 v54, v2, v108, s[38:39]
	v_lshl_add_u32 v2, v54, 7, s37
	ds_read_b128 v[26:29], v2
	ds_read_b128 v[34:37], v2 offset:16
	ds_read_b128 v[38:41], v2 offset:32
	ds_read_b128 v[42:45], v2 offset:48
	s_waitcnt lgkmcnt(3)
	v_mul_f32_e32 v2, v24, v27
	v_fmac_f32_e32 v2, v23, v26
	s_waitcnt lgkmcnt(2)
	v_mul_f32_e32 v3, v19, v35
	v_fmac_f32_e32 v2, v25, v28
	v_fmac_f32_e32 v3, v0, v34
	v_fmac_f32_e32 v2, v87, v29
	v_fmac_f32_e32 v3, v22, v36
	v_add_f32_e32 v2, v249, v2
	v_fmac_f32_e32 v3, v245, v37
	v_add_f32_e32 v2, v2, v3
	s_waitcnt lgkmcnt(1)
	v_mul_f32_e32 v3, v246, v39
	v_fmac_f32_e32 v3, v85, v38
	v_fmac_f32_e32 v3, v247, v40
	v_fmac_f32_e32 v3, v248, v41
	v_add_f32_e32 v2, v2, v3
	s_waitcnt lgkmcnt(0)
	v_mul_f32_e32 v3, v5, v43
	v_fmac_f32_e32 v3, v1, v42
	v_fmac_f32_e32 v3, v17, v44
	v_fmac_f32_e32 v3, v4, v45
	v_add_f32_e32 v2, v2, v3
	v_min_f32_e32 v3, 0, v2
	v_mul_f32_e64 v2, |v2|, s97
	v_exp_f32_e32 v2, v2
	s_nop 0
	v_add_f32_e32 v2, 1.0, v2
	v_cmp_gt_f32_e32 vcc, s33, v2
	s_nop 1
	v_cndmask_b32_e64 v20, 0, 32, vcc
	v_ldexp_f32 v2, v2, v20
	v_log_f32_e32 v2, v2
	s_nop 0
	v_mul_f32_e32 v20, 0x3f317217, v2
	v_fma_f32 v20, v2, s72, -v20
	v_fmac_f32_e32 v20, 0x3377d1cf, v2
	v_fmac_f32_e32 v20, 0x3f317217, v2
	v_cmp_lt_f32_e64 s[0:1], |v2|, s73
	s_nop 1
	v_cndmask_b32_e64 v2, v2, v20, s[0:1]
	v_cndmask_b32_e32 v20, 0, v227, vcc
	v_sub_f32_e32 v2, v2, v20
	v_sub_f32_e32 v2, v3, v2
	v_fmamk_f32 v51, v2, 0x3d800000, v53
	v_sub_u32_e32 v2, 63, v109
	v_cndmask_b32_e64 v52, v2, v109, s[38:39]
	v_lshl_add_u32 v2, v52, 7, s37
	ds_read_b128 v[26:29], v2
	ds_read_b128 v[34:37], v2 offset:16
	ds_read_b128 v[38:41], v2 offset:32
	ds_read_b128 v[42:45], v2 offset:48
	s_waitcnt lgkmcnt(3)
	v_mul_f32_e32 v2, v24, v27
	v_fmac_f32_e32 v2, v23, v26
	s_waitcnt lgkmcnt(2)
	v_mul_f32_e32 v3, v19, v35
	v_fmac_f32_e32 v2, v25, v28
	v_fmac_f32_e32 v3, v0, v34
	v_fmac_f32_e32 v2, v87, v29
	v_fmac_f32_e32 v3, v22, v36
	v_add_f32_e32 v2, v249, v2
	v_fmac_f32_e32 v3, v245, v37
	v_add_f32_e32 v2, v2, v3
	s_waitcnt lgkmcnt(1)
	v_mul_f32_e32 v3, v246, v39
	v_fmac_f32_e32 v3, v85, v38
	v_fmac_f32_e32 v3, v247, v40
	v_fmac_f32_e32 v3, v248, v41
	v_add_f32_e32 v2, v2, v3
	s_waitcnt lgkmcnt(0)
	v_mul_f32_e32 v3, v5, v43
	v_fmac_f32_e32 v3, v1, v42
	v_fmac_f32_e32 v3, v17, v44
	v_fmac_f32_e32 v3, v4, v45
	v_add_f32_e32 v2, v2, v3
	v_min_f32_e32 v3, 0, v2
	v_mul_f32_e64 v2, |v2|, s97
	v_exp_f32_e32 v2, v2
	s_nop 0
	v_add_f32_e32 v2, 1.0, v2
	v_cmp_gt_f32_e32 vcc, s33, v2
	s_nop 1
	v_cndmask_b32_e64 v20, 0, 32, vcc
	v_ldexp_f32 v2, v2, v20
	v_log_f32_e32 v2, v2
	s_nop 0
	v_mul_f32_e32 v20, 0x3f317217, v2
	v_fma_f32 v20, v2, s72, -v20
	v_fmac_f32_e32 v20, 0x3377d1cf, v2
	v_fmac_f32_e32 v20, 0x3f317217, v2
	v_cmp_lt_f32_e64 s[0:1], |v2|, s73
	s_nop 1
	v_cndmask_b32_e64 v2, v2, v20, s[0:1]
	v_cndmask_b32_e32 v20, 0, v227, vcc
	v_sub_f32_e32 v2, v2, v20
	v_sub_f32_e32 v2, v3, v2
	v_fmamk_f32 v49, v2, 0x3d800000, v51
	v_sub_u32_e32 v2, 63, v110
	v_cndmask_b32_e64 v50, v2, v110, s[38:39]
	v_lshl_add_u32 v2, v50, 7, s37
	ds_read_b128 v[26:29], v2
	ds_read_b128 v[34:37], v2 offset:16
	ds_read_b128 v[38:41], v2 offset:32
	ds_read_b128 v[42:45], v2 offset:48
	s_waitcnt lgkmcnt(3)
	v_mul_f32_e32 v2, v24, v27
	v_fmac_f32_e32 v2, v23, v26
	s_waitcnt lgkmcnt(2)
	v_mul_f32_e32 v3, v19, v35
	v_fmac_f32_e32 v2, v25, v28
	v_fmac_f32_e32 v3, v0, v34
	v_fmac_f32_e32 v2, v87, v29
	v_fmac_f32_e32 v3, v22, v36
	v_add_f32_e32 v2, v249, v2
	v_fmac_f32_e32 v3, v245, v37
	v_add_f32_e32 v2, v2, v3
	s_waitcnt lgkmcnt(1)
	v_mul_f32_e32 v3, v246, v39
	v_fmac_f32_e32 v3, v85, v38
	v_fmac_f32_e32 v3, v247, v40
	v_fmac_f32_e32 v3, v248, v41
	v_add_f32_e32 v2, v2, v3
	s_waitcnt lgkmcnt(0)
	v_mul_f32_e32 v3, v5, v43
	v_fmac_f32_e32 v3, v1, v42
	v_fmac_f32_e32 v3, v17, v44
	v_fmac_f32_e32 v3, v4, v45
	v_add_f32_e32 v2, v2, v3
	v_min_f32_e32 v3, 0, v2
	v_mul_f32_e64 v2, |v2|, s97
	v_exp_f32_e32 v2, v2
	s_nop 0
	v_add_f32_e32 v2, 1.0, v2
	v_cmp_gt_f32_e32 vcc, s33, v2
	s_nop 1
	v_cndmask_b32_e64 v20, 0, 32, vcc
	v_ldexp_f32 v2, v2, v20
	v_log_f32_e32 v2, v2
	s_nop 0
	v_mul_f32_e32 v20, 0x3f317217, v2
	v_fma_f32 v20, v2, s72, -v20
	v_fmac_f32_e32 v20, 0x3377d1cf, v2
	v_fmac_f32_e32 v20, 0x3f317217, v2
	v_cmp_lt_f32_e64 s[0:1], |v2|, s73
	s_nop 1
	v_cndmask_b32_e64 v2, v2, v20, s[0:1]
	v_cndmask_b32_e32 v20, 0, v227, vcc
	v_sub_f32_e32 v2, v2, v20
	v_sub_f32_e32 v2, v3, v2
	v_fmamk_f32 v47, v2, 0x3d800000, v49
	v_sub_u32_e32 v2, 63, v111
	v_cndmask_b32_e64 v48, v2, v111, s[38:39]
	v_lshl_add_u32 v2, v48, 7, s37
	ds_read_b128 v[26:29], v2
	ds_read_b128 v[34:37], v2 offset:16
	ds_read_b128 v[38:41], v2 offset:32
	ds_read_b128 v[42:45], v2 offset:48
	s_waitcnt lgkmcnt(3)
	v_mul_f32_e32 v2, v24, v27
	v_fmac_f32_e32 v2, v23, v26
	s_waitcnt lgkmcnt(2)
	v_mul_f32_e32 v3, v19, v35
	v_fmac_f32_e32 v2, v25, v28
	v_fmac_f32_e32 v3, v0, v34
	v_fmac_f32_e32 v2, v87, v29
	v_fmac_f32_e32 v3, v22, v36
	v_add_f32_e32 v2, v249, v2
	v_fmac_f32_e32 v3, v245, v37
	v_add_f32_e32 v2, v2, v3
	s_waitcnt lgkmcnt(1)
	v_mul_f32_e32 v3, v246, v39
	v_fmac_f32_e32 v3, v85, v38
	v_fmac_f32_e32 v3, v247, v40
	v_fmac_f32_e32 v3, v248, v41
	v_add_f32_e32 v2, v2, v3
	s_waitcnt lgkmcnt(0)
	v_mul_f32_e32 v3, v5, v43
	v_fmac_f32_e32 v3, v1, v42
	v_fmac_f32_e32 v3, v17, v44
	v_fmac_f32_e32 v3, v4, v45
	v_add_f32_e32 v2, v2, v3
	v_min_f32_e32 v3, 0, v2
	v_mul_f32_e64 v2, |v2|, s97
	v_exp_f32_e32 v2, v2
	s_nop 0
	v_add_f32_e32 v2, 1.0, v2
	v_cmp_gt_f32_e32 vcc, s33, v2
	s_nop 1
	v_cndmask_b32_e64 v20, 0, 32, vcc
	v_ldexp_f32 v2, v2, v20
	v_log_f32_e32 v2, v2
	s_nop 0
	v_mul_f32_e32 v20, 0x3f317217, v2
	v_fma_f32 v20, v2, s72, -v20
	v_fmac_f32_e32 v20, 0x3377d1cf, v2
	v_fmac_f32_e32 v20, 0x3f317217, v2
	v_cmp_lt_f32_e64 s[0:1], |v2|, s73
	s_nop 1
	v_cndmask_b32_e64 v2, v2, v20, s[0:1]
	v_cndmask_b32_e32 v20, 0, v227, vcc
	v_sub_f32_e32 v2, v2, v20
	v_sub_f32_e32 v2, v3, v2
	v_fmamk_f32 v45, v2, 0x3d800000, v47
	v_sub_u32_e32 v2, 63, v112
	v_cndmask_b32_e64 v46, v2, v112, s[38:39]
	v_lshl_add_u32 v2, v46, 7, s37
	ds_read_b128 v[26:29], v2
	ds_read_b128 v[34:37], v2 offset:16
	ds_read_b128 v[38:41], v2 offset:32
	ds_read_b128 v[220:223], v2 offset:48
	s_waitcnt lgkmcnt(3)
	v_mul_f32_e32 v2, v24, v27
	v_fmac_f32_e32 v2, v23, v26
	s_waitcnt lgkmcnt(2)
	v_mul_f32_e32 v3, v19, v35
	v_fmac_f32_e32 v2, v25, v28
	v_fmac_f32_e32 v3, v0, v34
	v_fmac_f32_e32 v2, v87, v29
	v_fmac_f32_e32 v3, v22, v36
	v_add_f32_e32 v2, v249, v2
	v_fmac_f32_e32 v3, v245, v37
	v_add_f32_e32 v2, v2, v3
	s_waitcnt lgkmcnt(1)
	v_mul_f32_e32 v3, v246, v39
	v_fmac_f32_e32 v3, v85, v38
	v_fmac_f32_e32 v3, v247, v40
	v_fmac_f32_e32 v3, v248, v41
	v_add_f32_e32 v2, v2, v3
	s_waitcnt lgkmcnt(0)
	v_mul_f32_e32 v3, v5, v221
	v_fmac_f32_e32 v3, v1, v220
	v_fmac_f32_e32 v3, v17, v222
	v_fmac_f32_e32 v3, v4, v223
	v_add_f32_e32 v2, v2, v3
	v_min_f32_e32 v3, 0, v2
	v_mul_f32_e64 v2, |v2|, s97
	v_exp_f32_e32 v2, v2
	s_nop 0
	v_add_f32_e32 v2, 1.0, v2
	v_cmp_gt_f32_e32 vcc, s33, v2
	s_nop 1
	v_cndmask_b32_e64 v20, 0, 32, vcc
	v_ldexp_f32 v2, v2, v20
	v_log_f32_e32 v2, v2
	s_nop 0
	v_mul_f32_e32 v20, 0x3f317217, v2
	v_fma_f32 v20, v2, s72, -v20
	v_fmac_f32_e32 v20, 0x3377d1cf, v2
	v_fmac_f32_e32 v20, 0x3f317217, v2
	v_cmp_lt_f32_e64 s[0:1], |v2|, s73
	s_nop 1
	v_cndmask_b32_e64 v2, v2, v20, s[0:1]
	v_cndmask_b32_e32 v20, 0, v227, vcc
	v_sub_f32_e32 v2, v2, v20
	v_sub_f32_e32 v2, v3, v2
	v_fmamk_f32 v43, v2, 0x3d800000, v45
	v_sub_u32_e32 v2, 63, v113
	v_cndmask_b32_e64 v44, v2, v113, s[38:39]
	v_lshl_add_u32 v2, v44, 7, s37
	ds_read_b128 v[26:29], v2
	ds_read_b128 v[34:37], v2 offset:16
	ds_read_b128 v[38:41], v2 offset:32
	ds_read_b128 v[220:223], v2 offset:48
	s_waitcnt lgkmcnt(3)
	v_mul_f32_e32 v2, v24, v27
	v_fmac_f32_e32 v2, v23, v26
	s_waitcnt lgkmcnt(2)
	v_mul_f32_e32 v3, v19, v35
	v_fmac_f32_e32 v2, v25, v28
	v_fmac_f32_e32 v3, v0, v34
	v_fmac_f32_e32 v2, v87, v29
	v_fmac_f32_e32 v3, v22, v36
	v_add_f32_e32 v2, v249, v2
	v_fmac_f32_e32 v3, v245, v37
	v_add_f32_e32 v2, v2, v3
	s_waitcnt lgkmcnt(1)
	v_mul_f32_e32 v3, v246, v39
	v_fmac_f32_e32 v3, v85, v38
	v_fmac_f32_e32 v3, v247, v40
	v_fmac_f32_e32 v3, v248, v41
	v_add_f32_e32 v2, v2, v3
	s_waitcnt lgkmcnt(0)
	v_mul_f32_e32 v3, v5, v221
	v_fmac_f32_e32 v3, v1, v220
	v_fmac_f32_e32 v3, v17, v222
	v_fmac_f32_e32 v3, v4, v223
	v_add_f32_e32 v2, v2, v3
	v_min_f32_e32 v3, 0, v2
	v_mul_f32_e64 v2, |v2|, s97
	v_exp_f32_e32 v2, v2
	s_nop 0
	v_add_f32_e32 v2, 1.0, v2
	v_cmp_gt_f32_e32 vcc, s33, v2
	s_nop 1
	v_cndmask_b32_e64 v20, 0, 32, vcc
	v_ldexp_f32 v2, v2, v20
	v_log_f32_e32 v2, v2
	s_nop 0
	v_mul_f32_e32 v20, 0x3f317217, v2
	v_fma_f32 v20, v2, s72, -v20
	v_fmac_f32_e32 v20, 0x3377d1cf, v2
	v_fmac_f32_e32 v20, 0x3f317217, v2
	v_cmp_lt_f32_e64 s[0:1], |v2|, s73
	s_nop 1
	v_cndmask_b32_e64 v2, v2, v20, s[0:1]
	v_cndmask_b32_e32 v20, 0, v227, vcc
	v_sub_f32_e32 v2, v2, v20
	v_sub_f32_e32 v2, v3, v2
	v_fmamk_f32 v41, v2, 0x3d800000, v43
	v_sub_u32_e32 v2, 63, v114
	v_cndmask_b32_e64 v42, v2, v114, s[38:39]
	v_lshl_add_u32 v2, v42, 7, s37
	ds_read_b128 v[26:29], v2
	ds_read_b128 v[34:37], v2 offset:16
	ds_read_b128 v[220:223], v2 offset:32
	ds_read_b128 v[156:159], v2 offset:48
	s_waitcnt lgkmcnt(3)
	v_mul_f32_e32 v2, v24, v27
	v_fmac_f32_e32 v2, v23, v26
	s_waitcnt lgkmcnt(2)
	v_mul_f32_e32 v3, v19, v35
	v_fmac_f32_e32 v2, v25, v28
	v_fmac_f32_e32 v3, v0, v34
	v_fmac_f32_e32 v2, v87, v29
	v_fmac_f32_e32 v3, v22, v36
	v_add_f32_e32 v2, v249, v2
	v_fmac_f32_e32 v3, v245, v37
	v_add_f32_e32 v2, v2, v3
	s_waitcnt lgkmcnt(1)
	v_mul_f32_e32 v3, v246, v221
	v_fmac_f32_e32 v3, v85, v220
	v_fmac_f32_e32 v3, v247, v222
	v_fmac_f32_e32 v3, v248, v223
	v_add_f32_e32 v2, v2, v3
	s_waitcnt lgkmcnt(0)
	v_mul_f32_e32 v3, v5, v157
	v_fmac_f32_e32 v3, v1, v156
	v_fmac_f32_e32 v3, v17, v158
	v_fmac_f32_e32 v3, v4, v159
	v_add_f32_e32 v2, v2, v3
	v_min_f32_e32 v3, 0, v2
	v_mul_f32_e64 v2, |v2|, s97
	v_exp_f32_e32 v2, v2
	s_nop 0
	v_add_f32_e32 v2, 1.0, v2
	v_cmp_gt_f32_e32 vcc, s33, v2
	s_nop 1
	v_cndmask_b32_e64 v20, 0, 32, vcc
	v_ldexp_f32 v2, v2, v20
	v_log_f32_e32 v2, v2
	s_nop 0
	v_mul_f32_e32 v20, 0x3f317217, v2
	v_fma_f32 v20, v2, s72, -v20
	v_fmac_f32_e32 v20, 0x3377d1cf, v2
	v_fmac_f32_e32 v20, 0x3f317217, v2
	v_cmp_lt_f32_e64 s[0:1], |v2|, s73
	s_nop 1
	v_cndmask_b32_e64 v2, v2, v20, s[0:1]
	v_cndmask_b32_e32 v20, 0, v227, vcc
	v_sub_f32_e32 v2, v2, v20
	v_sub_f32_e32 v2, v3, v2
	v_fmamk_f32 v39, v2, 0x3d800000, v41
	v_sub_u32_e32 v2, 63, v115
	v_cndmask_b32_e64 v40, v2, v115, s[38:39]
	v_lshl_add_u32 v2, v40, 7, s37
	ds_read_b128 v[26:29], v2
	ds_read_b128 v[34:37], v2 offset:16
	ds_read_b128 v[156:159], v2 offset:32
	ds_read_b128 v[220:223], v2 offset:48
	s_waitcnt lgkmcnt(3)
	v_mul_f32_e32 v2, v24, v27
	v_fmac_f32_e32 v2, v23, v26
	s_waitcnt lgkmcnt(2)
	v_mul_f32_e32 v3, v19, v35
	v_fmac_f32_e32 v2, v25, v28
	v_fmac_f32_e32 v3, v0, v34
	v_fmac_f32_e32 v2, v87, v29
	v_fmac_f32_e32 v3, v22, v36
	v_add_f32_e32 v2, v249, v2
	v_fmac_f32_e32 v3, v245, v37
	v_add_f32_e32 v2, v2, v3
	s_waitcnt lgkmcnt(1)
	v_mul_f32_e32 v3, v246, v157
	v_fmac_f32_e32 v3, v85, v156
	v_fmac_f32_e32 v3, v247, v158
	v_fmac_f32_e32 v3, v248, v159
	v_add_f32_e32 v2, v2, v3
	s_waitcnt lgkmcnt(0)
	v_mul_f32_e32 v3, v5, v221
	v_fmac_f32_e32 v3, v1, v220
	v_fmac_f32_e32 v3, v17, v222
	v_fmac_f32_e32 v3, v4, v223
	v_add_f32_e32 v2, v2, v3
	v_min_f32_e32 v3, 0, v2
	v_mul_f32_e64 v2, |v2|, s97
	v_exp_f32_e32 v2, v2
	s_nop 0
	v_add_f32_e32 v2, 1.0, v2
	v_cmp_gt_f32_e32 vcc, s33, v2
	s_nop 1
	v_cndmask_b32_e64 v20, 0, 32, vcc
	v_ldexp_f32 v2, v2, v20
	v_log_f32_e32 v2, v2
	s_nop 0
	v_mul_f32_e32 v20, 0x3f317217, v2
	v_fma_f32 v20, v2, s72, -v20
	v_fmac_f32_e32 v20, 0x3377d1cf, v2
	v_fmac_f32_e32 v20, 0x3f317217, v2
	v_cmp_lt_f32_e64 s[0:1], |v2|, s73
	s_nop 1
	v_cndmask_b32_e64 v2, v2, v20, s[0:1]
	v_cndmask_b32_e32 v20, 0, v227, vcc
	v_sub_f32_e32 v2, v2, v20
	v_sub_f32_e32 v2, v3, v2
	v_fmamk_f32 v37, v2, 0x3d800000, v39
	v_sub_u32_e32 v2, 63, v116
	v_cndmask_b32_e64 v38, v2, v116, s[38:39]
	v_lshl_add_u32 v2, v38, 7, s37
	ds_read_b128 v[26:29], v2
	ds_read_b128 v[156:159], v2 offset:16
	ds_read_b128 v[220:223], v2 offset:32
	ds_read_b128 v[216:219], v2 offset:48
	s_waitcnt lgkmcnt(3)
	v_mul_f32_e32 v2, v24, v27
	v_fmac_f32_e32 v2, v23, v26
	s_waitcnt lgkmcnt(2)
	v_mul_f32_e32 v3, v19, v157
	v_fmac_f32_e32 v2, v25, v28
	v_fmac_f32_e32 v3, v0, v156
	v_fmac_f32_e32 v2, v87, v29
	v_fmac_f32_e32 v3, v22, v158
	v_add_f32_e32 v2, v249, v2
	v_fmac_f32_e32 v3, v245, v159
	v_add_f32_e32 v2, v2, v3
	s_waitcnt lgkmcnt(1)
	v_mul_f32_e32 v3, v246, v221
	v_fmac_f32_e32 v3, v85, v220
	v_fmac_f32_e32 v3, v247, v222
	v_fmac_f32_e32 v3, v248, v223
	v_add_f32_e32 v2, v2, v3
	s_waitcnt lgkmcnt(0)
	v_mul_f32_e32 v3, v5, v217
	v_fmac_f32_e32 v3, v1, v216
	v_fmac_f32_e32 v3, v17, v218
	v_fmac_f32_e32 v3, v4, v219
	v_add_f32_e32 v2, v2, v3
	v_min_f32_e32 v3, 0, v2
	v_mul_f32_e64 v2, |v2|, s97
	v_exp_f32_e32 v2, v2
	s_nop 0
	v_add_f32_e32 v2, 1.0, v2
	v_cmp_gt_f32_e32 vcc, s33, v2
	s_nop 1
	v_cndmask_b32_e64 v20, 0, 32, vcc
	v_ldexp_f32 v2, v2, v20
	v_log_f32_e32 v2, v2
	s_nop 0
	v_mul_f32_e32 v20, 0x3f317217, v2
	v_fma_f32 v20, v2, s72, -v20
	v_fmac_f32_e32 v20, 0x3377d1cf, v2
	v_fmac_f32_e32 v20, 0x3f317217, v2
	v_cmp_lt_f32_e64 s[0:1], |v2|, s73
	s_nop 1
	v_cndmask_b32_e64 v2, v2, v20, s[0:1]
	v_cndmask_b32_e32 v20, 0, v227, vcc
	v_sub_f32_e32 v2, v2, v20
	v_sub_f32_e32 v2, v3, v2
	v_fmamk_f32 v35, v2, 0x3d800000, v37
	v_sub_u32_e32 v2, 63, v117
	v_cndmask_b32_e64 v36, v2, v117, s[38:39]
	v_lshl_add_u32 v2, v36, 7, s37
	ds_read_b128 v[26:29], v2
	s_waitcnt lgkmcnt(0)
	v_mul_f32_e32 v3, v24, v27
	v_fmac_f32_e32 v3, v23, v26
	v_fmac_f32_e32 v3, v25, v28
	v_fmac_f32_e32 v3, v87, v29
	ds_read_b128 v[26:29], v2 offset:16
	v_add_f32_e32 v3, v249, v3
	s_waitcnt lgkmcnt(0)
	v_mul_f32_e32 v20, v19, v27
	v_fmac_f32_e32 v20, v0, v26
	v_fmac_f32_e32 v20, v22, v28
	v_fmac_f32_e32 v20, v245, v29
	ds_read_b128 v[26:29], v2 offset:32
	v_add_f32_e32 v3, v3, v20
	s_waitcnt lgkmcnt(0)
	v_mul_f32_e32 v20, v246, v27
	v_fmac_f32_e32 v20, v85, v26
	v_fmac_f32_e32 v20, v247, v28
	v_fmac_f32_e32 v20, v248, v29
	ds_read_b128 v[26:29], v2 offset:48
	v_add_f32_e32 v3, v3, v20
	s_waitcnt lgkmcnt(0)
	v_mul_f32_e32 v2, v5, v27
	v_fmac_f32_e32 v2, v1, v26
	v_fmac_f32_e32 v2, v17, v28
	v_fmac_f32_e32 v2, v4, v29
	v_add_f32_e32 v2, v3, v2
	v_min_f32_e32 v3, 0, v2
	v_mul_f32_e64 v2, |v2|, s97
	v_exp_f32_e32 v2, v2
	s_nop 0
	v_add_f32_e32 v2, 1.0, v2
	v_cmp_gt_f32_e32 vcc, s33, v2
	s_nop 1
	v_cndmask_b32_e64 v20, 0, 32, vcc
	v_ldexp_f32 v2, v2, v20
	v_log_f32_e32 v2, v2
	s_nop 0
	v_mul_f32_e32 v20, 0x3f317217, v2
	v_fma_f32 v20, v2, s72, -v20
	v_fmac_f32_e32 v20, 0x3377d1cf, v2
	v_fmac_f32_e32 v20, 0x3f317217, v2
	v_cmp_lt_f32_e64 s[0:1], |v2|, s73
	s_nop 1
	v_cndmask_b32_e64 v2, v2, v20, s[0:1]
	v_cndmask_b32_e32 v20, 0, v227, vcc
	v_sub_f32_e32 v2, v2, v20
	v_sub_f32_e32 v2, v3, v2
	v_fmamk_f32 v32, v2, 0x3d800000, v35
	v_sub_u32_e32 v2, 63, v118
	v_cndmask_b32_e64 v34, v2, v118, s[38:39]
	v_lshl_add_u32 v2, v34, 7, s37
	ds_read_b128 v[26:29], v2
	s_waitcnt lgkmcnt(0)
	v_mul_f32_e32 v3, v24, v27
	v_fmac_f32_e32 v3, v23, v26
	v_fmac_f32_e32 v3, v25, v28
	v_fmac_f32_e32 v3, v87, v29
	ds_read_b128 v[26:29], v2 offset:16
	v_add_f32_e32 v3, v249, v3
	s_waitcnt lgkmcnt(0)
	v_mul_f32_e32 v20, v19, v27
	v_fmac_f32_e32 v20, v0, v26
	v_fmac_f32_e32 v20, v22, v28
	v_fmac_f32_e32 v20, v245, v29
	ds_read_b128 v[26:29], v2 offset:32
	v_add_f32_e32 v3, v3, v20
	s_waitcnt lgkmcnt(0)
	v_mul_f32_e32 v20, v246, v27
	v_fmac_f32_e32 v20, v85, v26
	v_fmac_f32_e32 v20, v247, v28
	v_fmac_f32_e32 v20, v248, v29
	ds_read_b128 v[26:29], v2 offset:48
	v_add_f32_e32 v3, v3, v20
	s_waitcnt lgkmcnt(0)
	v_mul_f32_e32 v2, v5, v27
	v_fmac_f32_e32 v2, v1, v26
	v_fmac_f32_e32 v2, v17, v28
	v_fmac_f32_e32 v2, v4, v29
	v_add_f32_e32 v2, v3, v2
	v_min_f32_e32 v3, 0, v2
	v_mul_f32_e64 v2, |v2|, s97
	v_exp_f32_e32 v2, v2
	s_nop 0
	v_add_f32_e32 v2, 1.0, v2
	v_cmp_gt_f32_e32 vcc, s33, v2
	s_nop 1
	v_cndmask_b32_e64 v20, 0, 32, vcc
	v_ldexp_f32 v2, v2, v20
	v_log_f32_e32 v2, v2
	s_nop 0
	v_mul_f32_e32 v20, 0x3f317217, v2
	v_fma_f32 v20, v2, s72, -v20
	v_fmac_f32_e32 v20, 0x3377d1cf, v2
	v_fmac_f32_e32 v20, 0x3f317217, v2
	v_cmp_lt_f32_e64 s[0:1], |v2|, s73
	s_nop 1
	v_cndmask_b32_e64 v2, v2, v20, s[0:1]
	v_cndmask_b32_e32 v20, 0, v227, vcc
	v_sub_f32_e32 v2, v2, v20
	v_sub_f32_e32 v2, v3, v2
	v_fmamk_f32 v31, v2, 0x3d800000, v32
	v_lshl_add_u32 v2, v30, 7, s37
	ds_read_b128 v[26:29], v2
	s_waitcnt lgkmcnt(0)
	v_mul_f32_e32 v3, v24, v27
	v_fmac_f32_e32 v3, v23, v26
	v_fmac_f32_e32 v3, v25, v28
	v_fmac_f32_e32 v3, v87, v29
	ds_read_b128 v[26:29], v2 offset:16
	v_add_f32_e32 v3, v249, v3
	s_waitcnt lgkmcnt(0)
	v_mul_f32_e32 v20, v19, v27
	v_fmac_f32_e32 v20, v0, v26
	v_fmac_f32_e32 v20, v22, v28
	v_fmac_f32_e32 v20, v245, v29
	ds_read_b128 v[26:29], v2 offset:32
	v_add_f32_e32 v3, v3, v20
	s_waitcnt lgkmcnt(0)
	v_mul_f32_e32 v20, v246, v27
	v_fmac_f32_e32 v20, v85, v26
	v_fmac_f32_e32 v20, v247, v28
	v_fmac_f32_e32 v20, v248, v29
	ds_read_b128 v[26:29], v2 offset:48
	v_add_f32_e32 v3, v3, v20
	s_waitcnt lgkmcnt(0)
	v_mul_f32_e32 v2, v5, v27
	v_fmac_f32_e32 v2, v1, v26
	v_fmac_f32_e32 v2, v17, v28
	v_fmac_f32_e32 v2, v4, v29
	v_add_f32_e32 v2, v3, v2
	v_min_f32_e32 v3, 0, v2
	v_mul_f32_e64 v2, |v2|, s97
	v_exp_f32_e32 v2, v2
	v_cndmask_b32_e64 v28, v122, v121, s[38:39]
	v_cndmask_b32_e64 v26, v124, v123, s[38:39]
	v_add_f32_e32 v2, 1.0, v2
	v_cmp_gt_f32_e32 vcc, s33, v2
	s_nop 1
	v_cndmask_b32_e64 v20, 0, 32, vcc
	v_ldexp_f32 v2, v2, v20
	v_log_f32_e32 v2, v2
	s_nop 0
	v_mul_f32_e32 v20, 0x3f317217, v2
	v_fma_f32 v20, v2, s72, -v20
	v_fmac_f32_e32 v20, 0x3377d1cf, v2
	v_fmac_f32_e32 v20, 0x3f317217, v2
	v_cmp_lt_f32_e64 s[0:1], |v2|, s73
	s_nop 1
	v_cndmask_b32_e64 v2, v2, v20, s[0:1]
	v_cndmask_b32_e32 v20, 0, v227, vcc
	v_sub_f32_e32 v2, v2, v20
	v_sub_f32_e32 v2, v3, v2
	v_fmamk_f32 v29, v2, 0x3d800000, v31
	v_lshl_add_u32 v2, v28, 7, s37
	ds_read_b128 v[156:159], v2
	s_waitcnt lgkmcnt(0)
	v_mul_f32_e32 v3, v24, v157
	v_fmac_f32_e32 v3, v23, v156
	v_fmac_f32_e32 v3, v25, v158
	v_fmac_f32_e32 v3, v87, v159
	ds_read_b128 v[156:159], v2 offset:16
	v_add_f32_e32 v3, v249, v3
	s_waitcnt lgkmcnt(0)
	v_mul_f32_e32 v20, v19, v157
	v_fmac_f32_e32 v20, v0, v156
	v_fmac_f32_e32 v20, v22, v158
	v_fmac_f32_e32 v20, v245, v159
	ds_read_b128 v[156:159], v2 offset:32
	v_add_f32_e32 v3, v3, v20
	s_waitcnt lgkmcnt(0)
	v_mul_f32_e32 v20, v246, v157
	v_fmac_f32_e32 v20, v85, v156
	v_fmac_f32_e32 v20, v247, v158
	v_fmac_f32_e32 v20, v248, v159
	ds_read_b128 v[156:159], v2 offset:48
	v_add_f32_e32 v3, v3, v20
	s_waitcnt lgkmcnt(0)
	v_mul_f32_e32 v2, v5, v157
	v_fmac_f32_e32 v2, v1, v156
	v_fmac_f32_e32 v2, v17, v158
	v_fmac_f32_e32 v2, v4, v159
	v_add_f32_e32 v2, v3, v2
	v_min_f32_e32 v3, 0, v2
	v_mul_f32_e64 v2, |v2|, s97
	v_exp_f32_e32 v2, v2
	s_nop 0
	v_add_f32_e32 v2, 1.0, v2
	v_cmp_gt_f32_e32 vcc, s33, v2
	s_nop 1
	v_cndmask_b32_e64 v20, 0, 32, vcc
	v_ldexp_f32 v2, v2, v20
	v_log_f32_e32 v2, v2
	s_nop 0
	v_mul_f32_e32 v20, 0x3f317217, v2
	v_fma_f32 v20, v2, s72, -v20
	v_fmac_f32_e32 v20, 0x3377d1cf, v2
	v_fmac_f32_e32 v20, 0x3f317217, v2
	v_cmp_lt_f32_e64 s[0:1], |v2|, s73
	s_nop 1
	v_cndmask_b32_e64 v2, v2, v20, s[0:1]
	v_cndmask_b32_e32 v20, 0, v227, vcc
	v_sub_f32_e32 v2, v2, v20
	v_sub_f32_e32 v2, v3, v2
	v_fmamk_f32 v27, v2, 0x3d800000, v29
	v_lshl_add_u32 v2, v26, 7, s37
	ds_read_b128 v[156:159], v2
	s_waitcnt lgkmcnt(0)
	v_mul_f32_e32 v3, v24, v157
	v_fmac_f32_e32 v3, v23, v156
	v_fmac_f32_e32 v3, v25, v158
	v_fmac_f32_e32 v3, v87, v159
	ds_read_b128 v[156:159], v2 offset:16
	v_add_f32_e32 v3, v249, v3
	s_waitcnt lgkmcnt(0)
	v_mul_f32_e32 v20, v19, v157
	v_fmac_f32_e32 v20, v0, v156
	v_fmac_f32_e32 v20, v22, v158
	v_fmac_f32_e32 v20, v245, v159
	ds_read_b128 v[156:159], v2 offset:32
	v_add_f32_e32 v3, v3, v20
	s_waitcnt lgkmcnt(0)
	v_mul_f32_e32 v20, v246, v157
	v_fmac_f32_e32 v20, v85, v156
	v_fmac_f32_e32 v20, v247, v158
	v_fmac_f32_e32 v20, v248, v159
	ds_read_b128 v[156:159], v2 offset:48
	v_add_f32_e32 v3, v3, v20
	s_waitcnt lgkmcnt(0)
	v_mul_f32_e32 v2, v5, v157
	v_fmac_f32_e32 v2, v1, v156
	v_fmac_f32_e32 v2, v17, v158
	v_fmac_f32_e32 v2, v4, v159
	v_add_f32_e32 v2, v3, v2
	v_min_f32_e32 v3, 0, v2
	v_mul_f32_e64 v2, |v2|, s97
	v_exp_f32_e32 v2, v2
	s_nop 0
	v_add_f32_e32 v2, 1.0, v2
	v_cmp_gt_f32_e32 vcc, s33, v2
	s_nop 1
	v_cndmask_b32_e64 v20, 0, 32, vcc
	v_ldexp_f32 v2, v2, v20
	v_log_f32_e32 v2, v2
	s_nop 0
	v_mul_f32_e32 v20, 0x3f317217, v2
	v_fma_f32 v20, v2, s72, -v20
	v_fmac_f32_e32 v20, 0x3377d1cf, v2
	v_fmac_f32_e32 v20, 0x3f317217, v2
	v_cmp_lt_f32_e64 s[0:1], |v2|, s73
	s_nop 1
	v_cndmask_b32_e64 v2, v2, v20, s[0:1]
	v_cndmask_b32_e32 v20, 0, v227, vcc
	v_sub_f32_e32 v2, v2, v20
	v_sub_f32_e32 v2, v3, v2
	v_cndmask_b32_e64 v20, v126, v125, s[38:39]
	v_fmamk_f32 v21, v2, 0x3d800000, v27
	v_lshl_add_u32 v2, v20, 7, s37
	ds_read_b128 v[156:159], v2
	s_waitcnt lgkmcnt(0)
	v_mul_f32_e32 v3, v24, v157
	v_fmac_f32_e32 v3, v23, v156
	v_fmac_f32_e32 v3, v25, v158
	v_fmac_f32_e32 v3, v87, v159
	ds_read_b128 v[156:159], v2 offset:16
	v_add_f32_e32 v3, v249, v3
	s_waitcnt lgkmcnt(0)
	v_mul_f32_e32 v157, v19, v157
	v_fmac_f32_e32 v157, v0, v156
	v_fmac_f32_e32 v157, v22, v158
	v_fmac_f32_e32 v157, v245, v159
	v_add_f32_e32 v3, v3, v157
	ds_read_b128 v[156:159], v2 offset:32
	s_waitcnt lgkmcnt(0)
	v_mul_f32_e32 v157, v246, v157
	v_fmac_f32_e32 v157, v85, v156
	v_fmac_f32_e32 v157, v247, v158
	v_fmac_f32_e32 v157, v248, v159
	v_add_f32_e32 v3, v3, v157
	ds_read_b128 v[156:159], v2 offset:48
	s_waitcnt lgkmcnt(0)
	v_mul_f32_e32 v2, v5, v157
	v_fmac_f32_e32 v2, v1, v156
	v_fmac_f32_e32 v2, v17, v158
	v_fmac_f32_e32 v2, v4, v159
	v_add_f32_e32 v2, v3, v2
	v_min_f32_e32 v3, 0, v2
	v_mul_f32_e64 v2, |v2|, s97
	v_exp_f32_e32 v2, v2
	s_nop 0
	v_add_f32_e32 v2, 1.0, v2
	v_cmp_gt_f32_e32 vcc, s33, v2
	s_nop 1
	v_cndmask_b32_e64 v156, 0, 32, vcc
	v_ldexp_f32 v2, v2, v156
	v_log_f32_e32 v2, v2
	s_nop 0
	v_mul_f32_e32 v156, 0x3f317217, v2
	v_fma_f32 v156, v2, s72, -v156
	v_fmac_f32_e32 v156, 0x3377d1cf, v2
	v_fmac_f32_e32 v156, 0x3f317217, v2
	v_cmp_lt_f32_e64 s[0:1], |v2|, s73
	s_nop 1
	v_cndmask_b32_e64 v2, v2, v156, s[0:1]
	v_cndmask_b32_e32 v156, 0, v227, vcc
	v_sub_f32_e32 v2, v2, v156
	v_sub_f32_e32 v2, v3, v2
	v_fmamk_f32 v3, v2, 0x3d800000, v21
	v_cndmask_b32_e64 v2, v128, v127, s[38:39]
	v_lshl_add_u32 v216, v2, 7, s37
	ds_read_b128 v[156:159], v216
	s_waitcnt lgkmcnt(0)
	v_mul_f32_e32 v24, v24, v157
	v_fmac_f32_e32 v24, v23, v156
	v_fmac_f32_e32 v24, v25, v158
	v_fmac_f32_e32 v24, v87, v159
	ds_read_b128 v[156:159], v216 offset:16
	v_add_f32_e32 v23, v249, v24
	s_waitcnt lgkmcnt(0)
	v_mul_f32_e32 v19, v19, v157
	v_fmac_f32_e32 v19, v0, v156
	v_fmac_f32_e32 v19, v22, v158
	v_fmac_f32_e32 v19, v245, v159
	v_add_f32_e32 v0, v23, v19
	ds_read_b128 v[22:25], v216 offset:32
	s_waitcnt lgkmcnt(0)
	v_mul_f32_e32 v19, v246, v23
	v_fmac_f32_e32 v19, v85, v22
	v_fmac_f32_e32 v19, v247, v24
	v_fmac_f32_e32 v19, v248, v25
	ds_read_b128 v[22:25], v216 offset:48
	v_add_f32_e32 v0, v0, v19
	s_waitcnt lgkmcnt(0)
	v_mul_f32_e32 v5, v5, v23
	v_fmac_f32_e32 v5, v1, v22
	v_fmac_f32_e32 v5, v17, v24
	v_fmac_f32_e32 v5, v4, v25
	v_add_f32_e32 v0, v0, v5
	v_min_f32_e32 v1, 0, v0
	v_mul_f32_e64 v0, |v0|, s97
	v_exp_f32_e32 v0, v0
	s_nop 0
	v_add_f32_e32 v0, 1.0, v0
	v_cmp_gt_f32_e32 vcc, s33, v0
	s_nop 1
	v_cndmask_b32_e64 v4, 0, 32, vcc
	v_ldexp_f32 v0, v0, v4
	v_log_f32_e32 v0, v0
	s_nop 0
	v_mul_f32_e32 v4, 0x3f317217, v0
	v_fma_f32 v4, v0, s72, -v4
	v_fmac_f32_e32 v4, 0x3377d1cf, v0
	v_fmac_f32_e32 v4, 0x3f317217, v0
	v_cmp_lt_f32_e64 s[0:1], |v0|, s73
	s_nop 1
	v_cndmask_b32_e64 v0, v0, v4, s[0:1]
	v_cndmask_b32_e32 v4, 0, v227, vcc
	v_sub_f32_e32 v0, v0, v4
	v_sub_f32_e32 v0, v1, v0
	v_fmamk_f32 v19, v0, 0x3d800000, v3
	ds_write_b32 v91, v19
	s_waitcnt lgkmcnt(0)
	s_barrier
	ds_read2st64_b32 v[4:5], v92 offset1:4
	s_waitcnt lgkmcnt(0)
	v_add_f32_e32 v1, v4, v5
	s_and_saveexec_b64 s[0:1], s[2:3]
	s_cbranch_execz .LBB0_307
	v_mul_f32_e32 v0, 0x3fb8aa3b, v1
	v_exp_f32_e32 v0, v0
	v_lshl_add_u64 v[22:23], s[66:67], 2, v[6:7]
	global_store_dword v[22:23], v0, off
.LBB0_307:
	s_or_b64 exec, exec, s[0:1]
	s_and_b64 s[0:1], s[38:39], exec
	s_movk_i32 s0, 0x800
	s_mov_b32 s1, 0xc400800
	s_cselect_b32 s37, s30, s26
	s_cselect_b32 s0, 0x1900, s0
	s_cselect_b32 s66, s1, 0x6400800
	s_cselect_b32 s1, s31, s27
	s_add_u32 s60, s37, s58
	v_ashrrev_i32_e32 v87, 31, v86
	s_addc_u32 s61, s1, 0
	v_mov_b32_e32 v17, v33
	v_lshl_add_u64 v[86:87], v[86:87], 0, s[34:35]
	v_lshl_add_u64 v[24:25], s[60:61], 0, v[16:17]
	v_mad_u64_u32 v[156:157], s[60:61], v86, s93, v[12:13]
	v_mad_i32_i24 v157, v87, s93, v157
	global_load_ushort v216, v[156:157], off
	global_load_ushort v217, v[156:157], off offset:2048
	v_add_u32_e32 v245, s34, v84
	v_mad_u64_u32 v[158:159], s[60:61], v245, s93, v[12:13]
	global_load_ushort v218, v[158:159], off
	global_load_ushort v219, v[158:159], off offset:2048
	v_add_u32_e32 v245, s34, v82
	v_mad_u64_u32 v[158:159], s[60:61], v245, s93, v[12:13]
	global_load_ushort v220, v[158:159], off
	global_load_ushort v221, v[158:159], off offset:2048
	v_add_u32_e32 v245, s34, v80
	v_mad_u64_u32 v[158:159], s[60:61], v245, s93, v[12:13]
	global_load_ushort v222, v[158:159], off
	global_load_ushort v223, v[158:159], off offset:2048
	v_add_u32_e32 v245, s34, v78
	v_mad_u64_u32 v[158:159], s[60:61], v245, s93, v[12:13]
	global_load_ushort v246, v[158:159], off
	global_load_ushort v247, v[158:159], off offset:2048
	v_add_u32_e32 v245, s34, v76
	v_mad_u64_u32 v[158:159], s[60:61], v245, s93, v[12:13]
	global_load_ushort v248, v[158:159], off
	global_load_ushort v249, v[158:159], off offset:2048
	v_cndmask_b32_e64 v5, v4, 0, s[2:3]
	v_add_f32_e32 v83, v83, v5
	v_sub_f32_e32 v156, v83, v4
	v_mul_f32_e32 v156, 0x3fb8aa3b, v156
	v_exp_f32_e32 v156, v156
	v_lshl_add_u64 v[22:23], v[10:11], 0, s[66:67]
	v_add_f32_e32 v81, v81, v5
	v_add_f32_e32 v79, v79, v5
	v_add_f32_e32 v77, v77, v5
	v_add_f32_e32 v75, v75, v5
	v_add_f32_e32 v73, v73, v5
	v_add_f32_e32 v71, v71, v5
	v_add_f32_e32 v69, v69, v5
	v_add_f32_e32 v67, v67, v5
	v_add_f32_e32 v65, v65, v5
	v_add_f32_e32 v63, v63, v5
	v_add_f32_e32 v61, v61, v5
	v_add_f32_e32 v59, v59, v5
	v_add_f32_e32 v57, v57, v5
	v_add_f32_e32 v55, v55, v5
	v_add_f32_e32 v53, v53, v5
	v_add_f32_e32 v51, v51, v5
	v_add_f32_e32 v49, v49, v5
	v_add_f32_e32 v47, v47, v5
	v_add_f32_e32 v45, v45, v5
	v_add_f32_e32 v43, v43, v5
	v_add_f32_e32 v41, v41, v5
	v_add_f32_e32 v39, v39, v5
	v_add_f32_e32 v37, v37, v5
	v_add_f32_e32 v35, v35, v5
	v_add_f32_e32 v32, v32, v5
	v_add_f32_e32 v31, v31, v5
	v_add_f32_e32 v29, v29, v5
	v_add_f32_e32 v27, v27, v5
	v_add_f32_e32 v21, v21, v5
	v_add_f32_e32 v3, v3, v5
	v_add_f32_e32 v19, v5, v19
	v_sub_f32_e32 v5, v19, v4
	v_mul_f32_e32 v5, 0x3fb8aa3b, v5
	v_exp_f32_e32 v5, v5
	v_mov_b32_e32 v0, 0
	s_waitcnt vmcnt(10)
	v_lshlrev_b32_e32 v17, 16, v216
	v_mul_f32_e32 v17, 0x3d800000, v17
	v_mul_f32_e32 v156, v156, v17
	v_cvt_pk_bf16_f32 v156, v156, v33
	ds_write_b16 v129, v156
	v_sub_f32_e32 v156, v4, v83
	v_mul_f32_e32 v156, 0x3fb8aa3b, v156
	v_exp_f32_e32 v156, v156
	v_lshlrev_b32_e32 v85, 16, v217
	v_add_u32_e32 v245, s34, v74
	v_mad_u64_u32 v[158:159], s[60:61], v245, s93, v[12:13]
	global_load_ushort v216, v[158:159], off
	global_load_ushort v217, v[158:159], off offset:2048
	v_mul_f32_e32 v156, v156, v85
	v_cvt_pk_bf16_f32 v156, v156, v33
	ds_write_b16 v129, v156 offset:33792
	v_mul_f32_e32 v156, 0x3fb8aa3b, v83
	v_exp_f32_e32 v156, v156
	s_nop 0
	v_mul_f32_e32 v17, v156, v17
	v_mad_u64_u32 v[156:157], s[60:61], v86, s0, 0
	v_mad_i32_i24 v157, v87, s0, v157
	v_lshlrev_b64 v[86:87], 1, v[156:157]
	v_cvt_pk_bf16_f32 v17, v17, v33
	v_lshl_add_u64 v[156:157], v[24:25], 0, v[86:87]
	global_store_short v[156:157], v17, off
	v_sub_f32_e32 v17, v1, v83
	v_mul_f32_e32 v17, 0x3fb8aa3b, v17
	v_exp_f32_e32 v17, v17
	v_lshl_add_u64 v[86:87], v[22:23], 0, v[86:87]
	v_mul_f32_e32 v17, v17, v85
	v_ashrrev_i32_e32 v85, 31, v84
	v_lshl_add_u64 v[84:85], v[84:85], 0, s[34:35]
	v_cvt_pk_bf16_f32 v17, v17, v33
	global_store_short v[86:87], v17, off
	v_sub_f32_e32 v86, v81, v4
	v_mul_f32_e32 v86, 0x3fb8aa3b, v86
	v_exp_f32_e32 v86, v86
	s_waitcnt vmcnt(12)
	v_lshlrev_b32_e32 v17, 16, v218
	v_mul_f32_e32 v17, 0x3d800000, v17
	v_mul_f32_e32 v86, v86, v17
	v_cvt_pk_bf16_f32 v86, v86, v33
	ds_write_b16 v130, v86
	v_sub_f32_e32 v86, v4, v81
	v_mul_f32_e32 v86, 0x3fb8aa3b, v86
	v_exp_f32_e32 v86, v86
	v_lshlrev_b32_e32 v83, 16, v219
	v_add_u32_e32 v245, s34, v72
	v_mad_u64_u32 v[158:159], s[60:61], v245, s93, v[12:13]
	global_load_ushort v218, v[158:159], off
	global_load_ushort v219, v[158:159], off offset:2048
	v_mul_f32_e32 v86, v86, v83
	v_cvt_pk_bf16_f32 v86, v86, v33
	ds_write_b16 v130, v86 offset:33792
	v_mul_f32_e32 v86, 0x3fb8aa3b, v81
	v_exp_f32_e32 v86, v86
	s_nop 0
	v_mul_f32_e32 v17, v86, v17
	v_mad_u64_u32 v[86:87], s[60:61], v84, s0, 0
	v_mad_i32_i24 v87, v85, s0, v87
	v_lshlrev_b64 v[84:85], 1, v[86:87]
	v_cvt_pk_bf16_f32 v17, v17, v33
	v_lshl_add_u64 v[86:87], v[24:25], 0, v[84:85]
	global_store_short v[86:87], v17, off
	v_sub_f32_e32 v17, v1, v81
	v_mul_f32_e32 v17, 0x3fb8aa3b, v17
	v_exp_f32_e32 v17, v17
	v_lshl_add_u64 v[84:85], v[22:23], 0, v[84:85]
	v_mul_f32_e32 v17, v17, v83
	v_ashrrev_i32_e32 v83, 31, v82
	v_lshl_add_u64 v[82:83], v[82:83], 0, s[34:35]
	v_cvt_pk_bf16_f32 v17, v17, v33
	global_store_short v[84:85], v17, off
	v_sub_f32_e32 v84, v79, v4
	v_mul_f32_e32 v84, 0x3fb8aa3b, v84
	v_exp_f32_e32 v84, v84
	s_waitcnt vmcnt(14)
	v_lshlrev_b32_e32 v17, 16, v220
	v_mul_f32_e32 v17, 0x3d800000, v17
	v_mul_f32_e32 v84, v84, v17
	v_cvt_pk_bf16_f32 v84, v84, v33
	ds_write_b16 v131, v84
	v_sub_f32_e32 v84, v4, v79
	v_mul_f32_e32 v84, 0x3fb8aa3b, v84
	v_exp_f32_e32 v84, v84
	v_lshlrev_b32_e32 v81, 16, v221
	v_add_u32_e32 v245, s34, v70
	v_mad_u64_u32 v[158:159], s[60:61], v245, s93, v[12:13]
	global_load_ushort v220, v[158:159], off
	global_load_ushort v221, v[158:159], off offset:2048
	v_mul_f32_e32 v84, v84, v81
	v_cvt_pk_bf16_f32 v84, v84, v33
	ds_write_b16 v131, v84 offset:33792
	v_mul_f32_e32 v84, 0x3fb8aa3b, v79
	v_exp_f32_e32 v84, v84
	s_nop 0
	v_mul_f32_e32 v17, v84, v17
	v_mad_u64_u32 v[84:85], s[60:61], v82, s0, 0
	v_mad_i32_i24 v85, v83, s0, v85
	v_lshlrev_b64 v[82:83], 1, v[84:85]
	v_cvt_pk_bf16_f32 v17, v17, v33
	v_lshl_add_u64 v[84:85], v[24:25], 0, v[82:83]
	global_store_short v[84:85], v17, off
	v_sub_f32_e32 v17, v1, v79
	v_mul_f32_e32 v17, 0x3fb8aa3b, v17
	v_exp_f32_e32 v17, v17
	v_lshl_add_u64 v[82:83], v[22:23], 0, v[82:83]
	v_mul_f32_e32 v17, v17, v81
	v_ashrrev_i32_e32 v81, 31, v80
	v_lshl_add_u64 v[80:81], v[80:81], 0, s[34:35]
	v_cvt_pk_bf16_f32 v17, v17, v33
	global_store_short v[82:83], v17, off
	v_sub_f32_e32 v82, v77, v4
	v_mul_f32_e32 v82, 0x3fb8aa3b, v82
	v_exp_f32_e32 v82, v82
	s_waitcnt vmcnt(16)
	v_lshlrev_b32_e32 v17, 16, v222
	v_mul_f32_e32 v17, 0x3d800000, v17
	v_mul_f32_e32 v82, v82, v17
	v_cvt_pk_bf16_f32 v82, v82, v33
	ds_write_b16 v132, v82
	v_sub_f32_e32 v82, v4, v77
	v_mul_f32_e32 v82, 0x3fb8aa3b, v82
	v_exp_f32_e32 v82, v82
	v_lshlrev_b32_e32 v79, 16, v223
	v_add_u32_e32 v245, s34, v68
	v_mad_u64_u32 v[158:159], s[60:61], v245, s93, v[12:13]
	global_load_ushort v222, v[158:159], off
	global_load_ushort v223, v[158:159], off offset:2048
	v_mul_f32_e32 v82, v82, v79
	v_cvt_pk_bf16_f32 v82, v82, v33
	ds_write_b16 v132, v82 offset:33792
	v_mul_f32_e32 v82, 0x3fb8aa3b, v77
	v_exp_f32_e32 v82, v82
	s_nop 0
	v_mul_f32_e32 v17, v82, v17
	v_mad_u64_u32 v[82:83], s[60:61], v80, s0, 0
	v_mad_i32_i24 v83, v81, s0, v83
	v_lshlrev_b64 v[80:81], 1, v[82:83]
	v_cvt_pk_bf16_f32 v17, v17, v33
	v_lshl_add_u64 v[82:83], v[24:25], 0, v[80:81]
	global_store_short v[82:83], v17, off
	v_sub_f32_e32 v17, v1, v77
	v_mul_f32_e32 v17, 0x3fb8aa3b, v17
	v_exp_f32_e32 v17, v17
	v_lshl_add_u64 v[80:81], v[22:23], 0, v[80:81]
	v_mul_f32_e32 v17, v17, v79
	v_ashrrev_i32_e32 v79, 31, v78
	v_lshl_add_u64 v[78:79], v[78:79], 0, s[34:35]
	v_cvt_pk_bf16_f32 v17, v17, v33
	global_store_short v[80:81], v17, off
	v_sub_f32_e32 v80, v75, v4
	v_mul_f32_e32 v80, 0x3fb8aa3b, v80
	v_exp_f32_e32 v80, v80
	s_waitcnt vmcnt(18)
	v_lshlrev_b32_e32 v17, 16, v246
	v_mul_f32_e32 v17, 0x3d800000, v17
	v_mul_f32_e32 v80, v80, v17
	v_cvt_pk_bf16_f32 v80, v80, v33
	ds_write_b16 v133, v80
	v_sub_f32_e32 v80, v4, v75
	v_mul_f32_e32 v80, 0x3fb8aa3b, v80
	v_exp_f32_e32 v80, v80
	v_lshlrev_b32_e32 v77, 16, v247
	v_add_u32_e32 v245, s34, v66
	v_mad_u64_u32 v[158:159], s[60:61], v245, s93, v[12:13]
	global_load_ushort v246, v[158:159], off
	global_load_ushort v247, v[158:159], off offset:2048
	v_mul_f32_e32 v80, v80, v77
	v_cvt_pk_bf16_f32 v80, v80, v33
	ds_write_b16 v133, v80 offset:33792
	v_mul_f32_e32 v80, 0x3fb8aa3b, v75
	v_exp_f32_e32 v80, v80
	s_nop 0
	v_mul_f32_e32 v17, v80, v17
	v_mad_u64_u32 v[80:81], s[60:61], v78, s0, 0
	v_mad_i32_i24 v81, v79, s0, v81
	v_lshlrev_b64 v[78:79], 1, v[80:81]
	v_cvt_pk_bf16_f32 v17, v17, v33
	v_lshl_add_u64 v[80:81], v[24:25], 0, v[78:79]
	global_store_short v[80:81], v17, off
	v_sub_f32_e32 v17, v1, v75
	v_mul_f32_e32 v17, 0x3fb8aa3b, v17
	v_exp_f32_e32 v17, v17
	v_lshl_add_u64 v[78:79], v[22:23], 0, v[78:79]
	v_mul_f32_e32 v17, v17, v77
	v_ashrrev_i32_e32 v77, 31, v76
	v_lshl_add_u64 v[76:77], v[76:77], 0, s[34:35]
	v_cvt_pk_bf16_f32 v17, v17, v33
	global_store_short v[78:79], v17, off
	v_sub_f32_e32 v78, v73, v4
	v_mul_f32_e32 v78, 0x3fb8aa3b, v78
	v_exp_f32_e32 v78, v78
	s_waitcnt vmcnt(20)
	v_lshlrev_b32_e32 v17, 16, v248
	v_mul_f32_e32 v17, 0x3d800000, v17
	v_mul_f32_e32 v78, v78, v17
	v_cvt_pk_bf16_f32 v78, v78, v33
	ds_write_b16 v134, v78
	v_sub_f32_e32 v78, v4, v73
	v_mul_f32_e32 v78, 0x3fb8aa3b, v78
	v_exp_f32_e32 v78, v78
	v_lshlrev_b32_e32 v75, 16, v249
	v_add_u32_e32 v245, s34, v64
	v_mad_u64_u32 v[158:159], s[60:61], v245, s93, v[12:13]
	global_load_ushort v248, v[158:159], off
	global_load_ushort v249, v[158:159], off offset:2048
	v_mul_f32_e32 v78, v78, v75
	v_cvt_pk_bf16_f32 v78, v78, v33
	ds_write_b16 v134, v78 offset:33792
	v_mul_f32_e32 v78, 0x3fb8aa3b, v73
	v_exp_f32_e32 v78, v78
	s_nop 0
	v_mul_f32_e32 v17, v78, v17
	v_mad_u64_u32 v[78:79], s[60:61], v76, s0, 0
	v_mad_i32_i24 v79, v77, s0, v79
	v_lshlrev_b64 v[76:77], 1, v[78:79]
	v_cvt_pk_bf16_f32 v17, v17, v33
	v_lshl_add_u64 v[78:79], v[24:25], 0, v[76:77]
	global_store_short v[78:79], v17, off
	v_sub_f32_e32 v17, v1, v73
	v_mul_f32_e32 v17, 0x3fb8aa3b, v17
	v_exp_f32_e32 v17, v17
	v_lshl_add_u64 v[76:77], v[22:23], 0, v[76:77]
	v_mul_f32_e32 v17, v17, v75
	v_ashrrev_i32_e32 v75, 31, v74
	v_lshl_add_u64 v[74:75], v[74:75], 0, s[34:35]
	v_cvt_pk_bf16_f32 v17, v17, v33
	global_store_short v[76:77], v17, off
	v_sub_f32_e32 v76, v71, v4
	v_mul_f32_e32 v76, 0x3fb8aa3b, v76
	v_exp_f32_e32 v76, v76
	s_waitcnt vmcnt(22)
	v_lshlrev_b32_e32 v17, 16, v216
	v_mul_f32_e32 v17, 0x3d800000, v17
	v_mul_f32_e32 v76, v76, v17
	v_cvt_pk_bf16_f32 v76, v76, v33
	ds_write_b16 v135, v76
	v_sub_f32_e32 v76, v4, v71
	v_mul_f32_e32 v76, 0x3fb8aa3b, v76
	v_exp_f32_e32 v76, v76
	v_lshlrev_b32_e32 v73, 16, v217
	v_add_u32_e32 v245, s34, v62
	v_mad_u64_u32 v[158:159], s[60:61], v245, s93, v[12:13]
	global_load_ushort v216, v[158:159], off
	global_load_ushort v217, v[158:159], off offset:2048
	v_mul_f32_e32 v76, v76, v73
	v_cvt_pk_bf16_f32 v76, v76, v33
	ds_write_b16 v135, v76 offset:33792
	v_mul_f32_e32 v76, 0x3fb8aa3b, v71
	v_exp_f32_e32 v76, v76
	s_nop 0
	v_mul_f32_e32 v17, v76, v17
	v_mad_u64_u32 v[76:77], s[60:61], v74, s0, 0
	v_mad_i32_i24 v77, v75, s0, v77
	v_lshlrev_b64 v[74:75], 1, v[76:77]
	v_cvt_pk_bf16_f32 v17, v17, v33
	v_lshl_add_u64 v[76:77], v[24:25], 0, v[74:75]
	global_store_short v[76:77], v17, off
	v_sub_f32_e32 v17, v1, v71
	v_mul_f32_e32 v17, 0x3fb8aa3b, v17
	v_exp_f32_e32 v17, v17
	v_lshl_add_u64 v[74:75], v[22:23], 0, v[74:75]
	v_mul_f32_e32 v17, v17, v73
	v_ashrrev_i32_e32 v73, 31, v72
	v_lshl_add_u64 v[72:73], v[72:73], 0, s[34:35]
	v_cvt_pk_bf16_f32 v17, v17, v33
	global_store_short v[74:75], v17, off
	v_sub_f32_e32 v74, v69, v4
	v_mul_f32_e32 v74, 0x3fb8aa3b, v74
	v_exp_f32_e32 v74, v74
	s_waitcnt vmcnt(22)
	v_lshlrev_b32_e32 v17, 16, v218
	v_mul_f32_e32 v17, 0x3d800000, v17
	v_mul_f32_e32 v74, v74, v17
	v_cvt_pk_bf16_f32 v74, v74, v33
	ds_write_b16 v136, v74
	v_sub_f32_e32 v74, v4, v69
	v_mul_f32_e32 v74, 0x3fb8aa3b, v74
	v_exp_f32_e32 v74, v74
	v_lshlrev_b32_e32 v71, 16, v219
	v_add_u32_e32 v245, s34, v60
	v_mad_u64_u32 v[158:159], s[60:61], v245, s93, v[12:13]
	global_load_ushort v218, v[158:159], off
	global_load_ushort v219, v[158:159], off offset:2048
	v_mul_f32_e32 v74, v74, v71
	v_cvt_pk_bf16_f32 v74, v74, v33
	ds_write_b16 v136, v74 offset:33792
	v_mul_f32_e32 v74, 0x3fb8aa3b, v69
	v_exp_f32_e32 v74, v74
	s_nop 0
	v_mul_f32_e32 v17, v74, v17
	v_mad_u64_u32 v[74:75], s[60:61], v72, s0, 0
	v_mad_i32_i24 v75, v73, s0, v75
	v_lshlrev_b64 v[72:73], 1, v[74:75]
	v_cvt_pk_bf16_f32 v17, v17, v33
	v_lshl_add_u64 v[74:75], v[24:25], 0, v[72:73]
	global_store_short v[74:75], v17, off
	v_sub_f32_e32 v17, v1, v69
	v_mul_f32_e32 v17, 0x3fb8aa3b, v17
	v_exp_f32_e32 v17, v17
	v_lshl_add_u64 v[72:73], v[22:23], 0, v[72:73]
	v_mul_f32_e32 v17, v17, v71
	v_ashrrev_i32_e32 v71, 31, v70
	v_lshl_add_u64 v[70:71], v[70:71], 0, s[34:35]
	v_cvt_pk_bf16_f32 v17, v17, v33
	global_store_short v[72:73], v17, off
	v_sub_f32_e32 v72, v67, v4
	v_mul_f32_e32 v72, 0x3fb8aa3b, v72
	v_exp_f32_e32 v72, v72
	s_waitcnt vmcnt(22)
	v_lshlrev_b32_e32 v17, 16, v220
	v_mul_f32_e32 v17, 0x3d800000, v17
	v_mul_f32_e32 v72, v72, v17
	v_cvt_pk_bf16_f32 v72, v72, v33
	ds_write_b16 v137, v72
	v_sub_f32_e32 v72, v4, v67
	v_mul_f32_e32 v72, 0x3fb8aa3b, v72
	v_exp_f32_e32 v72, v72
	v_lshlrev_b32_e32 v69, 16, v221
	v_add_u32_e32 v245, s34, v58
	v_mad_u64_u32 v[158:159], s[60:61], v245, s93, v[12:13]
	global_load_ushort v220, v[158:159], off
	global_load_ushort v221, v[158:159], off offset:2048
	v_mul_f32_e32 v72, v72, v69
	v_cvt_pk_bf16_f32 v72, v72, v33
	ds_write_b16 v137, v72 offset:33792
	v_mul_f32_e32 v72, 0x3fb8aa3b, v67
	v_exp_f32_e32 v72, v72
	s_nop 0
	v_mul_f32_e32 v17, v72, v17
	v_mad_u64_u32 v[72:73], s[60:61], v70, s0, 0
	v_mad_i32_i24 v73, v71, s0, v73
	v_lshlrev_b64 v[70:71], 1, v[72:73]
	v_cvt_pk_bf16_f32 v17, v17, v33
	v_lshl_add_u64 v[72:73], v[24:25], 0, v[70:71]
	global_store_short v[72:73], v17, off
	v_sub_f32_e32 v17, v1, v67
	v_mul_f32_e32 v17, 0x3fb8aa3b, v17
	v_exp_f32_e32 v17, v17
	v_lshl_add_u64 v[70:71], v[22:23], 0, v[70:71]
	v_mul_f32_e32 v17, v17, v69
	v_ashrrev_i32_e32 v69, 31, v68
	v_lshl_add_u64 v[68:69], v[68:69], 0, s[34:35]
	v_cvt_pk_bf16_f32 v17, v17, v33
	global_store_short v[70:71], v17, off
	v_sub_f32_e32 v70, v65, v4
	v_mul_f32_e32 v70, 0x3fb8aa3b, v70
	v_exp_f32_e32 v70, v70
	s_waitcnt vmcnt(22)
	v_lshlrev_b32_e32 v17, 16, v222
	v_mul_f32_e32 v17, 0x3d800000, v17
	v_mul_f32_e32 v70, v70, v17
	v_cvt_pk_bf16_f32 v70, v70, v33
	ds_write_b16 v138, v70
	v_sub_f32_e32 v70, v4, v65
	v_mul_f32_e32 v70, 0x3fb8aa3b, v70
	v_exp_f32_e32 v70, v70
	v_lshlrev_b32_e32 v67, 16, v223
	v_add_u32_e32 v245, s34, v56
	v_mad_u64_u32 v[158:159], s[60:61], v245, s93, v[12:13]
	global_load_ushort v222, v[158:159], off
	global_load_ushort v223, v[158:159], off offset:2048
	v_mul_f32_e32 v70, v70, v67
	v_cvt_pk_bf16_f32 v70, v70, v33
	ds_write_b16 v138, v70 offset:33792
	v_mul_f32_e32 v70, 0x3fb8aa3b, v65
	v_exp_f32_e32 v70, v70
	s_nop 0
	v_mul_f32_e32 v17, v70, v17
	v_mad_u64_u32 v[70:71], s[60:61], v68, s0, 0
	v_mad_i32_i24 v71, v69, s0, v71
	v_lshlrev_b64 v[68:69], 1, v[70:71]
	v_cvt_pk_bf16_f32 v17, v17, v33
	v_lshl_add_u64 v[70:71], v[24:25], 0, v[68:69]
	global_store_short v[70:71], v17, off
	v_sub_f32_e32 v17, v1, v65
	v_mul_f32_e32 v17, 0x3fb8aa3b, v17
	v_exp_f32_e32 v17, v17
	v_lshl_add_u64 v[68:69], v[22:23], 0, v[68:69]
	v_mul_f32_e32 v17, v17, v67
	v_ashrrev_i32_e32 v67, 31, v66
	v_lshl_add_u64 v[66:67], v[66:67], 0, s[34:35]
	v_cvt_pk_bf16_f32 v17, v17, v33
	global_store_short v[68:69], v17, off
	v_sub_f32_e32 v68, v63, v4
	v_mul_f32_e32 v68, 0x3fb8aa3b, v68
	v_exp_f32_e32 v68, v68
	s_waitcnt vmcnt(22)
	v_lshlrev_b32_e32 v17, 16, v246
	v_mul_f32_e32 v17, 0x3d800000, v17
	v_mul_f32_e32 v68, v68, v17
	v_cvt_pk_bf16_f32 v68, v68, v33
	ds_write_b16 v139, v68
	v_sub_f32_e32 v68, v4, v63
	v_mul_f32_e32 v68, 0x3fb8aa3b, v68
	v_exp_f32_e32 v68, v68
	v_lshlrev_b32_e32 v65, 16, v247
	v_add_u32_e32 v245, s34, v54
	v_mad_u64_u32 v[158:159], s[60:61], v245, s93, v[12:13]
	global_load_ushort v246, v[158:159], off
	global_load_ushort v247, v[158:159], off offset:2048
	v_mul_f32_e32 v68, v68, v65
	v_cvt_pk_bf16_f32 v68, v68, v33
	ds_write_b16 v139, v68 offset:33792
	v_mul_f32_e32 v68, 0x3fb8aa3b, v63
	v_exp_f32_e32 v68, v68
	s_nop 0
	v_mul_f32_e32 v17, v68, v17
	v_mad_u64_u32 v[68:69], s[60:61], v66, s0, 0
	v_mad_i32_i24 v69, v67, s0, v69
	v_lshlrev_b64 v[66:67], 1, v[68:69]
	v_cvt_pk_bf16_f32 v17, v17, v33
	v_lshl_add_u64 v[68:69], v[24:25], 0, v[66:67]
	global_store_short v[68:69], v17, off
	v_sub_f32_e32 v17, v1, v63
	v_mul_f32_e32 v17, 0x3fb8aa3b, v17
	v_exp_f32_e32 v17, v17
	v_lshl_add_u64 v[66:67], v[22:23], 0, v[66:67]
	v_mul_f32_e32 v17, v17, v65
	v_ashrrev_i32_e32 v65, 31, v64
	v_lshl_add_u64 v[64:65], v[64:65], 0, s[34:35]
	v_cvt_pk_bf16_f32 v17, v17, v33
	global_store_short v[66:67], v17, off
	v_sub_f32_e32 v66, v61, v4
	v_mul_f32_e32 v66, 0x3fb8aa3b, v66
	v_exp_f32_e32 v66, v66
	s_waitcnt vmcnt(22)
	v_lshlrev_b32_e32 v17, 16, v248
	v_mul_f32_e32 v17, 0x3d800000, v17
	v_mul_f32_e32 v66, v66, v17
	v_cvt_pk_bf16_f32 v66, v66, v33
	ds_write_b16 v140, v66
	v_sub_f32_e32 v66, v4, v61
	v_mul_f32_e32 v66, 0x3fb8aa3b, v66
	v_exp_f32_e32 v66, v66
	v_lshlrev_b32_e32 v63, 16, v249
	v_add_u32_e32 v245, s34, v52
	v_mad_u64_u32 v[158:159], s[60:61], v245, s93, v[12:13]
	global_load_ushort v248, v[158:159], off
	global_load_ushort v249, v[158:159], off offset:2048
	v_mul_f32_e32 v66, v66, v63
	v_cvt_pk_bf16_f32 v66, v66, v33
	ds_write_b16 v140, v66 offset:33792
	v_mul_f32_e32 v66, 0x3fb8aa3b, v61
	v_exp_f32_e32 v66, v66
	s_nop 0
	v_mul_f32_e32 v17, v66, v17
	v_mad_u64_u32 v[66:67], s[60:61], v64, s0, 0
	v_mad_i32_i24 v67, v65, s0, v67
	v_lshlrev_b64 v[64:65], 1, v[66:67]
	v_cvt_pk_bf16_f32 v17, v17, v33
	v_lshl_add_u64 v[66:67], v[24:25], 0, v[64:65]
	global_store_short v[66:67], v17, off
	v_sub_f32_e32 v17, v1, v61
	v_mul_f32_e32 v17, 0x3fb8aa3b, v17
	v_exp_f32_e32 v17, v17
	v_lshl_add_u64 v[64:65], v[22:23], 0, v[64:65]
	v_mul_f32_e32 v17, v17, v63
	v_ashrrev_i32_e32 v63, 31, v62
	v_lshl_add_u64 v[62:63], v[62:63], 0, s[34:35]
	v_cvt_pk_bf16_f32 v17, v17, v33
	global_store_short v[64:65], v17, off
	v_sub_f32_e32 v64, v59, v4
	v_mul_f32_e32 v64, 0x3fb8aa3b, v64
	v_exp_f32_e32 v64, v64
	s_waitcnt vmcnt(22)
	v_lshlrev_b32_e32 v17, 16, v216
	v_mul_f32_e32 v17, 0x3d800000, v17
	v_mul_f32_e32 v64, v64, v17
	v_cvt_pk_bf16_f32 v64, v64, v33
	ds_write_b16 v141, v64
	v_sub_f32_e32 v64, v4, v59
	v_mul_f32_e32 v64, 0x3fb8aa3b, v64
	v_exp_f32_e32 v64, v64
	v_lshlrev_b32_e32 v61, 16, v217
	v_add_u32_e32 v245, s34, v50
	v_mad_u64_u32 v[158:159], s[60:61], v245, s93, v[12:13]
	global_load_ushort v216, v[158:159], off
	global_load_ushort v217, v[158:159], off offset:2048
	v_mul_f32_e32 v64, v64, v61
	v_cvt_pk_bf16_f32 v64, v64, v33
	ds_write_b16 v141, v64 offset:33792
	v_mul_f32_e32 v64, 0x3fb8aa3b, v59
	v_exp_f32_e32 v64, v64
	s_nop 0
	v_mul_f32_e32 v17, v64, v17
	v_mad_u64_u32 v[64:65], s[60:61], v62, s0, 0
	v_mad_i32_i24 v65, v63, s0, v65
	v_lshlrev_b64 v[62:63], 1, v[64:65]
	v_cvt_pk_bf16_f32 v17, v17, v33
	v_lshl_add_u64 v[64:65], v[24:25], 0, v[62:63]
	global_store_short v[64:65], v17, off
	v_sub_f32_e32 v17, v1, v59
	v_mul_f32_e32 v17, 0x3fb8aa3b, v17
	v_exp_f32_e32 v17, v17
	v_lshl_add_u64 v[62:63], v[22:23], 0, v[62:63]
	v_mul_f32_e32 v17, v17, v61
	v_ashrrev_i32_e32 v61, 31, v60
	v_lshl_add_u64 v[60:61], v[60:61], 0, s[34:35]
	v_cvt_pk_bf16_f32 v17, v17, v33
	global_store_short v[62:63], v17, off
	v_sub_f32_e32 v62, v57, v4
	v_mul_f32_e32 v62, 0x3fb8aa3b, v62
	v_exp_f32_e32 v62, v62
	s_waitcnt vmcnt(22)
	v_lshlrev_b32_e32 v17, 16, v218
	v_mul_f32_e32 v17, 0x3d800000, v17
	v_mul_f32_e32 v62, v62, v17
	v_cvt_pk_bf16_f32 v62, v62, v33
	ds_write_b16 v142, v62
	v_sub_f32_e32 v62, v4, v57
	v_mul_f32_e32 v62, 0x3fb8aa3b, v62
	v_exp_f32_e32 v62, v62
	v_lshlrev_b32_e32 v59, 16, v219
	v_add_u32_e32 v245, s34, v48
	v_mad_u64_u32 v[158:159], s[60:61], v245, s93, v[12:13]
	global_load_ushort v218, v[158:159], off
	global_load_ushort v219, v[158:159], off offset:2048
	v_mul_f32_e32 v62, v62, v59
	v_cvt_pk_bf16_f32 v62, v62, v33
	ds_write_b16 v142, v62 offset:33792
	v_mul_f32_e32 v62, 0x3fb8aa3b, v57
	v_exp_f32_e32 v62, v62
	s_nop 0
	v_mul_f32_e32 v17, v62, v17
	v_mad_u64_u32 v[62:63], s[60:61], v60, s0, 0
	v_mad_i32_i24 v63, v61, s0, v63
	v_lshlrev_b64 v[60:61], 1, v[62:63]
	v_cvt_pk_bf16_f32 v17, v17, v33
	v_lshl_add_u64 v[62:63], v[24:25], 0, v[60:61]
	global_store_short v[62:63], v17, off
	v_sub_f32_e32 v17, v1, v57
	v_mul_f32_e32 v17, 0x3fb8aa3b, v17
	v_exp_f32_e32 v17, v17
	v_lshl_add_u64 v[60:61], v[22:23], 0, v[60:61]
	v_mul_f32_e32 v17, v17, v59
	v_ashrrev_i32_e32 v59, 31, v58
	v_lshl_add_u64 v[58:59], v[58:59], 0, s[34:35]
	v_cvt_pk_bf16_f32 v17, v17, v33
	global_store_short v[60:61], v17, off
	v_sub_f32_e32 v60, v55, v4
	v_mul_f32_e32 v60, 0x3fb8aa3b, v60
	v_exp_f32_e32 v60, v60
	s_waitcnt vmcnt(22)
	v_lshlrev_b32_e32 v17, 16, v220
	v_mul_f32_e32 v17, 0x3d800000, v17
	v_mul_f32_e32 v60, v60, v17
	v_cvt_pk_bf16_f32 v60, v60, v33
	ds_write_b16 v143, v60
	v_sub_f32_e32 v60, v4, v55
	v_mul_f32_e32 v60, 0x3fb8aa3b, v60
	v_exp_f32_e32 v60, v60
	v_lshlrev_b32_e32 v57, 16, v221
	v_add_u32_e32 v245, s34, v46
	v_mad_u64_u32 v[158:159], s[60:61], v245, s93, v[12:13]
	global_load_ushort v220, v[158:159], off
	global_load_ushort v221, v[158:159], off offset:2048
	v_mul_f32_e32 v60, v60, v57
	v_cvt_pk_bf16_f32 v60, v60, v33
	ds_write_b16 v143, v60 offset:33792
	v_mul_f32_e32 v60, 0x3fb8aa3b, v55
	v_exp_f32_e32 v60, v60
	s_nop 0
	v_mul_f32_e32 v17, v60, v17
	v_mad_u64_u32 v[60:61], s[60:61], v58, s0, 0
	v_mad_i32_i24 v61, v59, s0, v61
	v_lshlrev_b64 v[58:59], 1, v[60:61]
	v_cvt_pk_bf16_f32 v17, v17, v33
	v_lshl_add_u64 v[60:61], v[24:25], 0, v[58:59]
	global_store_short v[60:61], v17, off
	v_sub_f32_e32 v17, v1, v55
	v_mul_f32_e32 v17, 0x3fb8aa3b, v17
	v_exp_f32_e32 v17, v17
	v_lshl_add_u64 v[58:59], v[22:23], 0, v[58:59]
	v_mul_f32_e32 v17, v17, v57
	v_ashrrev_i32_e32 v57, 31, v56
	v_lshl_add_u64 v[56:57], v[56:57], 0, s[34:35]
	v_cvt_pk_bf16_f32 v17, v17, v33
	global_store_short v[58:59], v17, off
	v_sub_f32_e32 v58, v53, v4
	v_mul_f32_e32 v58, 0x3fb8aa3b, v58
	v_exp_f32_e32 v58, v58
	s_waitcnt vmcnt(22)
	v_lshlrev_b32_e32 v17, 16, v222
	v_mul_f32_e32 v17, 0x3d800000, v17
	v_mul_f32_e32 v58, v58, v17
	v_cvt_pk_bf16_f32 v58, v58, v33
	ds_write_b16 v144, v58
	v_sub_f32_e32 v58, v4, v53
	v_mul_f32_e32 v58, 0x3fb8aa3b, v58
	v_exp_f32_e32 v58, v58
	v_lshlrev_b32_e32 v55, 16, v223
	v_add_u32_e32 v245, s34, v44
	v_mad_u64_u32 v[158:159], s[60:61], v245, s93, v[12:13]
	global_load_ushort v222, v[158:159], off
	global_load_ushort v223, v[158:159], off offset:2048
	v_mul_f32_e32 v58, v58, v55
	v_cvt_pk_bf16_f32 v58, v58, v33
	ds_write_b16 v144, v58 offset:33792
	v_mul_f32_e32 v58, 0x3fb8aa3b, v53
	v_exp_f32_e32 v58, v58
	s_nop 0
	v_mul_f32_e32 v17, v58, v17
	v_mad_u64_u32 v[58:59], s[60:61], v56, s0, 0
	v_mad_i32_i24 v59, v57, s0, v59
	v_lshlrev_b64 v[56:57], 1, v[58:59]
	v_cvt_pk_bf16_f32 v17, v17, v33
	v_lshl_add_u64 v[58:59], v[24:25], 0, v[56:57]
	global_store_short v[58:59], v17, off
	v_sub_f32_e32 v17, v1, v53
	v_mul_f32_e32 v17, 0x3fb8aa3b, v17
	v_exp_f32_e32 v17, v17
	v_lshl_add_u64 v[56:57], v[22:23], 0, v[56:57]
	v_mul_f32_e32 v17, v17, v55
	v_ashrrev_i32_e32 v55, 31, v54
	v_lshl_add_u64 v[54:55], v[54:55], 0, s[34:35]
	v_cvt_pk_bf16_f32 v17, v17, v33
	global_store_short v[56:57], v17, off
	v_sub_f32_e32 v56, v51, v4
	v_mul_f32_e32 v56, 0x3fb8aa3b, v56
	v_exp_f32_e32 v56, v56
	s_waitcnt vmcnt(22)
	v_lshlrev_b32_e32 v17, 16, v246
	v_mul_f32_e32 v17, 0x3d800000, v17
	v_mul_f32_e32 v56, v56, v17
	v_cvt_pk_bf16_f32 v56, v56, v33
	ds_write_b16 v145, v56
	v_sub_f32_e32 v56, v4, v51
	v_mul_f32_e32 v56, 0x3fb8aa3b, v56
	v_exp_f32_e32 v56, v56
	v_lshlrev_b32_e32 v53, 16, v247
	v_add_u32_e32 v245, s34, v42
	v_mad_u64_u32 v[158:159], s[60:61], v245, s93, v[12:13]
	global_load_ushort v246, v[158:159], off
	global_load_ushort v247, v[158:159], off offset:2048
	v_mul_f32_e32 v56, v56, v53
	v_cvt_pk_bf16_f32 v56, v56, v33
	ds_write_b16 v145, v56 offset:33792
	v_mul_f32_e32 v56, 0x3fb8aa3b, v51
	v_exp_f32_e32 v56, v56
	s_nop 0
	v_mul_f32_e32 v17, v56, v17
	v_mad_u64_u32 v[56:57], s[60:61], v54, s0, 0
	v_mad_i32_i24 v57, v55, s0, v57
	v_lshlrev_b64 v[54:55], 1, v[56:57]
	v_cvt_pk_bf16_f32 v17, v17, v33
	v_lshl_add_u64 v[56:57], v[24:25], 0, v[54:55]
	global_store_short v[56:57], v17, off
	v_sub_f32_e32 v17, v1, v51
	v_mul_f32_e32 v17, 0x3fb8aa3b, v17
	v_exp_f32_e32 v17, v17
	v_lshl_add_u64 v[54:55], v[22:23], 0, v[54:55]
	v_mul_f32_e32 v17, v17, v53
	v_ashrrev_i32_e32 v53, 31, v52
	v_lshl_add_u64 v[52:53], v[52:53], 0, s[34:35]
	v_cvt_pk_bf16_f32 v17, v17, v33
	global_store_short v[54:55], v17, off
	v_sub_f32_e32 v54, v49, v4
	v_mul_f32_e32 v54, 0x3fb8aa3b, v54
	v_exp_f32_e32 v54, v54
	s_waitcnt vmcnt(22)
	v_lshlrev_b32_e32 v17, 16, v248
	v_mul_f32_e32 v17, 0x3d800000, v17
	v_mul_f32_e32 v54, v54, v17
	v_cvt_pk_bf16_f32 v54, v54, v33
	ds_write_b16 v146, v54
	v_sub_f32_e32 v54, v4, v49
	v_mul_f32_e32 v54, 0x3fb8aa3b, v54
	v_exp_f32_e32 v54, v54
	v_lshlrev_b32_e32 v51, 16, v249
	v_add_u32_e32 v245, s34, v40
	v_mad_u64_u32 v[158:159], s[60:61], v245, s93, v[12:13]
	global_load_ushort v248, v[158:159], off
	global_load_ushort v249, v[158:159], off offset:2048
	v_mul_f32_e32 v54, v54, v51
	v_cvt_pk_bf16_f32 v54, v54, v33
	ds_write_b16 v146, v54 offset:33792
	v_mul_f32_e32 v54, 0x3fb8aa3b, v49
	v_exp_f32_e32 v54, v54
	s_nop 0
	v_mul_f32_e32 v17, v54, v17
	v_mad_u64_u32 v[54:55], s[60:61], v52, s0, 0
	v_mad_i32_i24 v55, v53, s0, v55
	v_lshlrev_b64 v[52:53], 1, v[54:55]
	v_cvt_pk_bf16_f32 v17, v17, v33
	v_lshl_add_u64 v[54:55], v[24:25], 0, v[52:53]
	global_store_short v[54:55], v17, off
	v_sub_f32_e32 v17, v1, v49
	v_mul_f32_e32 v17, 0x3fb8aa3b, v17
	v_exp_f32_e32 v17, v17
	v_lshl_add_u64 v[52:53], v[22:23], 0, v[52:53]
	v_mul_f32_e32 v17, v17, v51
	v_ashrrev_i32_e32 v51, 31, v50
	v_lshl_add_u64 v[50:51], v[50:51], 0, s[34:35]
	v_cvt_pk_bf16_f32 v17, v17, v33
	global_store_short v[52:53], v17, off
	v_sub_f32_e32 v52, v47, v4
	v_mul_f32_e32 v52, 0x3fb8aa3b, v52
	v_exp_f32_e32 v52, v52
	s_waitcnt vmcnt(22)
	v_lshlrev_b32_e32 v17, 16, v216
	v_mul_f32_e32 v17, 0x3d800000, v17
	v_mul_f32_e32 v52, v52, v17
	v_cvt_pk_bf16_f32 v52, v52, v33
	ds_write_b16 v147, v52
	v_sub_f32_e32 v52, v4, v47
	v_mul_f32_e32 v52, 0x3fb8aa3b, v52
	v_exp_f32_e32 v52, v52
	v_lshlrev_b32_e32 v49, 16, v217
	v_add_u32_e32 v245, s34, v38
	v_mad_u64_u32 v[158:159], s[60:61], v245, s93, v[12:13]
	global_load_ushort v216, v[158:159], off
	global_load_ushort v217, v[158:159], off offset:2048
	v_mul_f32_e32 v52, v52, v49
	v_cvt_pk_bf16_f32 v52, v52, v33
	ds_write_b16 v147, v52 offset:33792
	v_mul_f32_e32 v52, 0x3fb8aa3b, v47
	v_exp_f32_e32 v52, v52
	s_nop 0
	v_mul_f32_e32 v17, v52, v17
	v_mad_u64_u32 v[52:53], s[60:61], v50, s0, 0
	v_mad_i32_i24 v53, v51, s0, v53
	v_lshlrev_b64 v[50:51], 1, v[52:53]
	v_cvt_pk_bf16_f32 v17, v17, v33
	v_lshl_add_u64 v[52:53], v[24:25], 0, v[50:51]
	global_store_short v[52:53], v17, off
	v_sub_f32_e32 v17, v1, v47
	v_mul_f32_e32 v17, 0x3fb8aa3b, v17
	v_exp_f32_e32 v17, v17
	v_lshl_add_u64 v[50:51], v[22:23], 0, v[50:51]
	v_mul_f32_e32 v17, v17, v49
	v_ashrrev_i32_e32 v49, 31, v48
	v_lshl_add_u64 v[48:49], v[48:49], 0, s[34:35]
	v_cvt_pk_bf16_f32 v17, v17, v33
	global_store_short v[50:51], v17, off
	v_sub_f32_e32 v50, v45, v4
	v_mul_f32_e32 v50, 0x3fb8aa3b, v50
	v_exp_f32_e32 v50, v50
	s_waitcnt vmcnt(22)
	v_lshlrev_b32_e32 v17, 16, v218
	v_mul_f32_e32 v17, 0x3d800000, v17
	v_mul_f32_e32 v50, v50, v17
	v_cvt_pk_bf16_f32 v50, v50, v33
	ds_write_b16 v148, v50
	v_sub_f32_e32 v50, v4, v45
	v_mul_f32_e32 v50, 0x3fb8aa3b, v50
	v_exp_f32_e32 v50, v50
	v_lshlrev_b32_e32 v47, 16, v219
	v_add_u32_e32 v245, s34, v36
	v_mad_u64_u32 v[158:159], s[60:61], v245, s93, v[12:13]
	global_load_ushort v218, v[158:159], off
	global_load_ushort v219, v[158:159], off offset:2048
	v_mul_f32_e32 v50, v50, v47
	v_cvt_pk_bf16_f32 v50, v50, v33
	ds_write_b16 v148, v50 offset:33792
	v_mul_f32_e32 v50, 0x3fb8aa3b, v45
	v_exp_f32_e32 v50, v50
	s_nop 0
	v_mul_f32_e32 v17, v50, v17
	v_mad_u64_u32 v[50:51], s[60:61], v48, s0, 0
	v_mad_i32_i24 v51, v49, s0, v51
	v_lshlrev_b64 v[48:49], 1, v[50:51]
	v_cvt_pk_bf16_f32 v17, v17, v33
	v_lshl_add_u64 v[50:51], v[24:25], 0, v[48:49]
	global_store_short v[50:51], v17, off
	v_sub_f32_e32 v17, v1, v45
	v_mul_f32_e32 v17, 0x3fb8aa3b, v17
	v_exp_f32_e32 v17, v17
	v_lshl_add_u64 v[48:49], v[22:23], 0, v[48:49]
	v_mul_f32_e32 v17, v17, v47
	v_ashrrev_i32_e32 v47, 31, v46
	v_lshl_add_u64 v[46:47], v[46:47], 0, s[34:35]
	v_cvt_pk_bf16_f32 v17, v17, v33
	global_store_short v[48:49], v17, off
	v_sub_f32_e32 v48, v43, v4
	v_mul_f32_e32 v48, 0x3fb8aa3b, v48
	v_exp_f32_e32 v48, v48
	s_waitcnt vmcnt(22)
	v_lshlrev_b32_e32 v17, 16, v220
	v_mul_f32_e32 v17, 0x3d800000, v17
	v_mul_f32_e32 v48, v48, v17
	v_cvt_pk_bf16_f32 v48, v48, v33
	ds_write_b16 v149, v48
	v_sub_f32_e32 v48, v4, v43
	v_mul_f32_e32 v48, 0x3fb8aa3b, v48
	v_exp_f32_e32 v48, v48
	v_lshlrev_b32_e32 v45, 16, v221
	v_add_u32_e32 v245, s34, v34
	v_mad_u64_u32 v[158:159], s[60:61], v245, s93, v[12:13]
	global_load_ushort v220, v[158:159], off
	global_load_ushort v221, v[158:159], off offset:2048
	v_mul_f32_e32 v48, v48, v45
	v_cvt_pk_bf16_f32 v48, v48, v33
	ds_write_b16 v149, v48 offset:33792
	v_mul_f32_e32 v48, 0x3fb8aa3b, v43
	v_exp_f32_e32 v48, v48
	s_nop 0
	v_mul_f32_e32 v17, v48, v17
	v_mad_u64_u32 v[48:49], s[60:61], v46, s0, 0
	v_mad_i32_i24 v49, v47, s0, v49
	v_lshlrev_b64 v[46:47], 1, v[48:49]
	v_cvt_pk_bf16_f32 v17, v17, v33
	v_lshl_add_u64 v[48:49], v[24:25], 0, v[46:47]
	global_store_short v[48:49], v17, off
	v_sub_f32_e32 v17, v1, v43
	v_mul_f32_e32 v17, 0x3fb8aa3b, v17
	v_exp_f32_e32 v17, v17
	v_lshl_add_u64 v[46:47], v[22:23], 0, v[46:47]
	v_mul_f32_e32 v17, v17, v45
	v_ashrrev_i32_e32 v45, 31, v44
	v_lshl_add_u64 v[44:45], v[44:45], 0, s[34:35]
	v_cvt_pk_bf16_f32 v17, v17, v33
	global_store_short v[46:47], v17, off
	v_sub_f32_e32 v46, v41, v4
	v_mul_f32_e32 v46, 0x3fb8aa3b, v46
	v_exp_f32_e32 v46, v46
	s_waitcnt vmcnt(22)
	v_lshlrev_b32_e32 v17, 16, v222
	v_mul_f32_e32 v17, 0x3d800000, v17
	v_mul_f32_e32 v46, v46, v17
	v_cvt_pk_bf16_f32 v46, v46, v33
	ds_write_b16 v150, v46
	v_sub_f32_e32 v46, v4, v41
	v_mul_f32_e32 v46, 0x3fb8aa3b, v46
	v_exp_f32_e32 v46, v46
	v_lshlrev_b32_e32 v43, 16, v223
	v_add_u32_e32 v245, s34, v30
	v_mad_u64_u32 v[158:159], s[60:61], v245, s93, v[12:13]
	global_load_ushort v222, v[158:159], off
	global_load_ushort v223, v[158:159], off offset:2048
	v_mul_f32_e32 v46, v46, v43
	v_cvt_pk_bf16_f32 v46, v46, v33
	ds_write_b16 v150, v46 offset:33792
	v_mul_f32_e32 v46, 0x3fb8aa3b, v41
	v_exp_f32_e32 v46, v46
	s_nop 0
	v_mul_f32_e32 v17, v46, v17
	v_mad_u64_u32 v[46:47], s[60:61], v44, s0, 0
	v_mad_i32_i24 v47, v45, s0, v47
	v_lshlrev_b64 v[44:45], 1, v[46:47]
	v_cvt_pk_bf16_f32 v17, v17, v33
	v_lshl_add_u64 v[46:47], v[24:25], 0, v[44:45]
	global_store_short v[46:47], v17, off
	v_sub_f32_e32 v17, v1, v41
	v_mul_f32_e32 v17, 0x3fb8aa3b, v17
	v_exp_f32_e32 v17, v17
	v_lshl_add_u64 v[44:45], v[22:23], 0, v[44:45]
	v_mul_f32_e32 v17, v17, v43
	v_ashrrev_i32_e32 v43, 31, v42
	v_lshl_add_u64 v[42:43], v[42:43], 0, s[34:35]
	v_cvt_pk_bf16_f32 v17, v17, v33
	global_store_short v[44:45], v17, off
	v_sub_f32_e32 v44, v39, v4
	v_mul_f32_e32 v44, 0x3fb8aa3b, v44
	v_exp_f32_e32 v44, v44
	s_waitcnt vmcnt(22)
	v_lshlrev_b32_e32 v17, 16, v246
	v_mul_f32_e32 v17, 0x3d800000, v17
	v_mul_f32_e32 v44, v44, v17
	v_cvt_pk_bf16_f32 v44, v44, v33
	ds_write_b16 v151, v44
	v_sub_f32_e32 v44, v4, v39
	v_mul_f32_e32 v44, 0x3fb8aa3b, v44
	v_exp_f32_e32 v44, v44
	v_lshlrev_b32_e32 v41, 16, v247
	v_add_u32_e32 v245, s34, v28
	v_mad_u64_u32 v[158:159], s[60:61], v245, s93, v[12:13]
	global_load_ushort v246, v[158:159], off
	global_load_ushort v247, v[158:159], off offset:2048
	v_mul_f32_e32 v44, v44, v41
	v_cvt_pk_bf16_f32 v44, v44, v33
	ds_write_b16 v151, v44 offset:33792
	v_mul_f32_e32 v44, 0x3fb8aa3b, v39
	v_exp_f32_e32 v44, v44
	s_nop 0
	v_mul_f32_e32 v17, v44, v17
	v_mad_u64_u32 v[44:45], s[60:61], v42, s0, 0
	v_mad_i32_i24 v45, v43, s0, v45
	v_lshlrev_b64 v[42:43], 1, v[44:45]
	v_cvt_pk_bf16_f32 v17, v17, v33
	v_lshl_add_u64 v[44:45], v[24:25], 0, v[42:43]
	global_store_short v[44:45], v17, off
	v_sub_f32_e32 v17, v1, v39
	v_mul_f32_e32 v17, 0x3fb8aa3b, v17
	v_exp_f32_e32 v17, v17
	v_lshl_add_u64 v[42:43], v[22:23], 0, v[42:43]
	v_mul_f32_e32 v17, v17, v41
	v_ashrrev_i32_e32 v41, 31, v40
	v_lshl_add_u64 v[40:41], v[40:41], 0, s[34:35]
	v_cvt_pk_bf16_f32 v17, v17, v33
	global_store_short v[42:43], v17, off
	v_sub_f32_e32 v42, v37, v4
	v_mul_f32_e32 v42, 0x3fb8aa3b, v42
	v_exp_f32_e32 v42, v42
	s_waitcnt vmcnt(22)
	v_lshlrev_b32_e32 v17, 16, v248
	v_mul_f32_e32 v17, 0x3d800000, v17
	v_mul_f32_e32 v42, v42, v17
	v_cvt_pk_bf16_f32 v42, v42, v33
	ds_write_b16 v152, v42
	v_sub_f32_e32 v42, v4, v37
	v_mul_f32_e32 v42, 0x3fb8aa3b, v42
	v_exp_f32_e32 v42, v42
	v_lshlrev_b32_e32 v39, 16, v249
	v_add_u32_e32 v245, s34, v26
	v_mad_u64_u32 v[158:159], s[60:61], v245, s93, v[12:13]
	global_load_ushort v248, v[158:159], off
	global_load_ushort v249, v[158:159], off offset:2048
	v_mul_f32_e32 v42, v42, v39
	v_cvt_pk_bf16_f32 v42, v42, v33
	ds_write_b16 v152, v42 offset:33792
	v_mul_f32_e32 v42, 0x3fb8aa3b, v37
	v_exp_f32_e32 v42, v42
	s_nop 0
	v_mul_f32_e32 v17, v42, v17
	v_mad_u64_u32 v[42:43], s[60:61], v40, s0, 0
	v_mad_i32_i24 v43, v41, s0, v43
	v_lshlrev_b64 v[40:41], 1, v[42:43]
	v_cvt_pk_bf16_f32 v17, v17, v33
	v_lshl_add_u64 v[42:43], v[24:25], 0, v[40:41]
	global_store_short v[42:43], v17, off
	v_sub_f32_e32 v17, v1, v37
	v_mul_f32_e32 v17, 0x3fb8aa3b, v17
	v_exp_f32_e32 v17, v17
	v_lshl_add_u64 v[40:41], v[22:23], 0, v[40:41]
	v_mul_f32_e32 v17, v17, v39
	v_ashrrev_i32_e32 v39, 31, v38
	v_lshl_add_u64 v[38:39], v[38:39], 0, s[34:35]
	v_cvt_pk_bf16_f32 v17, v17, v33
	global_store_short v[40:41], v17, off
	v_sub_f32_e32 v40, v35, v4
	v_mul_f32_e32 v40, 0x3fb8aa3b, v40
	v_exp_f32_e32 v40, v40
	s_waitcnt vmcnt(22)
	v_lshlrev_b32_e32 v17, 16, v216
	v_mul_f32_e32 v17, 0x3d800000, v17
	v_mul_f32_e32 v40, v40, v17
	v_cvt_pk_bf16_f32 v40, v40, v33
	ds_write_b16 v153, v40
	v_sub_f32_e32 v40, v4, v35
	v_mul_f32_e32 v40, 0x3fb8aa3b, v40
	v_exp_f32_e32 v40, v40
	v_lshlrev_b32_e32 v37, 16, v217
	v_add_u32_e32 v245, s34, v20
	v_mad_u64_u32 v[158:159], s[60:61], v245, s93, v[12:13]
	global_load_ushort v216, v[158:159], off
	global_load_ushort v217, v[158:159], off offset:2048
	v_mul_f32_e32 v40, v40, v37
	v_cvt_pk_bf16_f32 v40, v40, v33
	ds_write_b16 v153, v40 offset:33792
	v_mul_f32_e32 v40, 0x3fb8aa3b, v35
	v_exp_f32_e32 v40, v40
	s_nop 0
	v_mul_f32_e32 v17, v40, v17
	v_mad_u64_u32 v[40:41], s[60:61], v38, s0, 0
	v_mad_i32_i24 v41, v39, s0, v41
	v_lshlrev_b64 v[38:39], 1, v[40:41]
	v_cvt_pk_bf16_f32 v17, v17, v33
	v_lshl_add_u64 v[40:41], v[24:25], 0, v[38:39]
	global_store_short v[40:41], v17, off
	v_sub_f32_e32 v17, v1, v35
	v_mul_f32_e32 v17, 0x3fb8aa3b, v17
	v_exp_f32_e32 v17, v17
	v_lshl_add_u64 v[38:39], v[22:23], 0, v[38:39]
	v_mul_f32_e32 v17, v17, v37
	v_ashrrev_i32_e32 v37, 31, v36
	v_lshl_add_u64 v[36:37], v[36:37], 0, s[34:35]
	v_cvt_pk_bf16_f32 v17, v17, v33
	global_store_short v[38:39], v17, off
	v_sub_f32_e32 v38, v32, v4
	v_mul_f32_e32 v38, 0x3fb8aa3b, v38
	v_exp_f32_e32 v38, v38
	s_waitcnt vmcnt(22)
	v_lshlrev_b32_e32 v17, 16, v218
	v_mul_f32_e32 v17, 0x3d800000, v17
	v_mul_f32_e32 v38, v38, v17
	v_cvt_pk_bf16_f32 v38, v38, v33
	ds_write_b16 v155, v38
	v_sub_f32_e32 v38, v4, v32
	v_mul_f32_e32 v38, 0x3fb8aa3b, v38
	v_exp_f32_e32 v38, v38
	v_lshlrev_b32_e32 v35, 16, v219
	v_add_u32_e32 v245, s34, v2
	v_mad_u64_u32 v[158:159], s[60:61], v245, s93, v[12:13]
	global_load_ushort v218, v[158:159], off
	global_load_ushort v219, v[158:159], off offset:2048
	v_mul_f32_e32 v38, v38, v35
	v_cvt_pk_bf16_f32 v38, v38, v33
	ds_write_b16 v155, v38 offset:33792
	v_mul_f32_e32 v38, 0x3fb8aa3b, v32
	v_exp_f32_e32 v38, v38
	s_nop 0
	v_mul_f32_e32 v17, v38, v17
	v_mad_u64_u32 v[38:39], s[60:61], v36, s0, 0
	v_mad_i32_i24 v39, v37, s0, v39
	v_lshlrev_b64 v[36:37], 1, v[38:39]
	v_cvt_pk_bf16_f32 v17, v17, v33
	v_lshl_add_u64 v[38:39], v[24:25], 0, v[36:37]
	global_store_short v[38:39], v17, off
	v_sub_f32_e32 v17, v1, v32
	v_mul_f32_e32 v17, 0x3fb8aa3b, v17
	v_exp_f32_e32 v17, v17
	v_lshl_add_u64 v[36:37], v[22:23], 0, v[36:37]
	v_mul_f32_e32 v17, v17, v35
	v_ashrrev_i32_e32 v35, 31, v34
	v_lshl_add_u64 v[34:35], v[34:35], 0, s[34:35]
	v_cvt_pk_bf16_f32 v17, v17, v33
	global_store_short v[36:37], v17, off
	v_sub_f32_e32 v36, v31, v4
	v_mul_f32_e32 v36, 0x3fb8aa3b, v36
	v_exp_f32_e32 v36, v36
	s_waitcnt vmcnt(22)
	v_lshlrev_b32_e32 v17, 16, v220
	v_mul_f32_e32 v17, 0x3d800000, v17
	v_mul_f32_e32 v36, v36, v17
	v_cvt_pk_bf16_f32 v36, v36, v33
	ds_write_b16 v160, v36
	v_sub_f32_e32 v36, v4, v31
	v_mul_f32_e32 v36, 0x3fb8aa3b, v36
	v_exp_f32_e32 v36, v36
	v_lshlrev_b32_e32 v32, 16, v221
	v_mul_f32_e32 v36, v36, v32
	v_cvt_pk_bf16_f32 v36, v36, v33
	ds_write_b16 v160, v36 offset:33792
	v_mul_f32_e32 v36, 0x3fb8aa3b, v31
	v_exp_f32_e32 v36, v36
	s_nop 0
	v_mul_f32_e32 v17, v36, v17
	v_mad_u64_u32 v[36:37], s[60:61], v34, s0, 0
	v_mad_i32_i24 v37, v35, s0, v37
	v_lshlrev_b64 v[34:35], 1, v[36:37]
	v_cvt_pk_bf16_f32 v17, v17, v33
	v_lshl_add_u64 v[36:37], v[24:25], 0, v[34:35]
	global_store_short v[36:37], v17, off
	v_sub_f32_e32 v17, v1, v31
	v_mul_f32_e32 v17, 0x3fb8aa3b, v17
	v_exp_f32_e32 v17, v17
	v_ashrrev_i32_e32 v31, 31, v30
	v_lshl_add_u64 v[34:35], v[22:23], 0, v[34:35]
	v_lshl_add_u64 v[30:31], v[30:31], 0, s[34:35]
	v_mul_f32_e32 v17, v17, v32
	v_cvt_pk_bf16_f32 v17, v17, v33
	global_store_short v[34:35], v17, off
	v_sub_f32_e32 v34, v29, v4
	v_mul_f32_e32 v34, 0x3fb8aa3b, v34
	v_exp_f32_e32 v34, v34
	s_waitcnt vmcnt(20)
	v_lshlrev_b32_e32 v17, 16, v222
	v_mul_f32_e32 v17, 0x3d800000, v17
	v_mul_f32_e32 v34, v34, v17
	v_cvt_pk_bf16_f32 v34, v34, v33
	ds_write_b16 v161, v34
	v_sub_f32_e32 v34, v4, v29
	v_mul_f32_e32 v34, 0x3fb8aa3b, v34
	v_exp_f32_e32 v34, v34
	v_lshlrev_b32_e32 v32, 16, v223
	v_mul_f32_e32 v34, v34, v32
	v_cvt_pk_bf16_f32 v34, v34, v33
	ds_write_b16 v161, v34 offset:33792
	v_mul_f32_e32 v34, 0x3fb8aa3b, v29
	v_exp_f32_e32 v34, v34
	s_nop 0
	v_mul_f32_e32 v17, v34, v17
	v_mad_u64_u32 v[34:35], s[60:61], v30, s0, 0
	v_mad_i32_i24 v35, v31, s0, v35
	v_lshlrev_b64 v[30:31], 1, v[34:35]
	v_cvt_pk_bf16_f32 v17, v17, v33
	v_lshl_add_u64 v[34:35], v[24:25], 0, v[30:31]
	global_store_short v[34:35], v17, off
	v_sub_f32_e32 v17, v1, v29
	v_mul_f32_e32 v17, 0x3fb8aa3b, v17
	v_exp_f32_e32 v17, v17
	v_ashrrev_i32_e32 v29, 31, v28
	v_lshl_add_u64 v[30:31], v[22:23], 0, v[30:31]
	v_lshl_add_u64 v[28:29], v[28:29], 0, s[34:35]
	v_mul_f32_e32 v17, v17, v32
	v_cvt_pk_bf16_f32 v17, v17, v33
	global_store_short v[30:31], v17, off
	s_waitcnt vmcnt(18)
	v_lshlrev_b32_e32 v17, 16, v246
	v_mul_f32_e32 v17, 0x3d800000, v17
	v_lshlrev_b32_e32 v32, 16, v247
	v_sub_f32_e32 v30, v27, v4
	v_mul_f32_e32 v30, 0x3fb8aa3b, v30
	v_exp_f32_e32 v30, v30
	s_nop 0
	v_mul_f32_e32 v30, v30, v17
	v_cvt_pk_bf16_f32 v30, v30, v33
	ds_write_b16 v162, v30
	v_sub_f32_e32 v30, v4, v27
	v_mul_f32_e32 v30, 0x3fb8aa3b, v30
	v_exp_f32_e32 v30, v30
	s_nop 0
	v_mul_f32_e32 v30, v30, v32
	v_cvt_pk_bf16_f32 v30, v30, v33
	ds_write_b16 v162, v30 offset:33792
	v_mul_f32_e32 v30, 0x3fb8aa3b, v27
	v_exp_f32_e32 v30, v30
	s_nop 0
	v_mul_f32_e32 v17, v30, v17
	v_mad_u64_u32 v[30:31], s[60:61], v28, s0, 0
	v_mad_i32_i24 v31, v29, s0, v31
	v_lshlrev_b64 v[28:29], 1, v[30:31]
	v_cvt_pk_bf16_f32 v17, v17, v33
	v_lshl_add_u64 v[30:31], v[24:25], 0, v[28:29]
	global_store_short v[30:31], v17, off
	v_sub_f32_e32 v17, v1, v27
	v_mul_f32_e32 v17, 0x3fb8aa3b, v17
	v_exp_f32_e32 v17, v17
	v_ashrrev_i32_e32 v27, 31, v26
	v_lshl_add_u64 v[28:29], v[22:23], 0, v[28:29]
	v_lshl_add_u64 v[26:27], v[26:27], 0, s[34:35]
	v_mul_f32_e32 v17, v17, v32
	v_cvt_pk_bf16_f32 v17, v17, v33
	global_store_short v[28:29], v17, off
	s_waitcnt vmcnt(16)
	v_lshlrev_b32_e32 v17, 16, v248
	v_mul_f32_e32 v17, 0x3d800000, v17
	v_lshlrev_b32_e32 v30, 16, v249
	v_sub_f32_e32 v28, v21, v4
	v_mul_f32_e32 v28, 0x3fb8aa3b, v28
	v_exp_f32_e32 v28, v28
	s_nop 0
	v_mul_f32_e32 v28, v28, v17
	v_cvt_pk_bf16_f32 v28, v28, v33
	ds_write_b16 v163, v28
	v_sub_f32_e32 v28, v4, v21
	v_mul_f32_e32 v28, 0x3fb8aa3b, v28
	v_exp_f32_e32 v28, v28
	s_nop 0
	v_mul_f32_e32 v28, v28, v30
	v_cvt_pk_bf16_f32 v28, v28, v33
	ds_write_b16 v163, v28 offset:33792
	v_mul_f32_e32 v28, 0x3fb8aa3b, v21
	v_exp_f32_e32 v28, v28
	s_nop 0
	v_mul_f32_e32 v17, v28, v17
	v_mad_u64_u32 v[28:29], s[60:61], v26, s0, 0
	v_mad_i32_i24 v29, v27, s0, v29
	v_lshlrev_b64 v[26:27], 1, v[28:29]
	v_cvt_pk_bf16_f32 v17, v17, v33
	v_lshl_add_u64 v[28:29], v[24:25], 0, v[26:27]
	global_store_short v[28:29], v17, off
	v_sub_f32_e32 v17, v1, v21
	v_mul_f32_e32 v17, 0x3fb8aa3b, v17
	v_exp_f32_e32 v17, v17
	v_ashrrev_i32_e32 v21, 31, v20
	v_lshl_add_u64 v[26:27], v[22:23], 0, v[26:27]
	v_lshl_add_u64 v[20:21], v[20:21], 0, s[34:35]
	v_mul_f32_e32 v17, v17, v30
	v_cvt_pk_bf16_f32 v17, v17, v33
	global_store_short v[26:27], v17, off
	s_waitcnt vmcnt(14)
	v_lshlrev_b32_e32 v17, 16, v216
	v_mul_f32_e32 v17, 0x3d800000, v17
	v_lshlrev_b32_e32 v28, 16, v217
	v_sub_f32_e32 v26, v3, v4
	v_mul_f32_e32 v26, 0x3fb8aa3b, v26
	v_exp_f32_e32 v26, v26
	s_nop 0
	v_mul_f32_e32 v26, v26, v17
	v_cvt_pk_bf16_f32 v26, v26, v33
	ds_write_b16 v164, v26
	v_sub_f32_e32 v26, v4, v3
	v_mul_f32_e32 v26, 0x3fb8aa3b, v26
	v_exp_f32_e32 v26, v26
	v_sub_f32_e32 v4, v4, v19
	v_mul_f32_e32 v4, 0x3fb8aa3b, v4
	v_exp_f32_e32 v4, v4
	v_mul_f32_e32 v26, v26, v28
	v_cvt_pk_bf16_f32 v26, v26, v33
	ds_write_b16 v164, v26 offset:33792
	v_mul_f32_e32 v26, 0x3fb8aa3b, v3
	v_exp_f32_e32 v26, v26
	v_sub_f32_e32 v3, v1, v3
	v_mul_f32_e32 v3, 0x3fb8aa3b, v3
	v_exp_f32_e32 v3, v3
	v_mul_f32_e32 v17, v26, v17
	v_mad_u64_u32 v[26:27], s[60:61], v20, s0, 0
	v_mad_i32_i24 v27, v21, s0, v27
	v_lshlrev_b64 v[20:21], 1, v[26:27]
	v_mul_f32_e32 v3, v3, v28
	v_lshl_add_u64 v[26:27], v[24:25], 0, v[20:21]
	v_cvt_pk_bf16_f32 v3, v3, v33
	v_lshl_add_u64 v[20:21], v[22:23], 0, v[20:21]
	v_cvt_pk_bf16_f32 v17, v17, v33
	global_store_short v[26:27], v17, off
	global_store_short v[20:21], v3, off
	v_ashrrev_i32_e32 v3, 31, v2
	v_lshl_add_u64 v[2:3], v[2:3], 0, s[34:35]
	v_sub_f32_e32 v1, v1, v19
	v_mul_f32_e32 v1, 0x3fb8aa3b, v1
	v_exp_f32_e32 v1, v1
	s_waitcnt vmcnt(12)
	v_lshlrev_b32_e32 v17, 16, v218
	v_mul_f32_e32 v17, 0x3d800000, v17
	v_lshlrev_b32_e32 v20, 16, v219
	v_mul_f32_e32 v4, v4, v20
	v_cvt_pk_bf16_f32 v4, v4, v33
	ds_write_b16 v165, v4 offset:33792
	v_mul_f32_e32 v4, 0x3fb8aa3b, v19
	v_exp_f32_e32 v4, v4
	v_mul_f32_e32 v5, v5, v17
	v_cvt_pk_bf16_f32 v5, v5, v33
	ds_write_b16 v165, v5
	v_mul_f32_e32 v4, v4, v17
	v_cvt_pk_bf16_f32 v17, v4, v33
	v_mad_u64_u32 v[4:5], s[60:61], v2, s0, 0
	v_mad_i32_i24 v5, v3, s0, v5
	v_lshlrev_b64 v[2:3], 1, v[4:5]
	v_lshl_add_u64 v[4:5], v[24:25], 0, v[2:3]
	v_mul_f32_e32 v1, v1, v20
	v_lshl_add_u64 v[2:3], v[22:23], 0, v[2:3]
	global_store_short v[4:5], v17, off
	v_cvt_pk_bf16_f32 v1, v1, v33
	global_store_short v[2:3], v1, off
	v_mov_b32_e32 v2, 0
	v_mov_b32_e32 v3, 0
	v_mov_b32_e32 v4, 0
	v_mov_b32_e32 v5, 0
	s_waitcnt lgkmcnt(0)
	s_barrier
	s_and_saveexec_b64 s[0:1], s[4:5]
	s_cbranch_execz .LBB0_309
	ds_read_b128 v[2:5], v8
	ds_read_b128 v[20:23], v244 offset:33792
	s_waitcnt lgkmcnt(0)
	v_mfma_f32_16x16x32_bf16 v[2:5], v[2:5], v[20:23], 0
	ds_read_b128 v[20:23], v8 offset:64
	ds_read_b128 v[24:27], v244 offset:33856
	s_waitcnt lgkmcnt(0)
	v_mfma_f32_16x16x32_bf16 v[2:5], v[20:23], v[24:27], v[2:5]
	ds_read_b128 v[20:23], v8 offset:128
	ds_read_b128 v[24:27], v244 offset:33920
	s_waitcnt lgkmcnt(0)
	v_mfma_f32_16x16x32_bf16 v[2:5], v[20:23], v[24:27], v[2:5]
	ds_read_b128 v[20:23], v8 offset:192
	ds_read_b128 v[24:27], v244 offset:33984
	s_waitcnt lgkmcnt(0)
	v_mfma_f32_16x16x32_bf16 v[2:5], v[20:23], v[24:27], v[2:5]
	ds_read_b128 v[20:23], v8 offset:256
	ds_read_b128 v[24:27], v244 offset:34048
	s_waitcnt lgkmcnt(0)
	v_mfma_f32_16x16x32_bf16 v[2:5], v[20:23], v[24:27], v[2:5]
	ds_read_b128 v[20:23], v8 offset:320
	ds_read_b128 v[24:27], v244 offset:34112
	s_waitcnt lgkmcnt(0)
	v_mfma_f32_16x16x32_bf16 v[2:5], v[20:23], v[24:27], v[2:5]
	ds_read_b128 v[20:23], v8 offset:384
	ds_read_b128 v[24:27], v244 offset:34176
	s_waitcnt lgkmcnt(0)
	v_mfma_f32_16x16x32_bf16 v[2:5], v[20:23], v[24:27], v[2:5]
	ds_read_b128 v[20:23], v8 offset:448
	ds_read_b128 v[24:27], v244 offset:34240
	s_waitcnt lgkmcnt(0)
	v_mfma_f32_16x16x32_bf16 v[2:5], v[20:23], v[24:27], v[2:5]

.LBB0_311:
	s_or_b64 exec, exec, s[0:1]
	s_nop 6
	v_cndmask_b32_e64 v0, v0, 0, s[16:17]
	v_cvt_pk_bf16_f32 v0, v0, v33
	ds_write_b16 v212, v0
	v_cndmask_b32_e64 v0, v1, 0, s[18:19]
	v_cvt_pk_bf16_f32 v0, v0, v33
	ds_write_b16 v213, v0
	v_cndmask_b32_e64 v0, v2, 0, s[20:21]
	v_cvt_pk_bf16_f32 v0, v0, v33
	ds_write_b16 v214, v0
	v_cndmask_b32_e64 v0, v3, 0, s[22:23]
	v_cvt_pk_bf16_f32 v0, v0, v33
	ds_write_b16 v215, v0
	v_cndmask_b32_e64 v0, v166, v88, s[38:39]
	v_add_u32_e32 v0, s34, v0
	v_mov_b64_e32 v[4:5], s[30:31]
	v_mad_i64_i32 v[0:1], s[60:61], v0, s93, v[4:5]
	s_mov_b32 s37, s67
	v_lshl_add_u64 v[0:1], v[0:1], 0, s[36:37]
	v_mov_b32_e32 v19, v33
	v_lshl_add_u64 v[0:1], v[0:1], 0, v[18:19]
	v_add_co_u32_e32 v0, vcc, s94, v0
	s_waitcnt lgkmcnt(0)
	s_nop 0
	v_addc_co_u32_e32 v1, vcc, 0, v1, vcc
	s_barrier
	global_load_dwordx4 v[48:51], v[0:1], off
	v_cndmask_b32_e64 v17, v182, v181, s[38:39]
	v_cndmask_b32_e64 v32, v185, v184, s[38:39]
	v_cndmask_b32_e64 v42, v187, v186, s[38:39]
	v_cndmask_b32_e64 v40, v189, v188, s[38:39]
	v_cndmask_b32_e64 v38, v191, v190, s[38:39]
	v_cndmask_b32_e64 v36, v193, v192, s[38:39]
	v_cndmask_b32_e64 v34, v195, v194, s[38:39]
	v_cndmask_b32_e64 v30, v197, v196, s[38:39]
	v_cndmask_b32_e64 v28, v199, v198, s[38:39]
	v_cndmask_b32_e64 v26, v201, v200, s[38:39]
	v_cndmask_b32_e64 v24, v203, v202, s[38:39]
	v_cndmask_b32_e64 v22, v205, v204, s[38:39]
	s_xor_b64 s[0:1], s[64:65], -1
	v_add_u32_e32 v20, s34, v17
	v_add_u32_e32 v22, s34, v22
	v_add_u32_e32 v24, s34, v24
	v_add_u32_e32 v26, s34, v26
	v_add_u32_e32 v28, s34, v28
	v_add_u32_e32 v30, s34, v30
	v_add_u32_e32 v34, s34, v34
	v_add_u32_e32 v36, s34, v36
	v_add_u32_e32 v38, s34, v38
	v_add_u32_e32 v40, s34, v40
	v_add_u32_e32 v42, s34, v42
	v_add_u32_e32 v44, s34, v32
	s_and_b64 s[60:61], s[38:39], exec
	v_ashrrev_i32_e32 v21, 31, v20
	v_ashrrev_i32_e32 v23, 31, v22
	v_ashrrev_i32_e32 v25, 31, v24
	v_ashrrev_i32_e32 v27, 31, v26
	v_ashrrev_i32_e32 v29, 31, v28
	v_ashrrev_i32_e32 v31, 31, v30
	v_ashrrev_i32_e32 v35, 31, v34
	v_ashrrev_i32_e32 v37, 31, v36
	v_ashrrev_i32_e32 v39, 31, v38
	v_ashrrev_i32_e32 v41, 31, v40
	v_ashrrev_i32_e32 v43, 31, v42
	v_ashrrev_i32_e32 v45, 31, v44
	v_lshlrev_b64 v[20:21], 12, v[20:21]
	v_lshlrev_b64 v[22:23], 12, v[22:23]
	v_lshlrev_b64 v[24:25], 12, v[24:25]
	v_lshlrev_b64 v[26:27], 12, v[26:27]
	v_lshlrev_b64 v[28:29], 12, v[28:29]
	v_lshlrev_b64 v[30:31], 12, v[30:31]
	v_lshlrev_b64 v[34:35], 12, v[34:35]
	v_lshlrev_b64 v[36:37], 12, v[36:37]
	v_lshlrev_b64 v[38:39], 12, v[38:39]
	v_lshlrev_b64 v[40:41], 12, v[40:41]
	v_lshlrev_b64 v[42:43], 12, v[42:43]
	v_lshlrev_b64 v[44:45], 12, v[44:45]
	v_mov_b32_e32 v17, v233
	v_cndmask_b32_e64 v0, v168, v167, s[38:39]
	v_add_u32_e32 v0, s34, v0
	v_mad_i64_i32 v[0:1], s[60:61], v0, s93, v[4:5]
	v_lshl_add_u64 v[0:1], v[0:1], 0, s[36:37]
	v_lshl_add_u64 v[0:1], v[0:1], 0, v[18:19]
	v_add_co_u32_e32 v0, vcc, s94, v0
	s_nop 1
	v_addc_co_u32_e32 v1, vcc, 0, v1, vcc
	global_load_dwordx4 v[52:55], v[0:1], off
	v_cndmask_b32_e64 v0, v170, v169, s[38:39]
	v_add_u32_e32 v0, s34, v0
	v_mad_i64_i32 v[0:1], s[60:61], v0, s93, v[4:5]
	v_lshl_add_u64 v[0:1], v[0:1], 0, s[36:37]
	v_lshl_add_u64 v[0:1], v[0:1], 0, v[18:19]
	v_add_co_u32_e32 v0, vcc, s94, v0
	s_nop 1
	v_addc_co_u32_e32 v1, vcc, 0, v1, vcc
	global_load_dwordx4 v[56:59], v[0:1], off
	v_cndmask_b32_e64 v0, v172, v171, s[38:39]
	v_add_u32_e32 v0, s34, v0
	v_mad_i64_i32 v[0:1], s[60:61], v0, s93, v[4:5]
	v_lshl_add_u64 v[0:1], v[0:1], 0, s[36:37]
	v_lshl_add_u64 v[0:1], v[0:1], 0, v[18:19]
	v_add_co_u32_e32 v0, vcc, s94, v0
	s_nop 1
	v_addc_co_u32_e32 v1, vcc, 0, v1, vcc
	global_load_dwordx4 v[60:63], v[0:1], off
	v_cndmask_b32_e64 v0, v174, v173, s[38:39]
	v_add_u32_e32 v0, s34, v0
	v_mad_i64_i32 v[0:1], s[60:61], v0, s93, v[4:5]
	v_lshl_add_u64 v[0:1], v[0:1], 0, s[36:37]
	v_lshl_add_u64 v[0:1], v[0:1], 0, v[18:19]
	v_add_co_u32_e32 v0, vcc, s94, v0
	s_nop 1
	v_addc_co_u32_e32 v1, vcc, 0, v1, vcc
	global_load_dwordx4 v[64:67], v[0:1], off
	v_cndmask_b32_e64 v0, v176, v175, s[38:39]
	v_add_u32_e32 v0, s34, v0
	v_mad_i64_i32 v[0:1], s[60:61], v0, s93, v[4:5]
	v_lshl_add_u64 v[0:1], v[0:1], 0, s[36:37]
	v_lshl_add_u64 v[0:1], v[0:1], 0, v[18:19]
	v_add_co_u32_e32 v0, vcc, s94, v0
	s_nop 1
	v_addc_co_u32_e32 v1, vcc, 0, v1, vcc
	global_load_dwordx4 v[68:71], v[0:1], off
	v_cndmask_b32_e64 v0, v178, v177, s[38:39]
	v_add_u32_e32 v0, s34, v0
	v_mad_i64_i32 v[0:1], s[60:61], v0, s93, v[4:5]
	v_lshl_add_u64 v[0:1], v[0:1], 0, s[36:37]
	v_lshl_add_u64 v[0:1], v[0:1], 0, v[18:19]
	v_add_co_u32_e32 v0, vcc, s94, v0
	s_nop 1
	v_addc_co_u32_e32 v1, vcc, 0, v1, vcc
	global_load_dwordx4 v[72:75], v[0:1], off
	v_cndmask_b32_e64 v0, v180, v179, s[38:39]
	v_add_u32_e32 v0, s34, v0
	v_mad_i64_i32 v[0:1], s[60:61], v0, s93, v[4:5]
	v_lshl_add_u64 v[0:1], v[0:1], 0, s[36:37]
	v_lshl_add_u64 v[0:1], v[0:1], 0, v[18:19]
	v_add_co_u32_e32 v0, vcc, s94, v0
	v_cndmask_b32_e64 v19, v183, v93, s[38:39]
	s_nop 0
	v_addc_co_u32_e32 v1, vcc, 0, v1, vcc
	global_load_dwordx4 v[216:219], v[0:1], off
	v_cndmask_b32_e64 v4, v207, v206, s[38:39]
	v_add_u32_e32 v4, s34, v4
	v_add_u32_e32 v46, s34, v19
	s_mov_b32 s37, 0x1f000000
	v_ashrrev_i32_e32 v5, 31, v4
	v_ashrrev_i32_e32 v47, 31, v46
	s_cselect_b32 s66, s37, 0x25000000
	v_lshlrev_b64 v[4:5], 12, v[4:5]
	v_lshlrev_b64 v[46:47], 12, v[46:47]
	v_lshl_add_u64 v[4:5], s[66:67], 0, v[4:5]
	v_lshl_add_u64 v[20:21], s[66:67], 0, v[20:21]
	v_lshl_add_u64 v[22:23], s[66:67], 0, v[22:23]
	v_lshl_add_u64 v[24:25], s[66:67], 0, v[24:25]
	v_lshl_add_u64 v[26:27], s[66:67], 0, v[26:27]
	v_lshl_add_u64 v[28:29], s[66:67], 0, v[28:29]
	v_lshl_add_u64 v[30:31], s[66:67], 0, v[30:31]
	v_lshl_add_u64 v[34:35], s[66:67], 0, v[34:35]
	v_lshl_add_u64 v[36:37], s[66:67], 0, v[36:37]
	v_lshl_add_u64 v[38:39], s[66:67], 0, v[38:39]
	v_lshl_add_u64 v[40:41], s[66:67], 0, v[40:41]
	v_lshl_add_u64 v[42:43], s[66:67], 0, v[42:43]
	v_lshl_add_u64 v[44:45], s[66:67], 0, v[44:45]
	v_lshl_add_u64 v[46:47], s[66:67], 0, v[46:47]
	v_lshl_add_u64 v[4:5], v[14:15], 0, v[4:5]
	v_lshl_add_u64 v[20:21], v[14:15], 0, v[20:21]
	v_lshl_add_u64 v[22:23], v[14:15], 0, v[22:23]
	v_lshl_add_u64 v[24:25], v[14:15], 0, v[24:25]
	v_lshl_add_u64 v[26:27], v[14:15], 0, v[26:27]
	v_lshl_add_u64 v[28:29], v[14:15], 0, v[28:29]
	v_lshl_add_u64 v[30:31], v[14:15], 0, v[30:31]
	v_lshl_add_u64 v[34:35], v[14:15], 0, v[34:35]
	v_lshl_add_u64 v[36:37], v[14:15], 0, v[36:37]
	v_lshl_add_u64 v[38:39], v[14:15], 0, v[38:39]
	v_lshl_add_u64 v[40:41], v[14:15], 0, v[40:41]
	v_lshl_add_u64 v[42:43], v[14:15], 0, v[42:43]
	v_lshl_add_u64 v[44:45], v[14:15], 0, v[44:45]
	v_lshl_add_u64 v[46:47], v[14:15], 0, v[46:47]
	s_waitcnt vmcnt(0) lgkmcnt(0)
	ds_write_b128 v235, v[48:51]
	ds_write_b128 v236, v[52:55]
	ds_write_b128 v237, v[56:59]
	ds_write_b128 v238, v[60:63]
	ds_write_b128 v239, v[64:67]
	ds_write_b128 v240, v[68:71]
	ds_write_b128 v241, v[72:75]
	ds_write_b128 v242, v[216:219]
	v_cndmask_b32_e64 v2, v209, v208, s[38:39]
	v_cndmask_b32_e64 v0, v211, v210, s[38:39]
	v_add_u32_e32 v0, s34, v0
	v_add_u32_e32 v2, s34, v2
	v_ashrrev_i32_e32 v1, 31, v0
	v_ashrrev_i32_e32 v3, 31, v2
	v_lshlrev_b64 v[0:1], 12, v[0:1]
	v_lshlrev_b64 v[2:3], 12, v[2:3]
	v_lshl_add_u64 v[0:1], s[66:67], 0, v[0:1]
	v_lshl_add_u64 v[2:3], s[66:67], 0, v[2:3]
	v_lshl_add_u64 v[0:1], v[14:15], 0, v[0:1]
	v_lshl_add_u64 v[2:3], v[14:15], 0, v[2:3]
	s_mov_b64 s[38:39], 0
	s_waitcnt lgkmcnt(0)
	s_barrier

.LBB0_429:
	s_lshl_b32 s13, s14, 12
	s_addk_i32 s13, 0x2000
	s_lshl_b32 s14, s14, 8
	s_and_b64 s[4:5], s[4:5], exec
	s_cselect_b32 s4, s13, s14
	s_ashr_i32 s13, s4, 6
	s_add_u32 s4, s0, s20
	s_addc_u32 s5, s1, s21
	s_lshl_b32 s35, s31, 9
	s_add_u32 s4, s4, s35
	s_addc_u32 s5, s5, 0
	s_add_u32 s14, s0, s18
	s_addc_u32 s18, s1, s19
	v_and_b32_e32 v85, 0xffffffc0, v70
	v_lshlrev_b32_e32 v84, 3, v78
	s_add_u32 s20, s14, s35
	v_add3_u32 v83, 16, v85, v84
	s_movk_i32 s19, 0x210
	s_addc_u32 s21, s18, 0
	s_lshl_b32 s14, s31, 10
	s_waitcnt vmcnt(0)
	v_cvt_pk_bf16_f32 v0, v38, v39
	v_mad_u32_u24 v10, v79, s19, v83
	v_cvt_pk_bf16_f32 v8, v42, v43
	s_add_u32 s14, s22, s14
	v_cvt_pk_bf16_f32 v1, v40, v41
	v_cvt_pk_bf16_f32 v2, v46, v47
	v_cvt_pk_bf16_f32 v9, v44, v45
	ds_write2_b64 v10, v[0:1], v[8:9] offset1:4
	v_cvt_pk_bf16_f32 v0, v54, v55
	v_add_u32_e32 v8, 0x2000, v10
	s_addc_u32 s18, s23, 0
	v_cvt_pk_bf16_f32 v3, v48, v49
	v_cvt_pk_bf16_f32 v1, v56, v57
	ds_write2_b64 v8, v[2:3], v[0:1] offset0:32 offset1:36
	v_cvt_pk_bf16_f32 v0, v58, v59
	v_add_u32_e32 v2, 0x4000, v10
	s_lshl_b32 s36, s15, 1
	v_lshlrev_b32_e32 v34, 3, v70
	v_cvt_pk_bf16_f32 v4, v50, v51
	v_cvt_pk_bf16_f32 v5, v52, v53
	v_cvt_pk_bf16_f32 v1, v60, v61
	ds_write2_b64 v2, v[4:5], v[0:1] offset0:64 offset1:68
	v_cvt_pk_bf16_f32 v0, v66, v67
	v_add_u32_e32 v2, 0x6000, v10
	s_add_u32 s14, s14, s36
	v_cvt_pk_bf16_f32 v6, v62, v63
	v_cvt_pk_bf16_f32 v7, v64, v65
	v_cvt_pk_bf16_f32 v1, v68, v69
	ds_write2_b64 v2, v[6:7], v[0:1] offset0:96 offset1:100
	s_addc_u32 s15, s18, 0
	s_add_i32 s34, s29, -1
	v_and_b32_e32 v0, 0xf8, v34
	s_and_b64 s[18:19], s[2:3], exec
	v_lshlrev_b32_e32 v72, 1, v0
	v_mov_b32_e32 v73, v33
	v_add_u32_e32 v8, 0x200, v70
	v_add_u32_e32 v16, 0x400, v70
	v_add_u32_e32 v24, 0x600, v70
	s_cselect_b32 s18, 0, s34
	v_lshl_add_u64 v[114:115], s[4:5], 0, v[72:73]
	v_lshl_add_u64 v[116:117], s[20:21], 0, v[72:73]
	v_ashrrev_i32_e32 v73, 5, v70
	v_ashrrev_i32_e32 v87, 5, v8
	v_ashrrev_i32_e32 v88, 5, v16
	v_ashrrev_i32_e32 v89, 5, v24
	v_ashrrev_i32_e32 v86, 3, v70
	s_add_i32 s18, s18, s13
	v_sub_u32_e32 v0, 63, v73
	v_sub_u32_e32 v8, 63, v87
	v_sub_u32_e32 v16, 63, v88
	v_sub_u32_e32 v24, 63, v89
	s_ashr_i32 s19, s18, 31
	v_cndmask_b32_e64 v118, v0, v73, s[2:3]
	v_cndmask_b32_e64 v120, v8, v87, s[2:3]
	v_cndmask_b32_e64 v122, v16, v88, s[2:3]
	v_cndmask_b32_e64 v124, v24, v89, s[2:3]
	v_and_b32_e32 v71, 56, v34
	v_sub_u32_e32 v34, 63, v86
	s_lshl_b64 s[38:39], s[18:19], 6
	v_ashrrev_i32_e32 v119, 31, v118
	v_ashrrev_i32_e32 v121, 31, v120
	v_ashrrev_i32_e32 v123, 31, v122
	v_ashrrev_i32_e32 v125, 31, v124
	v_cndmask_b32_e64 v126, v34, v86, s[2:3]
	v_lshl_add_u64 v[0:1], s[38:39], 0, v[118:119]
	v_lshl_add_u64 v[8:9], s[38:39], 0, v[120:121]
	v_lshl_add_u64 v[16:17], s[38:39], 0, v[122:123]
	v_lshl_add_u64 v[24:25], s[38:39], 0, v[124:125]
	v_ashrrev_i32_e32 v127, 31, v126
	v_mad_u64_u32 v[2:3], s[4:5], s12, v0, 0
	v_mad_u64_u32 v[10:11], s[4:5], s12, v8, 0
	v_mad_u64_u32 v[18:19], s[4:5], s12, v16, 0
	v_mad_u64_u32 v[26:27], s[4:5], s12, v24, 0
	v_lshl_add_u64 v[34:35], s[38:39], 0, v[126:127]
	v_mov_b64_e32 v[36:37], s[14:15]
	v_mad_i32_i24 v3, s12, v1, v3
	v_mad_i32_i24 v11, s12, v9, v11
	v_mad_i32_i24 v19, s12, v17, v19
	v_mad_i32_i24 v27, s12, v25, v27
	v_mad_u64_u32 v[36:37], s[4:5], v34, s93, v[36:37]
	v_lshlrev_b64 v[0:1], 1, v[2:3]
	v_lshlrev_b64 v[8:9], 1, v[10:11]
	v_lshlrev_b64 v[16:17], 1, v[18:19]
	v_lshlrev_b64 v[24:25], 1, v[26:27]
	v_mad_i32_i24 v37, v35, s93, v37
	v_lshlrev_b32_e32 v74, 1, v71
	v_mov_b32_e32 v75, v33
	v_lshl_add_u64 v[2:3], v[114:115], 0, v[0:1]
	v_lshl_add_u64 v[4:5], v[116:117], 0, v[0:1]
	v_lshl_add_u64 v[10:11], v[114:115], 0, v[8:9]
	v_lshl_add_u64 v[12:13], v[116:117], 0, v[8:9]
	v_lshl_add_u64 v[18:19], v[114:115], 0, v[16:17]
	v_lshl_add_u64 v[20:21], v[116:117], 0, v[16:17]
	v_lshl_add_u64 v[26:27], v[114:115], 0, v[24:25]
	v_lshl_add_u64 v[28:29], v[116:117], 0, v[24:25]
	v_lshl_add_u64 v[34:35], v[36:37], 0, v[74:75]
	global_load_dwordx4 v[0:3], v[2:3], off
	s_nop 0
	global_load_dwordx4 v[4:7], v[4:5], off
	s_nop 0
	global_load_dwordx4 v[8:11], v[10:11], off
	s_nop 0
	global_load_dwordx4 v[12:15], v[12:13], off
	s_nop 0
	global_load_dwordx4 v[16:19], v[18:19], off
	s_nop 0
	global_load_dwordx4 v[20:23], v[20:21], off
	s_nop 0
	global_load_dwordx4 v[24:27], v[26:27], off
	s_nop 0
	global_load_dwordx4 v[28:31], v[28:29], off
	s_movk_i32 s4, 0x100
	global_load_dwordx4 v[34:37], v[34:35], off
	s_movk_i32 s20, 0xff
	v_cmp_gt_i32_e64 s[4:5], s4, v70
	v_cmp_lt_i32_e32 vcc, s20, v70
	s_and_saveexec_b64 s[20:21], vcc
	s_xor_b64 s[20:21], exec, s[20:21]
	s_lshl_b32 s66, s30, 12
	v_mov_b32_e32 v71, v33
	v_mov_b64_e32 v[76:77], s[66:67]
	s_or_saveexec_b64 s[20:21], s[20:21]
	s_lshl_b32 s31, s31, 8
	v_mov_b32_e32 v152, 0
	s_xor_b64 exec, exec, s[20:21]
	s_cbranch_execz .LBB0_433
	s_lshl_b64 s[18:19], s[18:19], 13
	s_add_u32 s18, s6, s18
	s_addc_u32 s19, s7, s19
	s_lshl_b32 s66, s30, 12
	s_add_u32 s18, s18, s66
	s_addc_u32 s19, s19, 0
	s_lshl_b32 s30, s31, 2
	s_add_u32 s18, s18, s30
	v_ashrrev_i32_e32 v71, 31, v70
	s_addc_u32 s19, s19, 0
	v_lshl_add_u64 v[76:77], v[70:71], 2, s[18:19]
	global_load_dword v152, v[76:77], off
	v_mov_b64_e32 v[76:77], s[66:67]

.LBB0_438:
	s_andn2_b64 vcc, exec, s[14:15]
	s_cbranch_vccnz .LBB0_442
	s_add_i32 s19, s34, -1
	s_and_b64 s[14:15], s[2:3], exec
	s_cselect_b32 s14, s18, s19
	s_add_i32 s14, s14, s13
	s_ashr_i32 s15, s14, 31
	s_lshl_b64 s[16:17], s[14:15], 6
	v_lshl_add_u64 v[0:1], s[16:17], 0, v[118:119]
	v_lshl_add_u64 v[8:9], s[16:17], 0, v[120:121]
	v_lshl_add_u64 v[16:17], s[16:17], 0, v[122:123]
	v_lshl_add_u64 v[24:25], s[16:17], 0, v[124:125]
	v_mad_u64_u32 v[2:3], s[20:21], v0, s12, 0
	v_mad_u64_u32 v[10:11], s[20:21], v8, s12, 0
	v_mad_u64_u32 v[18:19], s[20:21], v16, s12, 0
	v_mad_u64_u32 v[26:27], s[20:21], v24, s12, 0
	v_mad_i32_i24 v3, v1, s12, v3
	v_mad_i32_i24 v11, v9, s12, v11
	v_mad_i32_i24 v19, v17, s12, v19
	v_mad_i32_i24 v27, v25, s12, v27
	v_lshl_add_u64 v[34:35], s[16:17], 0, v[126:127]
	v_lshlrev_b64 v[0:1], 1, v[2:3]
	v_lshlrev_b64 v[8:9], 1, v[10:11]
	v_lshlrev_b64 v[16:17], 1, v[18:19]
	v_lshlrev_b64 v[24:25], 1, v[26:27]
	v_mad_u64_u32 v[36:37], s[16:17], v34, s93, v[128:129]
	v_lshl_add_u64 v[2:3], v[114:115], 0, v[0:1]
	v_lshl_add_u64 v[4:5], v[116:117], 0, v[0:1]
	v_lshl_add_u64 v[10:11], v[114:115], 0, v[8:9]
	v_lshl_add_u64 v[12:13], v[116:117], 0, v[8:9]
	v_lshl_add_u64 v[18:19], v[114:115], 0, v[16:17]
	v_lshl_add_u64 v[20:21], v[116:117], 0, v[16:17]
	v_lshl_add_u64 v[26:27], v[114:115], 0, v[24:25]
	v_lshl_add_u64 v[28:29], v[116:117], 0, v[24:25]
	v_mad_i32_i24 v37, v35, s93, v37
	global_load_dwordx4 v[0:3], v[2:3], off
	s_nop 0
	global_load_dwordx4 v[4:7], v[4:5], off
	s_nop 0
	global_load_dwordx4 v[8:11], v[10:11], off
	s_nop 0
	global_load_dwordx4 v[12:15], v[12:13], off
	s_nop 0
	global_load_dwordx4 v[16:19], v[18:19], off
	s_nop 0
	global_load_dwordx4 v[20:23], v[20:21], off
	s_nop 0
	global_load_dwordx4 v[24:27], v[26:27], off
	s_nop 0
	global_load_dwordx4 v[28:31], v[28:29], off
	s_nop 0
	global_load_dwordx4 v[34:37], v[36:37], off
	s_and_saveexec_b64 s[16:17], s[4:5]
	s_cbranch_execz .LBB0_441
	s_lshl_b64 s[14:15], s[14:15], 13
	v_lshl_add_u64 v[70:71], v[132:133], 0, s[14:15]
	global_load_dword v152, v[70:71], off

.LBB0_442:
	s_add_i32 s16, s18, -1
	s_and_b64 s[14:15], s[2:3], exec
	s_cselect_b32 s14, s16, s34
	s_add_i32 s14, s14, s13
	s_ashr_i32 s15, s14, 31
	s_lshl_b64 s[14:15], s[14:15], 18
	v_lshl_add_u64 v[70:71], v[142:143], 0, s[14:15]
	v_lshl_add_u64 v[150:151], v[70:71], 0, v[140:141]
	v_lshl_add_u64 v[144:145], v[70:71], 0, v[134:135]
	v_lshl_add_u64 v[146:147], v[70:71], 0, v[136:137]
	v_lshl_add_u64 v[148:149], v[70:71], 0, v[138:139]
	global_load_ushort v184, v[150:151], off
	global_load_ushort v181, v[144:145], off
	global_load_ushort v180, v[144:145], off offset:32
	global_load_ushort v182, v[146:147], off
	global_load_ushort v179, v[146:147], off offset:32
	global_load_ushort v183, v[148:149], off
	global_load_ushort v178, v[148:149], off offset:32
	global_load_ushort v177, v[150:151], off offset:32
	s_add_i32 s18, s18, 1
	s_cmp_eq_u32 s19, -1
	ds_read_b128 v[70:73], v130 offset:33792
	ds_read_b128 v[74:77], v167
	ds_read_b128 v[78:81], v168
	s_waitcnt lgkmcnt(1)
	v_mfma_f32_16x16x32_bf16 v[74:77], v[70:73], v[74:77], 0
	s_waitcnt lgkmcnt(0)
	v_mfma_f32_16x16x32_bf16 v[70:73], v[70:73], v[78:81], 0
	ds_read_b128 v[78:81], v130 offset:33856
	ds_read_b128 v[82:85], v167 offset:64
	s_waitcnt lgkmcnt(0)
	v_mfma_f32_16x16x32_bf16 v[74:77], v[78:81], v[82:85], v[74:77]
	ds_read_b128 v[82:85], v168 offset:64
	s_waitcnt lgkmcnt(0)
	v_mfma_f32_16x16x32_bf16 v[70:73], v[78:81], v[82:85], v[70:73]
	ds_read_b128 v[78:81], v130 offset:33920
	ds_read_b128 v[82:85], v167 offset:128
	s_waitcnt lgkmcnt(0)
	v_mfma_f32_16x16x32_bf16 v[74:77], v[78:81], v[82:85], v[74:77]
	ds_read_b128 v[82:85], v168 offset:128
	s_waitcnt lgkmcnt(0)
	v_mfma_f32_16x16x32_bf16 v[70:73], v[78:81], v[82:85], v[70:73]
	ds_read_b128 v[78:81], v130 offset:33984
	ds_read_b128 v[82:85], v167 offset:192
	s_waitcnt lgkmcnt(0)
	v_mfma_f32_16x16x32_bf16 v[74:77], v[78:81], v[82:85], v[74:77]
	ds_read_b128 v[82:85], v168 offset:192
	s_waitcnt lgkmcnt(0)
	v_mfma_f32_16x16x32_bf16 v[70:73], v[78:81], v[82:85], v[70:73]
	ds_read_b128 v[78:81], v130 offset:34048
	ds_read_b128 v[82:85], v167 offset:256
	s_waitcnt lgkmcnt(0)
	v_mfma_f32_16x16x32_bf16 v[74:77], v[78:81], v[82:85], v[74:77]
	ds_read_b128 v[82:85], v168 offset:256
	s_waitcnt lgkmcnt(0)
	v_mfma_f32_16x16x32_bf16 v[70:73], v[78:81], v[82:85], v[70:73]
	ds_read_b128 v[78:81], v130 offset:34112
	ds_read_b128 v[82:85], v167 offset:320
	s_waitcnt lgkmcnt(0)
	v_mfma_f32_16x16x32_bf16 v[74:77], v[78:81], v[82:85], v[74:77]
	ds_read_b128 v[82:85], v168 offset:320
	s_waitcnt lgkmcnt(0)
	v_mfma_f32_16x16x32_bf16 v[70:73], v[78:81], v[82:85], v[70:73]
	ds_read_b128 v[78:81], v130 offset:34176
	ds_read_b128 v[82:85], v167 offset:384
	s_waitcnt lgkmcnt(0)
	v_mfma_f32_16x16x32_bf16 v[74:77], v[78:81], v[82:85], v[74:77]
	ds_read_b128 v[82:85], v168 offset:384
	s_waitcnt lgkmcnt(0)
	v_mfma_f32_16x16x32_bf16 v[70:73], v[78:81], v[82:85], v[70:73]
	ds_read_b128 v[78:81], v130 offset:34240
	ds_read_b128 v[82:85], v167 offset:448
	ds_read_b128 v[86:89], v169
	s_waitcnt lgkmcnt(0)
	v_pk_mul_f32 v[96:97], v[40:41], v[88:89]
	v_mfma_f32_16x16x32_bf16 v[74:77], v[78:81], v[82:85], v[74:77]
	ds_read_b128 v[82:85], v168 offset:448
	v_pk_mul_f32 v[94:95], v[38:39], v[86:87]
	v_pk_mul_f32 v[40:41], v[64:65], v[88:89]
	s_waitcnt lgkmcnt(0)
	v_mfma_f32_16x16x32_bf16 v[70:73], v[78:81], v[82:85], v[70:73]
	v_mul_f32_e64 v84, v48, v88
	v_mul_f32_e64 v85, v49, v89
	v_pk_mul_f32 v[82:83], v[46:47], v[86:87]
	ds_read_b128 v[46:49], v169 offset:64
	v_pk_mul_f32 v[80:81], v[52:53], v[88:89]
	v_pk_mul_f32 v[78:79], v[50:51], v[86:87]
	v_pk_mul_f32 v[38:39], v[62:63], v[86:87]
	s_nop 0
	s_waitcnt vmcnt(0)
	v_lshlrev_b32_e32 v180, 16, v180
	v_lshlrev_b32_e32 v181, 16, v181
	v_lshlrev_b32_e32 v179, 16, v179
	v_lshlrev_b32_e32 v182, 16, v182
	v_lshlrev_b32_e32 v178, 16, v178
	v_lshlrev_b32_e32 v183, 16, v183
	v_lshlrev_b32_e32 v177, 16, v177
	v_lshlrev_b32_e32 v184, 16, v184
	v_add_f32_e32 v70, v70, v180
	s_waitcnt lgkmcnt(0)
	v_pk_mul_f32 v[52:53], v[44:45], v[48:49]
	v_pk_mul_f32 v[50:51], v[42:43], v[46:47]
	v_pk_mul_f32 v[92:93], v[56:57], v[48:49]
	v_pk_mul_f32 v[90:91], v[54:55], v[46:47]
	v_pk_mul_f32 v[88:89], v[60:61], v[48:49]
	v_pk_mul_f32 v[86:87], v[58:59], v[46:47]
	v_pk_mul_f32 v[44:45], v[68:69], v[48:49]
	v_pk_mul_f32 v[42:43], v[66:67], v[46:47]
	ds_read_u16 v46, v171 offset:528
	ds_read_u16 v47, v171 offset:1056
	ds_read_u16 v48, v171 offset:1584
	ds_read_u16 v49, v171 offset:2112
	ds_read_u16 v58, v171 offset:2640
	ds_read_u16 v59, v171 offset:3168
	ds_read_u16 v60, v170
	ds_read_u16 v61, v170 offset:32
	ds_read_u16 v62, v171
	ds_read_u16 v66, v171 offset:32
	ds_read_u16 v67, v171 offset:560
	ds_read_u16 v156, v171 offset:1088
	ds_read_u16 v68, v171 offset:1616
	ds_read_u16 v157, v171 offset:2144
	ds_read_u16 v69, v171 offset:2672
	ds_read_u16 v158, v171 offset:3200
	ds_read_u16 v54, v173 offset:144
	ds_read_u16 v55, v173 offset:288
	ds_read_u16 v56, v173 offset:432
	ds_read_u16 v63, v173 offset:576
	ds_read_u16 v57, v173 offset:720
	ds_read_u16 v64, v173 offset:864
	s_waitcnt lgkmcnt(4)
	v_perm_b32 v55, v55, v54, s74
	v_perm_b32 v65, v59, v58, s74
	s_waitcnt lgkmcnt(2)
	v_perm_b32 v56, v63, v56, s74
	ds_read_u16 v54, v172
	ds_read_u16 v159, v172 offset:32
	ds_read_u16 v63, v173
	ds_read_u16 v185, v173 offset:32
	s_waitcnt lgkmcnt(4)
	v_perm_b32 v57, v64, v57, s74
	v_perm_b32 v64, v49, v48, s74
	v_perm_b32 v62, v62, v60, s74
	s_waitcnt lgkmcnt(1)
	v_perm_b32 v54, v63, v54, s74
	v_perm_b32 v63, v47, v46, s74
	v_perm_b32 v69, v158, v69, s74
	v_perm_b32 v68, v157, v68, s74
	v_perm_b32 v67, v156, v67, s74
	v_perm_b32 v66, v66, v61, s74
	v_mfma_f32_16x16x32_bf16 v[46:49], v[62:65], v[54:57], v[94:97]
	v_add_f32_e32 v74, v74, v181
	v_cvt_pk_bf16_f32 v70, v70, v33
	v_cvt_pk_bf16_f32 v74, v74, v33
	v_mfma_f32_16x16x32_bf16 v[50:53], v[66:69], v[54:57], v[50:53]
	ds_read_u16 v54, v173 offset:176
	ds_read_u16 v55, v173 offset:320
	ds_read_u16 v56, v173 offset:464
	ds_read_u16 v57, v173 offset:608
	ds_read_u16 v58, v173 offset:752
	ds_read_u16 v59, v173 offset:896
	s_waitcnt lgkmcnt(2)
	v_perm_b32 v60, v57, v56, s74
	s_waitcnt lgkmcnt(0)
	v_perm_b32 v61, v59, v58, s74
	v_perm_b32 v59, v55, v54, s74
	v_perm_b32 v58, v185, v159, s74
	s_nop 1
	v_mfma_f32_16x16x32_bf16 v[54:57], v[62:65], v[58:61], v[82:85]
	v_mfma_f32_16x16x32_bf16 v[58:61], v[66:69], v[58:61], v[90:93]
	s_nop 1
	ds_read_u16 v82, v172 offset:64
	ds_read_u16 v90, v173 offset:64
	ds_read_u16 v83, v173 offset:208
	ds_read_u16 v91, v173 offset:352
	ds_read_u16 v84, v173 offset:496
	ds_read_u16 v92, v173 offset:640
	ds_read_u16 v85, v173 offset:784
	ds_read_u16 v93, v173 offset:928
	s_waitcnt lgkmcnt(4)
	v_perm_b32 v83, v91, v83, s74
	v_perm_b32 v82, v90, v82, s74
	s_waitcnt lgkmcnt(2)
	v_perm_b32 v84, v92, v84, s74
	s_waitcnt lgkmcnt(0)
	v_perm_b32 v85, v93, v85, s74
	s_nop 1
	v_mfma_f32_16x16x32_bf16 v[78:81], v[62:65], v[82:85], v[78:81]
	v_mfma_f32_16x16x32_bf16 v[82:85], v[66:69], v[82:85], v[86:89]
	s_nop 2
	ds_read_u16 v86, v172 offset:96
	ds_read_u16 v90, v173 offset:96
	ds_read_u16 v87, v173 offset:240
	ds_read_u16 v91, v173 offset:384
	ds_read_u16 v88, v173 offset:528
	ds_read_u16 v92, v173 offset:672
	ds_read_u16 v89, v173 offset:816
	ds_read_u16 v93, v173 offset:960
	s_waitcnt lgkmcnt(4)
	v_perm_b32 v87, v91, v87, s74
	v_perm_b32 v86, v90, v86, s74
	s_waitcnt lgkmcnt(2)
	v_perm_b32 v88, v92, v88, s74
	s_waitcnt lgkmcnt(0)
	v_perm_b32 v89, v93, v89, s74
	s_nop 1
	v_mfma_f32_16x16x32_bf16 v[62:65], v[62:65], v[86:89], v[38:41]
	v_mfma_f32_16x16x32_bf16 v[66:69], v[66:69], v[86:89], v[42:45]
	s_nop 1
	ds_read_u16 v38, v174 offset:528
	ds_read_u16 v39, v174 offset:1056
	ds_read_u16 v40, v174 offset:1584
	ds_read_u16 v41, v174 offset:2112
	ds_read_u16 v86, v174 offset:2640
	ds_read_u16 v87, v174 offset:3168
	ds_read_u16 v88, v174 offset:3696
	ds_read_u16 v89, v174
	ds_read_u16 v94, v174 offset:32
	ds_read_u16 v95, v174 offset:560
	ds_read_u16 v96, v174 offset:1088
	ds_read_u16 v97, v174 offset:1616
	ds_read_u16 v156, v174 offset:2144
	ds_read_u16 v157, v174 offset:2672
	ds_read_u16 v158, v174 offset:3200
	ds_read_u16 v159, v174 offset:3728
	ds_read_u16 v42, v175 offset:144
	ds_read_u16 v43, v175 offset:288
	ds_read_u16 v90, v175 offset:432
	ds_read_u16 v44, v175 offset:576
	ds_read_u16 v91, v175 offset:720
	ds_read_u16 v45, v175 offset:864
	ds_read_u16 v92, v175 offset:1008
	s_waitcnt lgkmcnt(4)
	v_perm_b32 v43, v90, v43, s74
	ds_read_u16 v90, v175
	ds_read_u16 v185, v175 offset:32
	s_waitcnt lgkmcnt(4)
	v_perm_b32 v44, v91, v44, s74
	v_perm_b32 v93, v88, v87, s74
	s_waitcnt lgkmcnt(2)
	v_perm_b32 v45, v92, v45, s74
	s_waitcnt lgkmcnt(1)
	v_perm_b32 v42, v42, v90, s74
	v_perm_b32 v92, v86, v41, s74
	v_perm_b32 v91, v40, v39, s74
	v_perm_b32 v90, v38, v89, s74
	v_perm_b32 v89, v159, v158, s74
	v_perm_b32 v88, v157, v156, s74
	v_perm_b32 v87, v97, v96, s74
	v_perm_b32 v86, v95, v94, s74
	v_mfma_f32_16x16x32_bf16 v[38:41], v[90:93], v[42:45], v[46:49]
	s_nop 0
	v_mfma_f32_16x16x32_bf16 v[42:45], v[86:89], v[42:45], v[50:53]
	s_nop 0
	ds_read_u16 v46, v175 offset:176
	ds_read_u16 v47, v175 offset:320
	ds_read_u16 v48, v175 offset:464
	ds_read_u16 v49, v175 offset:608
	ds_read_u16 v50, v175 offset:752
	ds_read_u16 v51, v175 offset:896
	ds_read_u16 v52, v175 offset:1040
	s_waitcnt lgkmcnt(0)
	v_perm_b32 v53, v52, v51, s74
	v_perm_b32 v52, v50, v49, s74
	v_perm_b32 v51, v48, v47, s74
	v_perm_b32 v50, v46, v185, s74
	s_nop 1
	v_mfma_f32_16x16x32_bf16 v[46:49], v[90:93], v[50:53], v[54:57]
	v_mfma_f32_16x16x32_bf16 v[54:57], v[86:89], v[50:53], v[58:61]
	ds_read_u16 v50, v175 offset:64
	ds_read_u16 v51, v175 offset:208
	ds_read_u16 v52, v175 offset:352
	ds_read_u16 v53, v175 offset:496
	ds_read_u16 v58, v175 offset:640
	ds_read_u16 v59, v175 offset:784
	ds_read_u16 v60, v175 offset:928
	ds_read_u16 v61, v175 offset:1072
	s_waitcnt lgkmcnt(0)
	v_perm_b32 v61, v61, v60, s74
	v_perm_b32 v60, v59, v58, s74
	v_perm_b32 v59, v53, v52, s74
	v_perm_b32 v58, v51, v50, s74
	s_nop 1
	v_mfma_f32_16x16x32_bf16 v[50:53], v[90:93], v[58:61], v[78:81]
	v_mfma_f32_16x16x32_bf16 v[58:61], v[86:89], v[58:61], v[82:85]
	s_nop 1
	ds_read_u16 v78, v175 offset:96
	ds_read_u16 v82, v175 offset:240
	ds_read_u16 v79, v175 offset:384
	ds_read_u16 v83, v175 offset:528
	ds_read_u16 v80, v175 offset:672
	ds_read_u16 v84, v175 offset:816
	ds_read_u16 v81, v175 offset:960
	ds_read_u16 v85, v175 offset:1104
	global_store_short v[144:145], v70, off offset:32
	v_add_f32_e32 v70, v71, v179
	global_store_short v[144:145], v74, off
	v_add_f32_e32 v74, v75, v182
	v_cvt_pk_bf16_f32 v70, v70, v33
	v_cvt_pk_bf16_f32 v74, v74, v33
	global_store_short v[146:147], v70, off offset:32
	v_add_f32_e32 v70, v72, v178
	global_store_short v[146:147], v74, off
	v_add_f32_e32 v74, v76, v183
	v_cvt_pk_bf16_f32 v70, v70, v33
	s_waitcnt lgkmcnt(0)
	v_perm_b32 v81, v85, v81, s74
	v_perm_b32 v80, v84, v80, s74
	v_perm_b32 v79, v83, v79, s74
	v_perm_b32 v78, v82, v78, s74
	v_cvt_pk_bf16_f32 v74, v74, v33
	global_store_short v[148:149], v70, off offset:32
	v_add_f32_e32 v70, v73, v177
	v_mfma_f32_16x16x32_bf16 v[62:65], v[90:93], v[78:81], v[62:65]
	global_store_short v[148:149], v74, off
	v_add_f32_e32 v74, v77, v184
	v_cvt_pk_bf16_f32 v70, v70, v33
	v_mfma_f32_16x16x32_bf16 v[66:69], v[86:89], v[78:81], v[66:69]
	v_cvt_pk_bf16_f32 v78, v42, v43
	v_cvt_pk_bf16_f32 v74, v74, v33
	global_store_short v[150:151], v74, off
	global_store_short v[150:151], v70, off offset:32
	s_waitcnt lgkmcnt(0)
	s_barrier
	v_cvt_pk_bf16_f32 v70, v38, v39
	v_cvt_pk_bf16_f32 v71, v40, v41
	v_cvt_pk_bf16_f32 v72, v46, v47
	v_cvt_pk_bf16_f32 v79, v44, v45
	ds_write2_b64 v176, v[70:71], v[78:79] offset1:4
	v_add_u32_e32 v78, 0x2000, v176
	v_cvt_pk_bf16_f32 v73, v48, v49
	v_cvt_pk_bf16_f32 v70, v54, v55
	v_cvt_pk_bf16_f32 v71, v56, v57
	ds_write2_b64 v78, v[72:73], v[70:71] offset0:32 offset1:36
	v_add_u32_e32 v72, 0x4000, v176
	v_cvt_pk_bf16_f32 v74, v50, v51
	v_cvt_pk_bf16_f32 v75, v52, v53
	v_cvt_pk_bf16_f32 v70, v58, v59
	v_cvt_pk_bf16_f32 v71, v60, v61
	ds_write2_b64 v72, v[74:75], v[70:71] offset0:64 offset1:68
	v_add_u32_e32 v72, 0x6000, v176
	v_cvt_pk_bf16_f32 v76, v62, v63
	v_cvt_pk_bf16_f32 v77, v64, v65
	v_cvt_pk_bf16_f32 v70, v66, v67
	v_cvt_pk_bf16_f32 v71, v68, v69
	ds_write2_b64 v72, v[76:77], v[70:71] offset0:96 offset1:100
	s_waitcnt lgkmcnt(0)
	s_barrier
	s_cbranch_scc1 .LBB0_444
	s_mov_b32 s34, s19
	s_branch .LBB0_434

.LBB0_643:
	s_or_b64 exec, exec, s[22:23]
	s_movk_i32 s22, 0x7f
	v_add_u32_e32 v79, 1, v44
	v_cmp_gt_u32_e32 vcc, s22, v44
	s_and_saveexec_b64 s[22:23], vcc
	s_cbranch_execz .LBB0_650
	v_and_b32_e32 v247, 1, v79
	v_cmp_eq_u32_e32 vcc, 1, v247
	v_lshlrev_b32_e32 v248, 5, v79
	s_mov_b32 s26, 0x3400
	s_mov_b32 s27, 0
	v_cndmask_b32_e32 v247, 0, v230, vcc
	s_mov_b32 s28, 0xffffcc00
	s_mov_b32 s29, -1
	v_add_u32_e32 v246, v77, v247
	v_lshl_add_u64 v[242:243], s[16:17], 0, v[32:33]
	v_lshl_add_u64 v[244:245], s[2:3], 0, v[32:33]
	v_add_co_u32_e32 v242, vcc, 0x2000, v242
	s_nop 1
	v_addc_co_u32_e32 v243, vcc, 0, v243, vcc
	v_add_co_u32_e32 v244, vcc, 0x800, v244
	s_nop 1
	v_addc_co_u32_e32 v245, vcc, 0, v245, vcc
	v_mov_b32_e32 v249, v74
	v_or_b32_e32 v247, v249, v248
	v_sub_u32_e32 v234, 4095, v247
	v_mad_u32_u24 v238, v249, s95, v246
	v_cndmask_b32_e64 v234, v234, v247, s[6:7]
	v_lshl_add_u32 v239, v249, 8, v246
	v_add_u32_e32 v236, s18, v234
	v_mad_u64_u32 v[216:217], vcc, v236, s26, v[242:243]
	v_lshlrev_b32_e32 v222, 13, v236
	v_mov_b32_e32 v223, 0
	v_mov_b32_e32 v178, 0
	v_mov_b32_e32 v179, 0
	v_mov_b32_e32 v180, 0
	v_mov_b32_e32 v181, 0
	v_mov_b32_e32 v182, 0
	v_mov_b32_e32 v183, 0
	v_mov_b32_e32 v184, 0
	v_mov_b32_e32 v185, 0
	v_mov_b32_e32 v186, 0
	v_mov_b32_e32 v187, 0
	v_mov_b32_e32 v188, 0
	v_mov_b32_e32 v189, 0
	v_lshl_add_u64 v[222:223], v[244:245], 0, v[222:223]
	global_load_dwordx2 v[172:173], v[216:217], off offset:-2048
	global_load_dwordx2 v[174:175], v[216:217], off
	global_load_dwordx2 v[176:177], v[216:217], off offset:2048
	v_lshl_add_u64 v[218:219], v[216:217], 0, s[28:29]
	v_lshl_add_u64 v[220:221], v[216:217], 0, s[26:27]
	global_load_dwordx2 v[190:191], v[222:223], off offset:-2048
	global_load_dwordx2 v[192:193], v[222:223], off offset:2048
	v_cmp_lt_i32_e32 vcc, 0, v234
	s_and_saveexec_b64 s[38:39], vcc
	global_load_dwordx2 v[178:179], v[218:219], off offset:-2048
	global_load_dwordx2 v[180:181], v[218:219], off
	global_load_dwordx2 v[182:183], v[218:219], off offset:2048
	s_mov_b64 exec, s[38:39]
	v_cmp_gt_i32_e32 vcc, 4095, v234
	s_and_saveexec_b64 s[38:39], vcc
	global_load_dwordx2 v[184:185], v[220:221], off offset:-2048
	global_load_dwordx2 v[186:187], v[220:221], off
	global_load_dwordx2 v[188:189], v[220:221], off offset:2048
	s_mov_b64 exec, s[38:39]
	v_or_b32_e32 v249, 16, v74
	v_or_b32_e32 v247, v249, v248
	v_sub_u32_e32 v235, 4095, v247
	v_mad_u32_u24 v240, v249, s95, v246
	v_cndmask_b32_e64 v235, v235, v247, s[6:7]
	v_lshl_add_u32 v241, v249, 8, v246
	v_add_u32_e32 v237, s18, v235
	v_mad_u64_u32 v[216:217], vcc, v237, s26, v[242:243]
	v_lshlrev_b32_e32 v222, 13, v237
	v_mov_b32_e32 v223, 0
	v_mov_b32_e32 v200, 0
	v_mov_b32_e32 v201, 0
	v_mov_b32_e32 v202, 0
	v_mov_b32_e32 v203, 0
	v_mov_b32_e32 v204, 0
	v_mov_b32_e32 v205, 0
	v_mov_b32_e32 v206, 0
	v_mov_b32_e32 v207, 0
	v_mov_b32_e32 v208, 0
	v_mov_b32_e32 v209, 0
	v_mov_b32_e32 v210, 0
	v_mov_b32_e32 v211, 0
	v_lshl_add_u64 v[222:223], v[244:245], 0, v[222:223]
	global_load_dwordx2 v[194:195], v[216:217], off offset:-2048
	global_load_dwordx2 v[196:197], v[216:217], off
	global_load_dwordx2 v[198:199], v[216:217], off offset:2048
	v_lshl_add_u64 v[218:219], v[216:217], 0, s[28:29]
	v_lshl_add_u64 v[220:221], v[216:217], 0, s[26:27]
	global_load_dwordx2 v[212:213], v[222:223], off offset:-2048
	global_load_dwordx2 v[214:215], v[222:223], off offset:2048
	v_cmp_lt_i32_e32 vcc, 0, v235
	s_and_saveexec_b64 s[38:39], vcc
	global_load_dwordx2 v[200:201], v[218:219], off offset:-2048
	global_load_dwordx2 v[202:203], v[218:219], off
	global_load_dwordx2 v[204:205], v[218:219], off offset:2048
	s_mov_b64 exec, s[38:39]
	v_cmp_gt_i32_e32 vcc, 4095, v235
	s_and_saveexec_b64 s[38:39], vcc
	global_load_dwordx2 v[206:207], v[220:221], off offset:-2048
	global_load_dwordx2 v[208:209], v[220:221], off
	global_load_dwordx2 v[210:211], v[220:221], off offset:2048
	s_mov_b64 exec, s[38:39]
	s_waitcnt vmcnt(0)
	v_lshlrev_b32_e32 v50, 16, v180
	v_and_b32_e32 v51, 0xffff0000, v180
	v_lshlrev_b32_e32 v52, 16, v181
	v_and_b32_e32 v53, 0xffff0000, v181
	v_lshlrev_b32_e32 v54, 16, v186
	v_and_b32_e32 v55, 0xffff0000, v186
	v_lshlrev_b32_e32 v56, 16, v187
	v_and_b32_e32 v57, 0xffff0000, v187
	v_lshlrev_b32_e32 v58, 16, v174
	v_and_b32_e32 v59, 0xffff0000, v174
	v_lshlrev_b32_e32 v60, 16, v175
	v_and_b32_e32 v61, 0xffff0000, v175
	v_pk_add_f32 v[50:51], v[50:51], v[54:55]
	v_pk_add_f32 v[52:53], v[52:53], v[56:57]
	v_pk_fma_f32 v[50:51], v[50:51], 0.5, v[58:59] op_sel_hi:[1,0,1] neg_lo:[0,0,1] neg_hi:[0,0,1]
	v_pk_fma_f32 v[52:53], v[52:53], 0.5, v[60:61] op_sel_hi:[1,0,1] neg_lo:[0,0,1] neg_hi:[0,0,1]
	v_pk_fma_f32 v[156:157], v[12:13], v[50:51], v[58:59]
	v_pk_fma_f32 v[158:159], v[14:15], v[52:53], v[60:61]
	v_lshlrev_b32_e32 v50, 16, v178
	v_and_b32_e32 v51, 0xffff0000, v178
	v_lshlrev_b32_e32 v52, 16, v179
	v_and_b32_e32 v53, 0xffff0000, v179
	v_lshlrev_b32_e32 v54, 16, v184
	v_and_b32_e32 v55, 0xffff0000, v184
	v_lshlrev_b32_e32 v56, 16, v185
	v_and_b32_e32 v57, 0xffff0000, v185
	v_lshlrev_b32_e32 v58, 16, v172
	v_and_b32_e32 v59, 0xffff0000, v172
	v_lshlrev_b32_e32 v60, 16, v173
	v_and_b32_e32 v61, 0xffff0000, v173
	v_pk_add_f32 v[50:51], v[50:51], v[54:55]
	v_pk_add_f32 v[52:53], v[52:53], v[56:57]
	v_pk_fma_f32 v[50:51], v[50:51], 0.5, v[58:59] op_sel_hi:[1,0,1] neg_lo:[0,0,1] neg_hi:[0,0,1]
	v_pk_fma_f32 v[52:53], v[52:53], 0.5, v[60:61] op_sel_hi:[1,0,1] neg_lo:[0,0,1] neg_hi:[0,0,1]
	v_pk_fma_f32 v[88:89], v[4:5], v[50:51], v[58:59]
	v_pk_fma_f32 v[90:91], v[6:7], v[52:53], v[60:61]
	v_pk_mul_f32 v[70:71], v[156:157], v[8:9]
	v_pk_mul_f32 v[72:73], v[158:159], v[10:11]
	v_lshlrev_b32_e32 v50, 16, v182
	v_and_b32_e32 v51, 0xffff0000, v182
	v_lshlrev_b32_e32 v52, 16, v183
	v_and_b32_e32 v53, 0xffff0000, v183
	v_lshlrev_b32_e32 v54, 16, v188
	v_and_b32_e32 v55, 0xffff0000, v188
	v_lshlrev_b32_e32 v56, 16, v189
	v_and_b32_e32 v57, 0xffff0000, v189
	v_lshlrev_b32_e32 v58, 16, v176
	v_and_b32_e32 v59, 0xffff0000, v176
	v_lshlrev_b32_e32 v60, 16, v177
	v_and_b32_e32 v61, 0xffff0000, v177
	v_pk_add_f32 v[50:51], v[50:51], v[54:55]
	v_pk_add_f32 v[52:53], v[52:53], v[56:57]
	v_pk_fma_f32 v[50:51], v[50:51], 0.5, v[58:59] op_sel_hi:[1,0,1] neg_lo:[0,0,1] neg_hi:[0,0,1]
	v_pk_fma_f32 v[52:53], v[52:53], 0.5, v[60:61] op_sel_hi:[1,0,1] neg_lo:[0,0,1] neg_hi:[0,0,1]
	v_pk_fma_f32 v[62:63], v[0:1], v[50:51], v[58:59]
	v_pk_fma_f32 v[64:65], v[2:3], v[52:53], v[60:61]
	v_pk_mul_f32 v[66:67], v[70:71], v[70:71]
	ds_write_b128 v238, v[88:91] offset:1024
	v_pk_fma_f32 v[66:67], v[72:73], v[72:73], v[66:67]
	ds_write_b128 v239, v[62:65] offset:40960
	v_lshlrev_b32_e32 v50, 16, v190
	v_add_f32_e32 v66, v66, v67
	v_and_b32_e32 v51, 0xffff0000, v190
	v_lshlrev_b32_e32 v52, 16, v191
	v_add_f32_dpp v66, v66, v66 quad_perm:[1,0,3,2] row_mask:0xf bank_mask:0xf bound_ctrl:1
	v_and_b32_e32 v53, 0xffff0000, v191
	v_mul_f32_e32 v50, 0xbfb8aa3b, v50
	v_add_f32_dpp v66, v66, v66 quad_perm:[2,3,0,1] row_mask:0xf bank_mask:0xf bound_ctrl:1
	v_mul_f32_e32 v51, 0xbfb8aa3b, v51
	v_mul_f32_e32 v52, 0xbfb8aa3b, v52
	v_add_f32_dpp v66, v66, v66 row_half_mirror row_mask:0xf bank_mask:0xf bound_ctrl:1
	v_mul_f32_e32 v53, 0xbfb8aa3b, v53
	v_lshlrev_b32_e32 v54, 16, v192
	v_add_f32_dpp v66, v66, v66 row_mirror row_mask:0xf bank_mask:0xf bound_ctrl:1
	v_and_b32_e32 v55, 0xffff0000, v192
	v_lshlrev_b32_e32 v56, 16, v193
	v_add_f32_e32 v66, 0x2b8cbccc, v66
	v_and_b32_e32 v57, 0xffff0000, v193
	v_exp_f32_e32 v50, v50
	v_rsq_f32_e32 v66, v66
	v_exp_f32_e32 v51, v51
	v_exp_f32_e32 v52, v52
	v_exp_f32_e32 v53, v53
	v_pk_add_f32 v[58:59], v[54:55], -1.0 op_sel_hi:[1,0]
	v_pk_add_f32 v[60:61], v[56:57], -1.0 op_sel_hi:[1,0]
	v_pk_mul_f32 v[92:93], v[70:71], v[66:67] op_sel_hi:[1,0]
	v_pk_mul_f32 v[94:95], v[72:73], v[66:67] op_sel_hi:[1,0]
	v_pk_fma_f32 v[58:59], v[16:17], v[58:59], 1.0 op_sel_hi:[1,1,0]
	v_pk_fma_f32 v[60:61], v[18:19], v[60:61], 1.0 op_sel_hi:[1,1,0]
	ds_write_b128 v238, v[50:53] offset:256
	ds_write_b128 v238, v[92:95]
	v_pk_mul_f32 v[70:71], v[92:93], v[54:55]
	v_pk_mul_f32 v[72:73], v[94:95], v[56:57]
	v_pk_mul_f32 v[58:59], v[156:157], v[58:59]
	v_pk_mul_f32 v[60:61], v[158:159], v[60:61]
	ds_write_b128 v238, v[70:73] offset:512
	ds_write_b128 v238, v[58:61] offset:768
	v_lshlrev_b32_e32 v50, 16, v202
	v_and_b32_e32 v51, 0xffff0000, v202
	v_lshlrev_b32_e32 v52, 16, v203
	v_and_b32_e32 v53, 0xffff0000, v203
	v_lshlrev_b32_e32 v54, 16, v208
	v_and_b32_e32 v55, 0xffff0000, v208
	v_lshlrev_b32_e32 v56, 16, v209
	v_and_b32_e32 v57, 0xffff0000, v209
	v_lshlrev_b32_e32 v58, 16, v196
	v_and_b32_e32 v59, 0xffff0000, v196
	v_lshlrev_b32_e32 v60, 16, v197
	v_and_b32_e32 v61, 0xffff0000, v197
	v_pk_add_f32 v[50:51], v[50:51], v[54:55]
	v_pk_add_f32 v[52:53], v[52:53], v[56:57]
	v_pk_fma_f32 v[50:51], v[50:51], 0.5, v[58:59] op_sel_hi:[1,0,1] neg_lo:[0,0,1] neg_hi:[0,0,1]
	v_pk_fma_f32 v[52:53], v[52:53], 0.5, v[60:61] op_sel_hi:[1,0,1] neg_lo:[0,0,1] neg_hi:[0,0,1]
	v_pk_fma_f32 v[156:157], v[12:13], v[50:51], v[58:59]
	v_pk_fma_f32 v[158:159], v[14:15], v[52:53], v[60:61]
	v_lshlrev_b32_e32 v50, 16, v200
	v_and_b32_e32 v51, 0xffff0000, v200
	v_lshlrev_b32_e32 v52, 16, v201
	v_and_b32_e32 v53, 0xffff0000, v201
	v_lshlrev_b32_e32 v54, 16, v206
	v_and_b32_e32 v55, 0xffff0000, v206
	v_lshlrev_b32_e32 v56, 16, v207
	v_and_b32_e32 v57, 0xffff0000, v207
	v_lshlrev_b32_e32 v58, 16, v194
	v_and_b32_e32 v59, 0xffff0000, v194
	v_lshlrev_b32_e32 v60, 16, v195
	v_and_b32_e32 v61, 0xffff0000, v195
	v_pk_add_f32 v[50:51], v[50:51], v[54:55]
	v_pk_add_f32 v[52:53], v[52:53], v[56:57]
	v_pk_fma_f32 v[50:51], v[50:51], 0.5, v[58:59] op_sel_hi:[1,0,1] neg_lo:[0,0,1] neg_hi:[0,0,1]
	v_pk_fma_f32 v[52:53], v[52:53], 0.5, v[60:61] op_sel_hi:[1,0,1] neg_lo:[0,0,1] neg_hi:[0,0,1]
	v_pk_fma_f32 v[88:89], v[4:5], v[50:51], v[58:59]
	v_pk_fma_f32 v[90:91], v[6:7], v[52:53], v[60:61]
	v_pk_mul_f32 v[70:71], v[156:157], v[8:9]
	v_pk_mul_f32 v[72:73], v[158:159], v[10:11]
	v_lshlrev_b32_e32 v50, 16, v204
	v_and_b32_e32 v51, 0xffff0000, v204
	v_lshlrev_b32_e32 v52, 16, v205
	v_and_b32_e32 v53, 0xffff0000, v205
	v_lshlrev_b32_e32 v54, 16, v210
	v_and_b32_e32 v55, 0xffff0000, v210
	v_lshlrev_b32_e32 v56, 16, v211
	v_and_b32_e32 v57, 0xffff0000, v211
	v_lshlrev_b32_e32 v58, 16, v198
	v_and_b32_e32 v59, 0xffff0000, v198
	v_lshlrev_b32_e32 v60, 16, v199
	v_and_b32_e32 v61, 0xffff0000, v199
	v_pk_add_f32 v[50:51], v[50:51], v[54:55]
	v_pk_add_f32 v[52:53], v[52:53], v[56:57]
	v_pk_fma_f32 v[50:51], v[50:51], 0.5, v[58:59] op_sel_hi:[1,0,1] neg_lo:[0,0,1] neg_hi:[0,0,1]
	v_pk_fma_f32 v[52:53], v[52:53], 0.5, v[60:61] op_sel_hi:[1,0,1] neg_lo:[0,0,1] neg_hi:[0,0,1]
	v_pk_fma_f32 v[62:63], v[0:1], v[50:51], v[58:59]
	v_pk_fma_f32 v[64:65], v[2:3], v[52:53], v[60:61]
	v_pk_mul_f32 v[66:67], v[70:71], v[70:71]
	ds_write_b128 v240, v[88:91] offset:1024
	v_pk_fma_f32 v[66:67], v[72:73], v[72:73], v[66:67]
	ds_write_b128 v241, v[62:65] offset:40960
	v_lshlrev_b32_e32 v50, 16, v212
	v_add_f32_e32 v66, v66, v67
	v_and_b32_e32 v51, 0xffff0000, v212
	v_lshlrev_b32_e32 v52, 16, v213
	v_add_f32_dpp v66, v66, v66 quad_perm:[1,0,3,2] row_mask:0xf bank_mask:0xf bound_ctrl:1
	v_and_b32_e32 v53, 0xffff0000, v213
	v_mul_f32_e32 v50, 0xbfb8aa3b, v50
	v_add_f32_dpp v66, v66, v66 quad_perm:[2,3,0,1] row_mask:0xf bank_mask:0xf bound_ctrl:1
	v_mul_f32_e32 v51, 0xbfb8aa3b, v51
	v_mul_f32_e32 v52, 0xbfb8aa3b, v52
	v_add_f32_dpp v66, v66, v66 row_half_mirror row_mask:0xf bank_mask:0xf bound_ctrl:1
	v_mul_f32_e32 v53, 0xbfb8aa3b, v53
	v_lshlrev_b32_e32 v54, 16, v214
	v_add_f32_dpp v66, v66, v66 row_mirror row_mask:0xf bank_mask:0xf bound_ctrl:1
	v_and_b32_e32 v55, 0xffff0000, v214
	v_lshlrev_b32_e32 v56, 16, v215
	v_add_f32_e32 v66, 0x2b8cbccc, v66
	v_and_b32_e32 v57, 0xffff0000, v215
	v_exp_f32_e32 v50, v50
	v_rsq_f32_e32 v66, v66
	v_exp_f32_e32 v51, v51
	v_exp_f32_e32 v52, v52
	v_exp_f32_e32 v53, v53
	v_pk_add_f32 v[58:59], v[54:55], -1.0 op_sel_hi:[1,0]
	v_pk_add_f32 v[60:61], v[56:57], -1.0 op_sel_hi:[1,0]
	v_pk_mul_f32 v[92:93], v[70:71], v[66:67] op_sel_hi:[1,0]
	v_pk_mul_f32 v[94:95], v[72:73], v[66:67] op_sel_hi:[1,0]
	v_pk_fma_f32 v[58:59], v[16:17], v[58:59], 1.0 op_sel_hi:[1,1,0]
	v_pk_fma_f32 v[60:61], v[18:19], v[60:61], 1.0 op_sel_hi:[1,1,0]
	ds_write_b128 v240, v[50:53] offset:256
	ds_write_b128 v240, v[92:95]
	v_pk_mul_f32 v[70:71], v[92:93], v[54:55]
	v_pk_mul_f32 v[72:73], v[94:95], v[56:57]
	v_pk_mul_f32 v[58:59], v[156:157], v[58:59]
	v_pk_mul_f32 v[60:61], v[158:159], v[60:61]
	ds_write_b128 v240, v[70:73] offset:512
	ds_write_b128 v240, v[58:61] offset:768

.LBB0_763:
	s_or_b64 exec, exec, s[18:19]
	v_add_u32_e32 v86, 1, v48
	v_cmp_gt_u32_e32 vcc, 7, v48
	s_and_saveexec_b64 s[60:61], vcc
	s_cbranch_execz .LBB0_770
	v_and_b32_e32 v247, 1, v86
	v_cmp_eq_u32_e32 vcc, 1, v247
	v_lshlrev_b32_e32 v248, 5, v86
	s_mov_b32 s26, 0x3400
	s_mov_b32 s27, 0
	v_cndmask_b32_e32 v247, 0, v230, vcc
	s_mov_b32 s46, 0xffffcc00
	s_mov_b32 s47, -1
	v_add_u32_e32 v246, v83, v247
	v_lshl_add_u64 v[242:243], s[28:29], 0, v[32:33]
	v_lshl_add_u64 v[244:245], v[42:43], 0, v[32:33]
	v_add_co_u32_e32 v242, vcc, 0x2000, v242
	s_nop 1
	v_addc_co_u32_e32 v243, vcc, 0, v243, vcc
	v_add_co_u32_e32 v244, vcc, 0x800, v244
	s_nop 1
	v_addc_co_u32_e32 v245, vcc, 0, v245, vcc
	v_mov_b32_e32 v249, v81
	v_or_b32_e32 v247, v249, v248
	v_sub_u32_e32 v234, 255, v247
	v_mad_u32_u24 v238, v249, s95, v246
	v_cndmask_b32_e64 v234, v234, v247, s[6:7]
	v_lshl_add_u32 v239, v249, 8, v246
	v_add_u32_e32 v236, v38, v234
	v_mad_u64_u32 v[216:217], vcc, v236, s26, v[242:243]
	v_lshlrev_b32_e32 v222, 13, v236
	v_mov_b32_e32 v223, 0
	v_mov_b32_e32 v178, 0
	v_mov_b32_e32 v179, 0
	v_mov_b32_e32 v180, 0
	v_mov_b32_e32 v181, 0
	v_mov_b32_e32 v182, 0
	v_mov_b32_e32 v183, 0
	v_mov_b32_e32 v184, 0
	v_mov_b32_e32 v185, 0
	v_mov_b32_e32 v186, 0
	v_mov_b32_e32 v187, 0
	v_mov_b32_e32 v188, 0
	v_mov_b32_e32 v189, 0
	v_lshl_add_u64 v[222:223], v[244:245], 0, v[222:223]
	global_load_dwordx2 v[172:173], v[216:217], off offset:-2048
	global_load_dwordx2 v[174:175], v[216:217], off
	global_load_dwordx2 v[176:177], v[216:217], off offset:2048
	v_lshl_add_u64 v[218:219], v[216:217], 0, s[46:47]
	v_lshl_add_u64 v[220:221], v[216:217], 0, s[26:27]
	global_load_dwordx2 v[190:191], v[222:223], off offset:-2048
	global_load_dwordx2 v[192:193], v[222:223], off offset:2048
	v_cmp_lt_i32_e32 vcc, 0, v234
	s_and_saveexec_b64 s[18:19], vcc
	global_load_dwordx2 v[178:179], v[218:219], off offset:-2048
	global_load_dwordx2 v[180:181], v[218:219], off
	global_load_dwordx2 v[182:183], v[218:219], off offset:2048
	s_mov_b64 exec, s[18:19]
	v_cmp_gt_i32_e32 vcc, 255, v234
	s_and_saveexec_b64 s[18:19], vcc
	global_load_dwordx2 v[184:185], v[220:221], off offset:-2048
	global_load_dwordx2 v[186:187], v[220:221], off
	global_load_dwordx2 v[188:189], v[220:221], off offset:2048
	s_mov_b64 exec, s[18:19]
	v_or_b32_e32 v249, 16, v81
	v_or_b32_e32 v247, v249, v248
	v_sub_u32_e32 v235, 255, v247
	v_mad_u32_u24 v240, v249, s95, v246
	v_cndmask_b32_e64 v235, v235, v247, s[6:7]
	v_lshl_add_u32 v241, v249, 8, v246
	v_add_u32_e32 v237, v38, v235
	v_mad_u64_u32 v[216:217], vcc, v237, s26, v[242:243]
	v_lshlrev_b32_e32 v222, 13, v237
	v_mov_b32_e32 v223, 0
	v_mov_b32_e32 v200, 0
	v_mov_b32_e32 v201, 0
	v_mov_b32_e32 v202, 0
	v_mov_b32_e32 v203, 0
	v_mov_b32_e32 v204, 0
	v_mov_b32_e32 v205, 0
	v_mov_b32_e32 v206, 0
	v_mov_b32_e32 v207, 0
	v_mov_b32_e32 v208, 0
	v_mov_b32_e32 v209, 0
	v_mov_b32_e32 v210, 0
	v_mov_b32_e32 v211, 0
	v_lshl_add_u64 v[222:223], v[244:245], 0, v[222:223]
	global_load_dwordx2 v[194:195], v[216:217], off offset:-2048
	global_load_dwordx2 v[196:197], v[216:217], off
	global_load_dwordx2 v[198:199], v[216:217], off offset:2048
	v_lshl_add_u64 v[218:219], v[216:217], 0, s[46:47]
	v_lshl_add_u64 v[220:221], v[216:217], 0, s[26:27]
	global_load_dwordx2 v[212:213], v[222:223], off offset:-2048
	global_load_dwordx2 v[214:215], v[222:223], off offset:2048
	v_cmp_lt_i32_e32 vcc, 0, v235
	s_and_saveexec_b64 s[18:19], vcc
	global_load_dwordx2 v[200:201], v[218:219], off offset:-2048
	global_load_dwordx2 v[202:203], v[218:219], off
	global_load_dwordx2 v[204:205], v[218:219], off offset:2048
	s_mov_b64 exec, s[18:19]
	v_cmp_gt_i32_e32 vcc, 255, v235
	s_and_saveexec_b64 s[18:19], vcc
	global_load_dwordx2 v[206:207], v[220:221], off offset:-2048
	global_load_dwordx2 v[208:209], v[220:221], off
	global_load_dwordx2 v[210:211], v[220:221], off offset:2048
	s_mov_b64 exec, s[18:19]
	s_waitcnt vmcnt(0)
	v_lshlrev_b32_e32 v50, 16, v180
	v_and_b32_e32 v51, 0xffff0000, v180
	v_lshlrev_b32_e32 v52, 16, v181
	v_and_b32_e32 v53, 0xffff0000, v181
	v_lshlrev_b32_e32 v54, 16, v186
	v_and_b32_e32 v55, 0xffff0000, v186
	v_lshlrev_b32_e32 v56, 16, v187
	v_and_b32_e32 v57, 0xffff0000, v187
	v_lshlrev_b32_e32 v58, 16, v174
	v_and_b32_e32 v59, 0xffff0000, v174
	v_lshlrev_b32_e32 v60, 16, v175
	v_and_b32_e32 v61, 0xffff0000, v175
	v_pk_add_f32 v[50:51], v[50:51], v[54:55]
	v_pk_add_f32 v[52:53], v[52:53], v[56:57]
	v_pk_fma_f32 v[50:51], v[50:51], 0.5, v[58:59] op_sel_hi:[1,0,1] neg_lo:[0,0,1] neg_hi:[0,0,1]
	v_pk_fma_f32 v[52:53], v[52:53], 0.5, v[60:61] op_sel_hi:[1,0,1] neg_lo:[0,0,1] neg_hi:[0,0,1]
	v_pk_fma_f32 v[156:157], v[12:13], v[50:51], v[58:59]
	v_pk_fma_f32 v[158:159], v[14:15], v[52:53], v[60:61]
	v_lshlrev_b32_e32 v50, 16, v178
	v_and_b32_e32 v51, 0xffff0000, v178
	v_lshlrev_b32_e32 v52, 16, v179
	v_and_b32_e32 v53, 0xffff0000, v179
	v_lshlrev_b32_e32 v54, 16, v184
	v_and_b32_e32 v55, 0xffff0000, v184
	v_lshlrev_b32_e32 v56, 16, v185
	v_and_b32_e32 v57, 0xffff0000, v185
	v_lshlrev_b32_e32 v58, 16, v172
	v_and_b32_e32 v59, 0xffff0000, v172
	v_lshlrev_b32_e32 v60, 16, v173
	v_and_b32_e32 v61, 0xffff0000, v173
	v_pk_add_f32 v[50:51], v[50:51], v[54:55]
	v_pk_add_f32 v[52:53], v[52:53], v[56:57]
	v_pk_fma_f32 v[50:51], v[50:51], 0.5, v[58:59] op_sel_hi:[1,0,1] neg_lo:[0,0,1] neg_hi:[0,0,1]
	v_pk_fma_f32 v[52:53], v[52:53], 0.5, v[60:61] op_sel_hi:[1,0,1] neg_lo:[0,0,1] neg_hi:[0,0,1]
	v_pk_fma_f32 v[88:89], v[4:5], v[50:51], v[58:59]
	v_pk_fma_f32 v[90:91], v[6:7], v[52:53], v[60:61]
	v_pk_mul_f32 v[70:71], v[156:157], v[8:9]
	v_pk_mul_f32 v[72:73], v[158:159], v[10:11]
	v_lshlrev_b32_e32 v50, 16, v182
	v_and_b32_e32 v51, 0xffff0000, v182
	v_lshlrev_b32_e32 v52, 16, v183
	v_and_b32_e32 v53, 0xffff0000, v183
	v_lshlrev_b32_e32 v54, 16, v188
	v_and_b32_e32 v55, 0xffff0000, v188
	v_lshlrev_b32_e32 v56, 16, v189
	v_and_b32_e32 v57, 0xffff0000, v189
	v_lshlrev_b32_e32 v58, 16, v176
	v_and_b32_e32 v59, 0xffff0000, v176
	v_lshlrev_b32_e32 v60, 16, v177
	v_and_b32_e32 v61, 0xffff0000, v177
	v_pk_add_f32 v[50:51], v[50:51], v[54:55]
	v_pk_add_f32 v[52:53], v[52:53], v[56:57]
	v_pk_fma_f32 v[50:51], v[50:51], 0.5, v[58:59] op_sel_hi:[1,0,1] neg_lo:[0,0,1] neg_hi:[0,0,1]
	v_pk_fma_f32 v[52:53], v[52:53], 0.5, v[60:61] op_sel_hi:[1,0,1] neg_lo:[0,0,1] neg_hi:[0,0,1]
	v_pk_fma_f32 v[62:63], v[0:1], v[50:51], v[58:59]
	v_pk_fma_f32 v[64:65], v[2:3], v[52:53], v[60:61]
	v_pk_mul_f32 v[66:67], v[70:71], v[70:71]
	ds_write_b128 v238, v[88:91] offset:1024
	v_pk_fma_f32 v[66:67], v[72:73], v[72:73], v[66:67]
	ds_write_b128 v239, v[62:65] offset:40960
	v_lshlrev_b32_e32 v50, 16, v190
	v_add_f32_e32 v66, v66, v67
	v_and_b32_e32 v51, 0xffff0000, v190
	v_lshlrev_b32_e32 v52, 16, v191
	v_add_f32_dpp v66, v66, v66 quad_perm:[1,0,3,2] row_mask:0xf bank_mask:0xf bound_ctrl:1
	v_and_b32_e32 v53, 0xffff0000, v191
	v_mul_f32_e32 v50, 0xbfb8aa3b, v50
	v_add_f32_dpp v66, v66, v66 quad_perm:[2,3,0,1] row_mask:0xf bank_mask:0xf bound_ctrl:1
	v_mul_f32_e32 v51, 0xbfb8aa3b, v51
	v_mul_f32_e32 v52, 0xbfb8aa3b, v52
	v_add_f32_dpp v66, v66, v66 row_half_mirror row_mask:0xf bank_mask:0xf bound_ctrl:1
	v_mul_f32_e32 v53, 0xbfb8aa3b, v53
	v_lshlrev_b32_e32 v54, 16, v192
	v_add_f32_dpp v66, v66, v66 row_mirror row_mask:0xf bank_mask:0xf bound_ctrl:1
	v_and_b32_e32 v55, 0xffff0000, v192
	v_lshlrev_b32_e32 v56, 16, v193
	v_add_f32_e32 v66, 0x2b8cbccc, v66
	v_and_b32_e32 v57, 0xffff0000, v193
	v_exp_f32_e32 v50, v50
	v_rsq_f32_e32 v66, v66
	v_exp_f32_e32 v51, v51
	v_exp_f32_e32 v52, v52
	v_exp_f32_e32 v53, v53
	v_pk_add_f32 v[58:59], v[54:55], -1.0 op_sel_hi:[1,0]
	v_pk_add_f32 v[60:61], v[56:57], -1.0 op_sel_hi:[1,0]
	v_pk_mul_f32 v[92:93], v[70:71], v[66:67] op_sel_hi:[1,0]
	v_pk_mul_f32 v[94:95], v[72:73], v[66:67] op_sel_hi:[1,0]
	v_pk_fma_f32 v[58:59], v[16:17], v[58:59], 1.0 op_sel_hi:[1,1,0]
	v_pk_fma_f32 v[60:61], v[18:19], v[60:61], 1.0 op_sel_hi:[1,1,0]
	ds_write_b128 v238, v[50:53] offset:256
	ds_write_b128 v238, v[92:95]
	v_pk_mul_f32 v[70:71], v[92:93], v[54:55]
	v_pk_mul_f32 v[72:73], v[94:95], v[56:57]
	v_pk_mul_f32 v[58:59], v[156:157], v[58:59]
	v_pk_mul_f32 v[60:61], v[158:159], v[60:61]
	ds_write_b128 v238, v[70:73] offset:512
	ds_write_b128 v238, v[58:61] offset:768
	v_lshlrev_b32_e32 v50, 16, v202
	v_and_b32_e32 v51, 0xffff0000, v202
	v_lshlrev_b32_e32 v52, 16, v203
	v_and_b32_e32 v53, 0xffff0000, v203
	v_lshlrev_b32_e32 v54, 16, v208
	v_and_b32_e32 v55, 0xffff0000, v208
	v_lshlrev_b32_e32 v56, 16, v209
	v_and_b32_e32 v57, 0xffff0000, v209
	v_lshlrev_b32_e32 v58, 16, v196
	v_and_b32_e32 v59, 0xffff0000, v196
	v_lshlrev_b32_e32 v60, 16, v197
	v_and_b32_e32 v61, 0xffff0000, v197
	v_pk_add_f32 v[50:51], v[50:51], v[54:55]
	v_pk_add_f32 v[52:53], v[52:53], v[56:57]
	v_pk_fma_f32 v[50:51], v[50:51], 0.5, v[58:59] op_sel_hi:[1,0,1] neg_lo:[0,0,1] neg_hi:[0,0,1]
	v_pk_fma_f32 v[52:53], v[52:53], 0.5, v[60:61] op_sel_hi:[1,0,1] neg_lo:[0,0,1] neg_hi:[0,0,1]
	v_pk_fma_f32 v[156:157], v[12:13], v[50:51], v[58:59]
	v_pk_fma_f32 v[158:159], v[14:15], v[52:53], v[60:61]
	v_lshlrev_b32_e32 v50, 16, v200
	v_and_b32_e32 v51, 0xffff0000, v200
	v_lshlrev_b32_e32 v52, 16, v201
	v_and_b32_e32 v53, 0xffff0000, v201
	v_lshlrev_b32_e32 v54, 16, v206
	v_and_b32_e32 v55, 0xffff0000, v206
	v_lshlrev_b32_e32 v56, 16, v207
	v_and_b32_e32 v57, 0xffff0000, v207
	v_lshlrev_b32_e32 v58, 16, v194
	v_and_b32_e32 v59, 0xffff0000, v194
	v_lshlrev_b32_e32 v60, 16, v195
	v_and_b32_e32 v61, 0xffff0000, v195
	v_pk_add_f32 v[50:51], v[50:51], v[54:55]
	v_pk_add_f32 v[52:53], v[52:53], v[56:57]
	v_pk_fma_f32 v[50:51], v[50:51], 0.5, v[58:59] op_sel_hi:[1,0,1] neg_lo:[0,0,1] neg_hi:[0,0,1]
	v_pk_fma_f32 v[52:53], v[52:53], 0.5, v[60:61] op_sel_hi:[1,0,1] neg_lo:[0,0,1] neg_hi:[0,0,1]
	v_pk_fma_f32 v[88:89], v[4:5], v[50:51], v[58:59]
	v_pk_fma_f32 v[90:91], v[6:7], v[52:53], v[60:61]
	v_pk_mul_f32 v[70:71], v[156:157], v[8:9]
	v_pk_mul_f32 v[72:73], v[158:159], v[10:11]
	v_lshlrev_b32_e32 v50, 16, v204
	v_and_b32_e32 v51, 0xffff0000, v204
	v_lshlrev_b32_e32 v52, 16, v205
	v_and_b32_e32 v53, 0xffff0000, v205
	v_lshlrev_b32_e32 v54, 16, v210
	v_and_b32_e32 v55, 0xffff0000, v210
	v_lshlrev_b32_e32 v56, 16, v211
	v_and_b32_e32 v57, 0xffff0000, v211
	v_lshlrev_b32_e32 v58, 16, v198
	v_and_b32_e32 v59, 0xffff0000, v198
	v_lshlrev_b32_e32 v60, 16, v199
	v_and_b32_e32 v61, 0xffff0000, v199
	v_pk_add_f32 v[50:51], v[50:51], v[54:55]
	v_pk_add_f32 v[52:53], v[52:53], v[56:57]
	v_pk_fma_f32 v[50:51], v[50:51], 0.5, v[58:59] op_sel_hi:[1,0,1] neg_lo:[0,0,1] neg_hi:[0,0,1]
	v_pk_fma_f32 v[52:53], v[52:53], 0.5, v[60:61] op_sel_hi:[1,0,1] neg_lo:[0,0,1] neg_hi:[0,0,1]
	v_pk_fma_f32 v[62:63], v[0:1], v[50:51], v[58:59]
	v_pk_fma_f32 v[64:65], v[2:3], v[52:53], v[60:61]
	v_pk_mul_f32 v[66:67], v[70:71], v[70:71]
	ds_write_b128 v240, v[88:91] offset:1024
	v_pk_fma_f32 v[66:67], v[72:73], v[72:73], v[66:67]
	ds_write_b128 v241, v[62:65] offset:40960
	v_lshlrev_b32_e32 v50, 16, v212
	v_add_f32_e32 v66, v66, v67
	v_and_b32_e32 v51, 0xffff0000, v212
	v_lshlrev_b32_e32 v52, 16, v213
	v_add_f32_dpp v66, v66, v66 quad_perm:[1,0,3,2] row_mask:0xf bank_mask:0xf bound_ctrl:1
	v_and_b32_e32 v53, 0xffff0000, v213
	v_mul_f32_e32 v50, 0xbfb8aa3b, v50
	v_add_f32_dpp v66, v66, v66 quad_perm:[2,3,0,1] row_mask:0xf bank_mask:0xf bound_ctrl:1
	v_mul_f32_e32 v51, 0xbfb8aa3b, v51
	v_mul_f32_e32 v52, 0xbfb8aa3b, v52
	v_add_f32_dpp v66, v66, v66 row_half_mirror row_mask:0xf bank_mask:0xf bound_ctrl:1
	v_mul_f32_e32 v53, 0xbfb8aa3b, v53
	v_lshlrev_b32_e32 v54, 16, v214
	v_add_f32_dpp v66, v66, v66 row_mirror row_mask:0xf bank_mask:0xf bound_ctrl:1
	v_and_b32_e32 v55, 0xffff0000, v214
	v_lshlrev_b32_e32 v56, 16, v215
	v_add_f32_e32 v66, 0x2b8cbccc, v66
	v_and_b32_e32 v57, 0xffff0000, v215
	v_exp_f32_e32 v50, v50
	v_rsq_f32_e32 v66, v66
	v_exp_f32_e32 v51, v51
	v_exp_f32_e32 v52, v52
	v_exp_f32_e32 v53, v53
	v_pk_add_f32 v[58:59], v[54:55], -1.0 op_sel_hi:[1,0]
	v_pk_add_f32 v[60:61], v[56:57], -1.0 op_sel_hi:[1,0]
	v_pk_mul_f32 v[92:93], v[70:71], v[66:67] op_sel_hi:[1,0]
	v_pk_mul_f32 v[94:95], v[72:73], v[66:67] op_sel_hi:[1,0]
	v_pk_fma_f32 v[58:59], v[16:17], v[58:59], 1.0 op_sel_hi:[1,1,0]
	v_pk_fma_f32 v[60:61], v[18:19], v[60:61], 1.0 op_sel_hi:[1,1,0]
	ds_write_b128 v240, v[50:53] offset:256
	ds_write_b128 v240, v[92:95]
	v_pk_mul_f32 v[70:71], v[92:93], v[54:55]
	v_pk_mul_f32 v[72:73], v[94:95], v[56:57]
	v_pk_mul_f32 v[58:59], v[156:157], v[58:59]
	v_pk_mul_f32 v[60:61], v[158:159], v[60:61]
	ds_write_b128 v240, v[70:73] offset:512
	ds_write_b128 v240, v[58:61] offset:768
